# static priority for waves 4-7 also across the FoX attention unit loop; redundant post-barrier lgkmcnt(0) removed from the K-loops
# baseline (speedup 1.0000x reference)
; #define PG8_STAGE(bufoff, gbase, voff) do { _Pragma("unroll") for (int _i = 0; _i < 2; ++_i) \
;         __builtin_amdgcn_global_load_lds((const unsigned*)((const char*)(gbase) + (voff)[_i]), (LAS unsigned*)(lds + (bufoff) + ldsw + _i * 8192), 16, 0, 0); } while (0)
; #define PG8_LDA(dst, b, h) do { _Pragma("unroll") for (int m = 0; m < 4; ++m) _Pragma("unroll") for (int k = 0; k < 2; ++k) dst[m][k] = *(const LAS bf16x8*)(lds + PG8_SA(b, h) + aoff + m * 2048 + k * 1024); } while (0)
; #define PG8_LDB(dst, b, h) do { _Pragma("unroll") for (int n = 0; n < 2; ++n) _Pragma("unroll") for (int k = 0; k < 2; ++k) dst[n][k] = *(const LAS bf16x8*)(lds + PG8_SB(b, h) + boff + n * 2048 + k * 1024); } while (0)
; #define PG8_MMA(ai, bj, At, Bt) do { __builtin_amdgcn_s_setprio(1); _Pragma("unroll") for (int m = 0; m < 4; ++m) _Pragma("unroll") for (int n = 0; n < 2; ++n) _Pragma("unroll") for (int k = 0; k < 2; ++k) \
;         acc[ai][bj][m][n] = __builtin_amdgcn_mfma_f32_16x16x32_bf16(Bt[n][k], At[m][k], acc[ai][bj][m][n], 0, 0, 0); __builtin_amdgcn_s_setprio(0); } while (0)
; #define PG8_WAIT_V(n) asm volatile("s_waitcnt vmcnt(" #n ")" ::: "memory")
; #define PG8_WAIT_L(n) asm volatile("s_waitcnt lgkmcnt(" #n ")" ::: "memory")
; #define PG8_BAR __builtin_amdgcn_s_barrier()
; #define PG8_SCHED __builtin_amdgcn_sched_barrier(0)
; template <class Epi, class Sched, bool ALIGN_EPI = true, bool SP2 = true>
; __device__ __forceinline__ void gemm_phase(LAS unsigned char* lds, const Gemm g, const Sched& S, const Epi& E) {
;     ...
;             const char* a1 = cA + (size_t)(t + 1) * kstep;
;             const char* a2 = last ? nA : cA + (size_t)(t + 2) * kstep; const char* b2 = last ? nB : cB + (size_t)(t + 2) * kstep;
;             const char* a3 = a2 + kstep; const char* b3 = b2 + kstep;
;             if constexpr (SP2) {
;             PG8_LDB(B0, 0, 0); PG8_LDB(B1, 0, 1); PG8_SCHED; PG8_LDA(At, 0, 0); PG8_STAGE(PG8_SA(1, 1), a1 + hstep, voffA);
;             PG8_WAIT_V(8); PG8_WAIT_L(0); PG8_BAR; PG8_MMA(0, 0, At, B0); PG8_MMA(0, 1, At, B1); PG8_BAR; PG8_SCHED;
;             PG8_LDA(At, 0, 1); PG8_STAGE(PG8_SB(0, 0), b2, voffB); PG8_STAGE(PG8_SB(0, 1), b2 + hstep, voffB); PG8_STAGE(PG8_SA(0, 0), a2, voffA);
;             PG8_WAIT_V(8); PG8_WAIT_L(0); PG8_BAR; PG8_MMA(1, 0, At, B0); PG8_MMA(1, 1, At, B1); PG8_BAR; PG8_SCHED;
.Lprio_skip_40:
.LBB0_40:
	s_add_u32 s24, s90, 0xfffe0080
	s_addc_u32 s25, s91, -1
	s_add_i32 s46, 0, 0x10000
	s_cmp_eq_u32 vcc_hi, 4
	s_cselect_b32 s83, s2, s25
	s_cselect_b32 s82, s3, s24
	v_add_u32_e32 v142, s46, v145
	s_cselect_b32 s25, s45, vcc_lo
	s_cselect_b32 s24, s53, s55
	s_add_i32 s48, 0, 0x14000
	ds_read_b128 v[138:141], v142
	ds_read_b128 v[148:151], v142 offset:1024
	ds_read_b128 v[152:155], v142 offset:2048
	ds_read_b128 v[156:159], v142 offset:3072
	v_add_u32_e32 v142, s48, v145
	ds_read_b128 v[170:173], v142
	ds_read_b128 v[174:177], v142 offset:1024
	ds_read_b128 v[178:181], v142 offset:2048
	ds_read_b128 v[182:185], v142 offset:3072
	s_add_i32 m0, s67, 0xc000
	ds_read_b128 v[186:189], v147
	ds_read_b128 v[190:193], v147 offset:1024
	ds_read_b128 v[194:197], v147 offset:2048
	ds_read_b128 v[198:201], v147 offset:3072
	ds_read_b128 v[202:205], v147 offset:4096
	ds_read_b128 v[206:209], v147 offset:5120
	ds_read_b128 v[210:213], v147 offset:6144
	ds_read_b128 v[214:217], v147 offset:7168
	global_load_lds_dwordx4 v134, s[90:91]
	s_add_i32 m0, s67, 0xe000
	s_nop 0
	global_load_lds_dwordx4 v136, s[90:91]
	s_waitcnt vmcnt(8)
	s_waitcnt lgkmcnt(0)
	s_barrier
	v_mfma_f32_16x16x32_bf16 v[124:127], v[138:141], v[186:189], v[124:127]
	v_mfma_f32_16x16x32_bf16 v[120:123], v[152:155], v[186:189], v[120:123]
	v_mfma_f32_16x16x32_bf16 v[108:111], v[138:141], v[194:197], v[108:111]
	v_mfma_f32_16x16x32_bf16 v[104:107], v[152:155], v[194:197], v[104:107]
	v_mfma_f32_16x16x32_bf16 v[92:95], v[138:141], v[202:205], v[92:95]
	v_mfma_f32_16x16x32_bf16 v[88:91], v[152:155], v[202:205], v[88:91]
	v_mfma_f32_16x16x32_bf16 v[76:79], v[138:141], v[210:213], v[76:79]
	v_mfma_f32_16x16x32_bf16 v[72:75], v[152:155], v[210:213], v[72:75]
	v_mfma_f32_16x16x32_bf16 v[124:127], v[148:151], v[190:193], v[124:127]
	v_mfma_f32_16x16x32_bf16 v[120:123], v[156:159], v[190:193], v[120:123]
	v_mfma_f32_16x16x32_bf16 v[108:111], v[148:151], v[198:201], v[108:111]
	v_mfma_f32_16x16x32_bf16 v[104:107], v[156:159], v[198:201], v[104:107]
	v_mfma_f32_16x16x32_bf16 v[92:95], v[148:151], v[206:209], v[92:95]
	v_mfma_f32_16x16x32_bf16 v[88:91], v[156:159], v[206:209], v[88:91]
	v_mfma_f32_16x16x32_bf16 v[76:79], v[148:151], v[214:217], v[76:79]
	v_mfma_f32_16x16x32_bf16 v[72:75], v[156:159], v[214:217], v[72:75]
	v_mfma_f32_16x16x32_bf16 v[116:119], v[170:173], v[186:189], v[116:119]
	v_mfma_f32_16x16x32_bf16 v[112:115], v[178:181], v[186:189], v[112:115]
	v_mfma_f32_16x16x32_bf16 v[100:103], v[170:173], v[194:197], v[100:103]
	v_mfma_f32_16x16x32_bf16 v[96:99], v[178:181], v[194:197], v[96:99]
	v_mfma_f32_16x16x32_bf16 v[84:87], v[170:173], v[202:205], v[84:87]
	v_mfma_f32_16x16x32_bf16 v[80:83], v[178:181], v[202:205], v[80:83]
	v_mfma_f32_16x16x32_bf16 v[68:71], v[170:173], v[210:213], v[68:71]
	v_mfma_f32_16x16x32_bf16 v[64:67], v[178:181], v[210:213], v[64:67]
	v_mfma_f32_16x16x32_bf16 v[116:119], v[174:177], v[190:193], v[116:119]
	v_mfma_f32_16x16x32_bf16 v[112:115], v[182:185], v[190:193], v[112:115]
	v_mfma_f32_16x16x32_bf16 v[100:103], v[174:177], v[198:201], v[100:103]
	v_mfma_f32_16x16x32_bf16 v[96:99], v[182:185], v[198:201], v[96:99]
	v_mfma_f32_16x16x32_bf16 v[84:87], v[174:177], v[206:209], v[84:87]
	v_mfma_f32_16x16x32_bf16 v[80:83], v[182:185], v[206:209], v[80:83]
	v_mfma_f32_16x16x32_bf16 v[68:71], v[174:177], v[214:217], v[68:71]
	v_mfma_f32_16x16x32_bf16 v[64:67], v[182:185], v[214:217], v[64:67]
	s_barrier
	s_add_i32 s46, s46, s93
	s_mov_b32 m0, s46
	ds_read_b128 v[186:189], v147 offset:16384
	ds_read_b128 v[190:193], v147 offset:17408
	ds_read_b128 v[194:197], v147 offset:18432
	ds_read_b128 v[198:201], v147 offset:19456
	ds_read_b128 v[202:205], v147 offset:20480
	ds_read_b128 v[206:209], v147 offset:21504
	ds_read_b128 v[210:213], v147 offset:22528
	ds_read_b128 v[214:217], v147 offset:23552
	global_load_lds_dwordx4 v160, s[24:25]
	s_add_i32 m0, s46, 0x2000
	s_add_u32 s46, s24, 0x20000
	s_addc_u32 s47, s25, 0
	s_add_i32 s48, s48, s93
	global_load_lds_dwordx4 v132, s[24:25]
	s_mov_b32 m0, s48
	s_nop 0
	global_load_lds_dwordx4 v160, s[46:47]
	s_add_i32 m0, s48, 0x2000
	s_nop 0
	global_load_lds_dwordx4 v132, s[46:47]
	s_mov_b32 m0, s67
	s_nop 0
	global_load_lds_dwordx4 v128, s[82:83]
	s_mov_b32 m0, s73
	s_nop 0
	global_load_lds_dwordx4 v130, s[82:83]
	s_waitcnt vmcnt(8)
	s_waitcnt lgkmcnt(0)
	s_barrier
	v_mfma_f32_16x16x32_bf16 v[60:63], v[138:141], v[186:189], v[60:63]
	v_mfma_f32_16x16x32_bf16 v[56:59], v[152:155], v[186:189], v[56:59]
	v_mfma_f32_16x16x32_bf16 v[44:47], v[138:141], v[194:197], v[44:47]
	v_mfma_f32_16x16x32_bf16 v[40:43], v[152:155], v[194:197], v[40:43]
	v_mfma_f32_16x16x32_bf16 v[28:31], v[138:141], v[202:205], v[28:31]
	v_mfma_f32_16x16x32_bf16 v[24:27], v[152:155], v[202:205], v[24:27]
	v_mfma_f32_16x16x32_bf16 v[12:15], v[138:141], v[210:213], v[12:15]
	v_mfma_f32_16x16x32_bf16 v[8:11], v[152:155], v[210:213], v[8:11]
	v_mfma_f32_16x16x32_bf16 v[60:63], v[148:151], v[190:193], v[60:63]
	v_mfma_f32_16x16x32_bf16 v[56:59], v[156:159], v[190:193], v[56:59]
	v_mfma_f32_16x16x32_bf16 v[44:47], v[148:151], v[198:201], v[44:47]
	v_mfma_f32_16x16x32_bf16 v[40:43], v[156:159], v[198:201], v[40:43]
	v_mfma_f32_16x16x32_bf16 v[28:31], v[148:151], v[206:209], v[28:31]
	v_mfma_f32_16x16x32_bf16 v[24:27], v[156:159], v[206:209], v[24:27]
	v_mfma_f32_16x16x32_bf16 v[12:15], v[148:151], v[214:217], v[12:15]
	v_mfma_f32_16x16x32_bf16 v[8:11], v[156:159], v[214:217], v[8:11]
	v_mfma_f32_16x16x32_bf16 v[52:55], v[170:173], v[186:189], v[52:55]
	v_mfma_f32_16x16x32_bf16 v[48:51], v[178:181], v[186:189], v[48:51]
	v_mfma_f32_16x16x32_bf16 v[36:39], v[170:173], v[194:197], v[36:39]
	v_mfma_f32_16x16x32_bf16 v[32:35], v[178:181], v[194:197], v[32:35]
	v_mfma_f32_16x16x32_bf16 v[20:23], v[170:173], v[202:205], v[20:23]
	v_mfma_f32_16x16x32_bf16 v[16:19], v[178:181], v[202:205], v[16:19]
	v_mfma_f32_16x16x32_bf16 v[4:7], v[170:173], v[210:213], v[4:7]
	v_mfma_f32_16x16x32_bf16 v[0:3], v[178:181], v[210:213], v[0:3]
	v_mfma_f32_16x16x32_bf16 v[52:55], v[174:177], v[190:193], v[52:55]
	v_mfma_f32_16x16x32_bf16 v[48:51], v[182:185], v[190:193], v[48:51]
	v_mfma_f32_16x16x32_bf16 v[36:39], v[174:177], v[198:201], v[36:39]
	v_mfma_f32_16x16x32_bf16 v[32:35], v[182:185], v[198:201], v[32:35]
	v_mfma_f32_16x16x32_bf16 v[20:23], v[174:177], v[206:209], v[20:23]
	v_mfma_f32_16x16x32_bf16 v[16:19], v[182:185], v[206:209], v[16:19]
	v_mfma_f32_16x16x32_bf16 v[4:7], v[174:177], v[214:217], v[4:7]
	v_mfma_f32_16x16x32_bf16 v[0:3], v[182:185], v[214:217], v[0:3]
	s_barrier
; #define PG8_STAGE(bufoff, gbase, voff) do { _Pragma("unroll") for (int _i = 0; _i < 2; ++_i) \
;         __builtin_amdgcn_global_load_lds((const unsigned*)((const char*)(gbase) + (voff)[_i]), (LAS unsigned*)(lds + (bufoff) + ldsw + _i * 8192), 16, 0, 0); } while (0)
; #define PG8_LDA(dst, b, h) do { _Pragma("unroll") for (int m = 0; m < 4; ++m) _Pragma("unroll") for (int k = 0; k < 2; ++k) dst[m][k] = *(const LAS bf16x8*)(lds + PG8_SA(b, h) + aoff + m * 2048 + k * 1024); } while (0)
; #define PG8_LDB(dst, b, h) do { _Pragma("unroll") for (int n = 0; n < 2; ++n) _Pragma("unroll") for (int k = 0; k < 2; ++k) dst[n][k] = *(const LAS bf16x8*)(lds + PG8_SB(b, h) + boff + n * 2048 + k * 1024); } while (0)
; #define PG8_MMA(ai, bj, At, Bt) do { __builtin_amdgcn_s_setprio(1); _Pragma("unroll") for (int m = 0; m < 4; ++m) _Pragma("unroll") for (int n = 0; n < 2; ++n) _Pragma("unroll") for (int k = 0; k < 2; ++k) \
;         acc[ai][bj][m][n] = __builtin_amdgcn_mfma_f32_16x16x32_bf16(Bt[n][k], At[m][k], acc[ai][bj][m][n], 0, 0, 0); __builtin_amdgcn_s_setprio(0); } while (0)
; #define PG8_WAIT_V(n) asm volatile("s_waitcnt vmcnt(" #n ")" ::: "memory")
; #define PG8_WAIT_L(n) asm volatile("s_waitcnt lgkmcnt(" #n ")" ::: "memory")
; #define PG8_BAR __builtin_amdgcn_s_barrier()
; #define PG8_SCHED __builtin_amdgcn_sched_barrier(0)
; template <class Epi, class Sched, bool ALIGN_EPI = true, bool SP2 = true>
; __device__ __forceinline__ void gemm_phase(LAS unsigned char* lds, const Gemm g, const Sched& S, const Epi& E) {
;     ...
;             PG8_LDB(B0, 1, 0); PG8_LDB(B1, 1, 1); PG8_SCHED; PG8_LDA(At, 1, 0); PG8_STAGE(PG8_SA(0, 1), a2 + hstep, voffA);
;             PG8_WAIT_V(8); PG8_WAIT_L(0); PG8_BAR; PG8_MMA(0, 0, At, B0); PG8_MMA(0, 1, At, B1); PG8_BAR; PG8_SCHED;
;             PG8_LDA(At, 1, 1); PG8_STAGE(PG8_SB(1, 0), b3, voffB); PG8_STAGE(PG8_SB(1, 1), b3 + hstep, voffB); PG8_STAGE(PG8_SA(1, 0), a3, voffA);
;             PG8_WAIT_V(8); PG8_WAIT_L(0); PG8_BAR; PG8_MMA(1, 0, At, B0); PG8_MMA(1, 1, At, B1); PG8_BAR; PG8_SCHED;
;     ...
;         if constexpr (ALIGN_EPI) { if (wr == 0) PG8_BAR; }
	s_add_i32 s48, 0, 0x18000
	s_add_i32 s49, 0, 0x1c000
	v_add_u32_e32 v156, s48, v145
	v_add_u32_e32 v182, s49, v145
	ds_read_b128 v[138:141], v156
	ds_read_b128 v[148:151], v156 offset:1024
	ds_read_b128 v[152:155], v156 offset:2048
	ds_read_b128 v[156:159], v156 offset:3072
	ds_read_b128 v[170:173], v182
	ds_read_b128 v[174:177], v182 offset:1024
	ds_read_b128 v[178:181], v182 offset:2048
	ds_read_b128 v[182:185], v182 offset:3072
	s_add_u32 s46, s82, 0x20000
	s_addc_u32 s47, s83, 0
	s_mov_b32 m0, s94
	ds_read_b128 v[186:189], v147 offset:32768
	ds_read_b128 v[190:193], v147 offset:33792
	ds_read_b128 v[194:197], v147 offset:34816
	ds_read_b128 v[198:201], v147 offset:35840
	ds_read_b128 v[202:205], v147 offset:36864
	ds_read_b128 v[206:209], v147 offset:37888
	ds_read_b128 v[210:213], v147 offset:38912
	ds_read_b128 v[214:217], v147 offset:39936
	global_load_lds_dwordx4 v128, s[46:47]
	s_mov_b32 m0, s95
	s_nop 0
	global_load_lds_dwordx4 v130, s[46:47]
	s_waitcnt vmcnt(8)
	s_waitcnt lgkmcnt(0)
	s_barrier
	v_mfma_f32_16x16x32_bf16 v[124:127], v[138:141], v[186:189], v[124:127]
	v_mfma_f32_16x16x32_bf16 v[120:123], v[152:155], v[186:189], v[120:123]
	v_mfma_f32_16x16x32_bf16 v[108:111], v[138:141], v[194:197], v[108:111]
	v_mfma_f32_16x16x32_bf16 v[104:107], v[152:155], v[194:197], v[104:107]
	v_mfma_f32_16x16x32_bf16 v[92:95], v[138:141], v[202:205], v[92:95]
	v_mfma_f32_16x16x32_bf16 v[88:91], v[152:155], v[202:205], v[88:91]
	v_mfma_f32_16x16x32_bf16 v[76:79], v[138:141], v[210:213], v[76:79]
	v_mfma_f32_16x16x32_bf16 v[72:75], v[152:155], v[210:213], v[72:75]
	v_mfma_f32_16x16x32_bf16 v[124:127], v[148:151], v[190:193], v[124:127]
	v_mfma_f32_16x16x32_bf16 v[120:123], v[156:159], v[190:193], v[120:123]
	v_mfma_f32_16x16x32_bf16 v[108:111], v[148:151], v[198:201], v[108:111]
	v_mfma_f32_16x16x32_bf16 v[104:107], v[156:159], v[198:201], v[104:107]
	v_mfma_f32_16x16x32_bf16 v[92:95], v[148:151], v[206:209], v[92:95]
	v_mfma_f32_16x16x32_bf16 v[88:91], v[156:159], v[206:209], v[88:91]
	v_mfma_f32_16x16x32_bf16 v[76:79], v[148:151], v[214:217], v[76:79]
	v_mfma_f32_16x16x32_bf16 v[72:75], v[156:159], v[214:217], v[72:75]
	v_mfma_f32_16x16x32_bf16 v[116:119], v[170:173], v[186:189], v[116:119]
	v_mfma_f32_16x16x32_bf16 v[112:115], v[178:181], v[186:189], v[112:115]
	v_mfma_f32_16x16x32_bf16 v[100:103], v[170:173], v[194:197], v[100:103]
	v_mfma_f32_16x16x32_bf16 v[96:99], v[178:181], v[194:197], v[96:99]
	v_mfma_f32_16x16x32_bf16 v[84:87], v[170:173], v[202:205], v[84:87]
	v_mfma_f32_16x16x32_bf16 v[80:83], v[178:181], v[202:205], v[80:83]
	v_mfma_f32_16x16x32_bf16 v[68:71], v[170:173], v[210:213], v[68:71]
	v_mfma_f32_16x16x32_bf16 v[64:67], v[178:181], v[210:213], v[64:67]
	v_mfma_f32_16x16x32_bf16 v[116:119], v[174:177], v[190:193], v[116:119]
	v_mfma_f32_16x16x32_bf16 v[112:115], v[182:185], v[190:193], v[112:115]
	v_mfma_f32_16x16x32_bf16 v[100:103], v[174:177], v[198:201], v[100:103]
	v_mfma_f32_16x16x32_bf16 v[96:99], v[182:185], v[198:201], v[96:99]
	v_mfma_f32_16x16x32_bf16 v[84:87], v[174:177], v[206:209], v[84:87]
	v_mfma_f32_16x16x32_bf16 v[80:83], v[182:185], v[206:209], v[80:83]
	v_mfma_f32_16x16x32_bf16 v[68:71], v[174:177], v[214:217], v[68:71]
	v_mfma_f32_16x16x32_bf16 v[64:67], v[182:185], v[214:217], v[64:67]
	s_barrier
	s_add_i32 s46, s48, s93
	s_mov_b32 m0, s46
	ds_read_b128 v[186:189], v147 offset:49152
	ds_read_b128 v[190:193], v147 offset:50176
	ds_read_b128 v[194:197], v147 offset:51200
	ds_read_b128 v[198:201], v147 offset:52224
	ds_read_b128 v[202:205], v147 offset:53248
	ds_read_b128 v[206:209], v147 offset:54272
	ds_read_b128 v[210:213], v147 offset:55296
	ds_read_b128 v[214:217], v147 offset:56320
	s_add_u32 s98, s24, 0x80
	s_addc_u32 s99, s25, 0
	global_load_lds_dwordx4 v160, s[98:99]
	s_add_i32 m0, s46, 0x2000
	s_add_u32 s24, s24, 0x20080
	s_addc_u32 s25, s25, 0
	s_add_i32 s46, s49, s93
	global_load_lds_dwordx4 v132, s[98:99]
	s_mov_b32 m0, s46
	s_nop 0
	global_load_lds_dwordx4 v160, s[24:25]
	s_add_i32 m0, s46, 0x2000
	s_nop 0
	global_load_lds_dwordx4 v132, s[24:25]
	s_mov_b32 m0, s96
	s_nop 0
	s_add_u32 s98, s82, 0x80
	s_addc_u32 s99, s83, 0
	global_load_lds_dwordx4 v128, s[98:99]
	s_mov_b32 m0, s97
	s_nop 0
	global_load_lds_dwordx4 v130, s[98:99]
	s_waitcnt vmcnt(8)
	s_waitcnt lgkmcnt(0)
	s_barrier
	v_mfma_f32_16x16x32_bf16 v[60:63], v[138:141], v[186:189], v[60:63]
	v_mfma_f32_16x16x32_bf16 v[56:59], v[152:155], v[186:189], v[56:59]
	v_mfma_f32_16x16x32_bf16 v[44:47], v[138:141], v[194:197], v[44:47]
	v_mfma_f32_16x16x32_bf16 v[40:43], v[152:155], v[194:197], v[40:43]
	v_mfma_f32_16x16x32_bf16 v[28:31], v[138:141], v[202:205], v[28:31]
	v_mfma_f32_16x16x32_bf16 v[24:27], v[152:155], v[202:205], v[24:27]
	v_mfma_f32_16x16x32_bf16 v[12:15], v[138:141], v[210:213], v[12:15]
	v_mfma_f32_16x16x32_bf16 v[8:11], v[152:155], v[210:213], v[8:11]
	v_mfma_f32_16x16x32_bf16 v[60:63], v[148:151], v[190:193], v[60:63]
	v_mfma_f32_16x16x32_bf16 v[56:59], v[156:159], v[190:193], v[56:59]
	v_mfma_f32_16x16x32_bf16 v[44:47], v[148:151], v[198:201], v[44:47]
	v_mfma_f32_16x16x32_bf16 v[40:43], v[156:159], v[198:201], v[40:43]
	v_mfma_f32_16x16x32_bf16 v[28:31], v[148:151], v[206:209], v[28:31]
	v_mfma_f32_16x16x32_bf16 v[24:27], v[156:159], v[206:209], v[24:27]
	v_mfma_f32_16x16x32_bf16 v[12:15], v[148:151], v[214:217], v[12:15]
	v_mfma_f32_16x16x32_bf16 v[8:11], v[156:159], v[214:217], v[8:11]
	v_mfma_f32_16x16x32_bf16 v[52:55], v[170:173], v[186:189], v[52:55]
	v_mfma_f32_16x16x32_bf16 v[48:51], v[178:181], v[186:189], v[48:51]
	v_mfma_f32_16x16x32_bf16 v[36:39], v[170:173], v[194:197], v[36:39]
	v_mfma_f32_16x16x32_bf16 v[32:35], v[178:181], v[194:197], v[32:35]
	v_mfma_f32_16x16x32_bf16 v[20:23], v[170:173], v[202:205], v[20:23]
	v_mfma_f32_16x16x32_bf16 v[16:19], v[178:181], v[202:205], v[16:19]
	v_mfma_f32_16x16x32_bf16 v[4:7], v[170:173], v[210:213], v[4:7]
	v_mfma_f32_16x16x32_bf16 v[0:3], v[178:181], v[210:213], v[0:3]
	v_mfma_f32_16x16x32_bf16 v[52:55], v[174:177], v[190:193], v[52:55]
	v_mfma_f32_16x16x32_bf16 v[48:51], v[182:185], v[190:193], v[48:51]
	v_mfma_f32_16x16x32_bf16 v[36:39], v[174:177], v[198:201], v[36:39]
	v_mfma_f32_16x16x32_bf16 v[32:35], v[182:185], v[198:201], v[32:35]
	v_mfma_f32_16x16x32_bf16 v[20:23], v[174:177], v[206:209], v[20:23]
	v_mfma_f32_16x16x32_bf16 v[16:19], v[182:185], v[206:209], v[16:19]
	v_mfma_f32_16x16x32_bf16 v[4:7], v[174:177], v[214:217], v[4:7]
	v_mfma_f32_16x16x32_bf16 v[0:3], v[182:185], v[214:217], v[0:3]
	s_barrier
	s_add_i32 vcc_hi, vcc_hi, 2
	s_add_u32 s90, s90, 0x100
	s_addc_u32 s91, s91, 0
	s_add_u32 s55, s55, 0x100
	s_addc_u32 vcc_lo, vcc_lo, 0
	s_cmp_gt_u32 vcc_hi, 5
	s_cbranch_scc0 .LBB0_40
	s_setprio 0
	s_and_b64 vcc, exec, s[30:31]
	s_cbranch_vccz .LBB0_43
	s_barrier

; #define PG8_STAGE(bufoff, gbase, voff) do { _Pragma("unroll") for (int _i = 0; _i < 2; ++_i) \
;         __builtin_amdgcn_global_load_lds((const unsigned*)((const char*)(gbase) + (voff)[_i]), (LAS unsigned*)(lds + (bufoff) + ldsw + _i * 8192), 16, 0, 0); } while (0)
; #define PG8_LDA(dst, b, h) do { _Pragma("unroll") for (int m = 0; m < 4; ++m) _Pragma("unroll") for (int k = 0; k < 2; ++k) dst[m][k] = *(const LAS bf16x8*)(lds + PG8_SA(b, h) + aoff + m * 2048 + k * 1024); } while (0)
; #define PG8_LDB(dst, b, h) do { _Pragma("unroll") for (int n = 0; n < 2; ++n) _Pragma("unroll") for (int k = 0; k < 2; ++k) dst[n][k] = *(const LAS bf16x8*)(lds + PG8_SB(b, h) + boff + n * 2048 + k * 1024); } while (0)
; #define PG8_MMA(ai, bj, At, Bt) do { __builtin_amdgcn_s_setprio(1); _Pragma("unroll") for (int m = 0; m < 4; ++m) _Pragma("unroll") for (int n = 0; n < 2; ++n) _Pragma("unroll") for (int k = 0; k < 2; ++k) \
;         acc[ai][bj][m][n] = __builtin_amdgcn_mfma_f32_16x16x32_bf16(Bt[n][k], At[m][k], acc[ai][bj][m][n], 0, 0, 0); __builtin_amdgcn_s_setprio(0); } while (0)
; #define PG8_WAIT_V(n) asm volatile("s_waitcnt vmcnt(" #n ")" ::: "memory")
; #define PG8_WAIT_L(n) asm volatile("s_waitcnt lgkmcnt(" #n ")" ::: "memory")
; #define PG8_BAR __builtin_amdgcn_s_barrier()
; #define PG8_SCHED __builtin_amdgcn_sched_barrier(0)
; template <class Epi, class Sched, bool ALIGN_EPI = true, bool SP2 = true>
; __device__ __forceinline__ void gemm_phase(LAS unsigned char* lds, const Gemm g, const Sched& S, const Epi& E) {
;     ...
;             const char* a1 = cA + (size_t)(t + 1) * kstep;
;             const char* a2 = last ? nA : cA + (size_t)(t + 2) * kstep; const char* b2 = last ? nB : cB + (size_t)(t + 2) * kstep;
;             const char* a3 = a2 + kstep; const char* b3 = b2 + kstep;
;             if constexpr (SP2) {
;             PG8_LDB(B0, 0, 0); PG8_LDB(B1, 0, 1); PG8_SCHED; PG8_LDA(At, 0, 0); PG8_STAGE(PG8_SA(1, 1), a1 + hstep, voffA);
;             PG8_WAIT_V(8); PG8_WAIT_L(0); PG8_BAR; PG8_MMA(0, 0, At, B0); PG8_MMA(0, 1, At, B1); PG8_BAR; PG8_SCHED;
;             PG8_LDA(At, 0, 1); PG8_STAGE(PG8_SB(0, 0), b2, voffB); PG8_STAGE(PG8_SB(0, 1), b2 + hstep, voffB); PG8_STAGE(PG8_SA(0, 0), a2, voffA);
;             PG8_WAIT_V(8); PG8_WAIT_L(0); PG8_BAR; PG8_MMA(1, 0, At, B0); PG8_MMA(1, 1, At, B1); PG8_BAR; PG8_SCHED;
.Lprio_skip_93:
.LBB0_93:
	s_add_u32 s24, s62, 0xfff80080
	s_addc_u32 s25, s63, -1
	s_add_i32 s46, 0, 0x10000
	s_cmp_eq_u32 s93, 28
	s_cselect_b32 s67, s2, s25
	s_cselect_b32 s66, s3, s24
	s_cselect_b32 s25, s19, s92
	s_cselect_b32 s24, s31, s91
	s_add_i32 s47, 0, 0x14000
	v_add_u32_e32 v154, s46, v143
	v_add_u32_e32 v158, s47, v143
	ds_read_b128 v[138:141], v154
	ds_read_b128 v[146:149], v154 offset:1024
	ds_read_b128 v[150:153], v154 offset:2048
	ds_read_b128 v[154:157], v154 offset:3072
	ds_read_b128 v[170:173], v158
	ds_read_b128 v[174:177], v158 offset:1024
	ds_read_b128 v[178:181], v158 offset:2048
	ds_read_b128 v[182:185], v158 offset:3072
	s_add_i32 m0, s44, 0xc000
	ds_read_b128 v[186:189], v145
	ds_read_b128 v[190:193], v145 offset:1024
	ds_read_b128 v[194:197], v145 offset:2048
	ds_read_b128 v[198:201], v145 offset:3072
	ds_read_b128 v[202:205], v145 offset:4096
	ds_read_b128 v[206:209], v145 offset:5120
	ds_read_b128 v[210:213], v145 offset:6144
	ds_read_b128 v[214:217], v145 offset:7168
	global_load_lds_dwordx4 v134, s[62:63]
	s_add_i32 m0, s44, 0xe000
	s_nop 0
	global_load_lds_dwordx4 v136, s[62:63]
	s_waitcnt vmcnt(8)
	s_waitcnt lgkmcnt(0)
	s_barrier
	v_mfma_f32_16x16x32_bf16 v[124:127], v[138:141], v[186:189], v[124:127]
	v_mfma_f32_16x16x32_bf16 v[120:123], v[150:153], v[186:189], v[120:123]
	v_mfma_f32_16x16x32_bf16 v[108:111], v[138:141], v[194:197], v[108:111]
	v_mfma_f32_16x16x32_bf16 v[104:107], v[150:153], v[194:197], v[104:107]
	v_mfma_f32_16x16x32_bf16 v[92:95], v[138:141], v[202:205], v[92:95]
	v_mfma_f32_16x16x32_bf16 v[88:91], v[150:153], v[202:205], v[88:91]
	v_mfma_f32_16x16x32_bf16 v[76:79], v[138:141], v[210:213], v[76:79]
	v_mfma_f32_16x16x32_bf16 v[72:75], v[150:153], v[210:213], v[72:75]
	v_mfma_f32_16x16x32_bf16 v[124:127], v[146:149], v[190:193], v[124:127]
	v_mfma_f32_16x16x32_bf16 v[120:123], v[154:157], v[190:193], v[120:123]
	v_mfma_f32_16x16x32_bf16 v[108:111], v[146:149], v[198:201], v[108:111]
	v_mfma_f32_16x16x32_bf16 v[104:107], v[154:157], v[198:201], v[104:107]
	v_mfma_f32_16x16x32_bf16 v[92:95], v[146:149], v[206:209], v[92:95]
	v_mfma_f32_16x16x32_bf16 v[88:91], v[154:157], v[206:209], v[88:91]
	v_mfma_f32_16x16x32_bf16 v[76:79], v[146:149], v[214:217], v[76:79]
	v_mfma_f32_16x16x32_bf16 v[72:75], v[154:157], v[214:217], v[72:75]
	v_mfma_f32_16x16x32_bf16 v[116:119], v[170:173], v[186:189], v[116:119]
	v_mfma_f32_16x16x32_bf16 v[112:115], v[178:181], v[186:189], v[112:115]
	v_mfma_f32_16x16x32_bf16 v[100:103], v[170:173], v[194:197], v[100:103]
	v_mfma_f32_16x16x32_bf16 v[96:99], v[178:181], v[194:197], v[96:99]
	v_mfma_f32_16x16x32_bf16 v[84:87], v[170:173], v[202:205], v[84:87]
	v_mfma_f32_16x16x32_bf16 v[80:83], v[178:181], v[202:205], v[80:83]
	v_mfma_f32_16x16x32_bf16 v[68:71], v[170:173], v[210:213], v[68:71]
	v_mfma_f32_16x16x32_bf16 v[64:67], v[178:181], v[210:213], v[64:67]
	v_mfma_f32_16x16x32_bf16 v[116:119], v[174:177], v[190:193], v[116:119]
	v_mfma_f32_16x16x32_bf16 v[112:115], v[182:185], v[190:193], v[112:115]
	v_mfma_f32_16x16x32_bf16 v[100:103], v[174:177], v[198:201], v[100:103]
	v_mfma_f32_16x16x32_bf16 v[96:99], v[182:185], v[198:201], v[96:99]
	v_mfma_f32_16x16x32_bf16 v[84:87], v[174:177], v[206:209], v[84:87]
	v_mfma_f32_16x16x32_bf16 v[80:83], v[182:185], v[206:209], v[80:83]
	v_mfma_f32_16x16x32_bf16 v[68:71], v[174:177], v[214:217], v[68:71]
	v_mfma_f32_16x16x32_bf16 v[64:67], v[182:185], v[214:217], v[64:67]
	s_barrier
	s_add_i32 s46, s46, s43
	s_mov_b32 m0, s46
	ds_read_b128 v[186:189], v145 offset:16384
	ds_read_b128 v[190:193], v145 offset:17408
	ds_read_b128 v[194:197], v145 offset:18432
	ds_read_b128 v[198:201], v145 offset:19456
	ds_read_b128 v[202:205], v145 offset:20480
	ds_read_b128 v[206:209], v145 offset:21504
	ds_read_b128 v[210:213], v145 offset:22528
	ds_read_b128 v[214:217], v145 offset:23552
	global_load_lds_dwordx4 v160, s[24:25]
	s_add_i32 m0, s46, 0x2000
	s_add_u32 s94, s24, 0x80000
	s_addc_u32 s95, s25, 0
	s_add_i32 s46, s47, s43
	global_load_lds_dwordx4 v132, s[24:25]
	s_mov_b32 m0, s46
	s_nop 0
	global_load_lds_dwordx4 v160, s[94:95]
	s_add_i32 m0, s46, 0x2000
	s_nop 0
	global_load_lds_dwordx4 v132, s[94:95]
	s_mov_b32 m0, s44
	s_nop 0
	global_load_lds_dwordx4 v128, s[66:67]
	s_mov_b32 m0, s45
	s_nop 0
	global_load_lds_dwordx4 v130, s[66:67]
	s_waitcnt vmcnt(8)
	s_waitcnt lgkmcnt(0)
	s_barrier
	v_mfma_f32_16x16x32_bf16 v[60:63], v[138:141], v[186:189], v[60:63]
	v_mfma_f32_16x16x32_bf16 v[56:59], v[150:153], v[186:189], v[56:59]
	v_mfma_f32_16x16x32_bf16 v[44:47], v[138:141], v[194:197], v[44:47]
	v_mfma_f32_16x16x32_bf16 v[40:43], v[150:153], v[194:197], v[40:43]
	v_mfma_f32_16x16x32_bf16 v[28:31], v[138:141], v[202:205], v[28:31]
	v_mfma_f32_16x16x32_bf16 v[24:27], v[150:153], v[202:205], v[24:27]
	v_mfma_f32_16x16x32_bf16 v[12:15], v[138:141], v[210:213], v[12:15]
	v_mfma_f32_16x16x32_bf16 v[8:11], v[150:153], v[210:213], v[8:11]
	v_mfma_f32_16x16x32_bf16 v[60:63], v[146:149], v[190:193], v[60:63]
	v_mfma_f32_16x16x32_bf16 v[56:59], v[154:157], v[190:193], v[56:59]
	v_mfma_f32_16x16x32_bf16 v[44:47], v[146:149], v[198:201], v[44:47]
	v_mfma_f32_16x16x32_bf16 v[40:43], v[154:157], v[198:201], v[40:43]
	v_mfma_f32_16x16x32_bf16 v[28:31], v[146:149], v[206:209], v[28:31]
	v_mfma_f32_16x16x32_bf16 v[24:27], v[154:157], v[206:209], v[24:27]
	v_mfma_f32_16x16x32_bf16 v[12:15], v[146:149], v[214:217], v[12:15]
	v_mfma_f32_16x16x32_bf16 v[8:11], v[154:157], v[214:217], v[8:11]
	v_mfma_f32_16x16x32_bf16 v[52:55], v[170:173], v[186:189], v[52:55]
	v_mfma_f32_16x16x32_bf16 v[48:51], v[178:181], v[186:189], v[48:51]
	v_mfma_f32_16x16x32_bf16 v[36:39], v[170:173], v[194:197], v[36:39]
	v_mfma_f32_16x16x32_bf16 v[32:35], v[178:181], v[194:197], v[32:35]
	v_mfma_f32_16x16x32_bf16 v[20:23], v[170:173], v[202:205], v[20:23]
	v_mfma_f32_16x16x32_bf16 v[16:19], v[178:181], v[202:205], v[16:19]
	v_mfma_f32_16x16x32_bf16 v[4:7], v[170:173], v[210:213], v[4:7]
	v_mfma_f32_16x16x32_bf16 v[0:3], v[178:181], v[210:213], v[0:3]
	v_mfma_f32_16x16x32_bf16 v[52:55], v[174:177], v[190:193], v[52:55]
	v_mfma_f32_16x16x32_bf16 v[48:51], v[182:185], v[190:193], v[48:51]
	v_mfma_f32_16x16x32_bf16 v[36:39], v[174:177], v[198:201], v[36:39]
	v_mfma_f32_16x16x32_bf16 v[32:35], v[182:185], v[198:201], v[32:35]
	v_mfma_f32_16x16x32_bf16 v[20:23], v[174:177], v[206:209], v[20:23]
	v_mfma_f32_16x16x32_bf16 v[16:19], v[182:185], v[206:209], v[16:19]
	v_mfma_f32_16x16x32_bf16 v[4:7], v[174:177], v[214:217], v[4:7]
	v_mfma_f32_16x16x32_bf16 v[0:3], v[182:185], v[214:217], v[0:3]
	s_barrier
; #define PG8_STAGE(bufoff, gbase, voff) do { _Pragma("unroll") for (int _i = 0; _i < 2; ++_i) \
;         __builtin_amdgcn_global_load_lds((const unsigned*)((const char*)(gbase) + (voff)[_i]), (LAS unsigned*)(lds + (bufoff) + ldsw + _i * 8192), 16, 0, 0); } while (0)
; #define PG8_LDA(dst, b, h) do { _Pragma("unroll") for (int m = 0; m < 4; ++m) _Pragma("unroll") for (int k = 0; k < 2; ++k) dst[m][k] = *(const LAS bf16x8*)(lds + PG8_SA(b, h) + aoff + m * 2048 + k * 1024); } while (0)
; #define PG8_LDB(dst, b, h) do { _Pragma("unroll") for (int n = 0; n < 2; ++n) _Pragma("unroll") for (int k = 0; k < 2; ++k) dst[n][k] = *(const LAS bf16x8*)(lds + PG8_SB(b, h) + boff + n * 2048 + k * 1024); } while (0)
; #define PG8_MMA(ai, bj, At, Bt) do { __builtin_amdgcn_s_setprio(1); _Pragma("unroll") for (int m = 0; m < 4; ++m) _Pragma("unroll") for (int n = 0; n < 2; ++n) _Pragma("unroll") for (int k = 0; k < 2; ++k) \
;         acc[ai][bj][m][n] = __builtin_amdgcn_mfma_f32_16x16x32_bf16(Bt[n][k], At[m][k], acc[ai][bj][m][n], 0, 0, 0); __builtin_amdgcn_s_setprio(0); } while (0)
; #define PG8_WAIT_V(n) asm volatile("s_waitcnt vmcnt(" #n ")" ::: "memory")
; #define PG8_WAIT_L(n) asm volatile("s_waitcnt lgkmcnt(" #n ")" ::: "memory")
; #define PG8_BAR __builtin_amdgcn_s_barrier()
; #define PG8_SCHED __builtin_amdgcn_sched_barrier(0)
; template <class Epi, class Sched, bool ALIGN_EPI = true, bool SP2 = true>
; __device__ __forceinline__ void gemm_phase(LAS unsigned char* lds, const Gemm g, const Sched& S, const Epi& E) {
;     ...
;             PG8_LDB(B0, 1, 0); PG8_LDB(B1, 1, 1); PG8_SCHED; PG8_LDA(At, 1, 0); PG8_STAGE(PG8_SA(0, 1), a2 + hstep, voffA);
;             PG8_WAIT_V(8); PG8_WAIT_L(0); PG8_BAR; PG8_MMA(0, 0, At, B0); PG8_MMA(0, 1, At, B1); PG8_BAR; PG8_SCHED;
;             PG8_LDA(At, 1, 1); PG8_STAGE(PG8_SB(1, 0), b3, voffB); PG8_STAGE(PG8_SB(1, 1), b3 + hstep, voffB); PG8_STAGE(PG8_SA(1, 0), a3, voffA);
;             PG8_WAIT_V(8); PG8_WAIT_L(0); PG8_BAR; PG8_MMA(1, 0, At, B0); PG8_MMA(1, 1, At, B1); PG8_BAR; PG8_SCHED;
;     ...
;         if constexpr (ALIGN_EPI) { if (wr == 0) PG8_BAR; }
	s_add_i32 s46, 0, 0x18000
	s_add_i32 s47, 0, 0x1c000
	v_add_u32_e32 v154, s46, v143
	v_add_u32_e32 v182, s47, v143
	ds_read_b128 v[138:141], v154
	ds_read_b128 v[146:149], v154 offset:1024
	ds_read_b128 v[150:153], v154 offset:2048
	ds_read_b128 v[154:157], v154 offset:3072
	ds_read_b128 v[170:173], v182
	ds_read_b128 v[174:177], v182 offset:1024
	ds_read_b128 v[178:181], v182 offset:2048
	ds_read_b128 v[182:185], v182 offset:3072
	s_add_u32 s66, s66, 0x80000
	s_addc_u32 s67, s67, 0
	s_mov_b32 m0, s61
	ds_read_b128 v[186:189], v145 offset:32768
	ds_read_b128 v[190:193], v145 offset:33792
	ds_read_b128 v[194:197], v145 offset:34816
	ds_read_b128 v[198:201], v145 offset:35840
	ds_read_b128 v[202:205], v145 offset:36864
	ds_read_b128 v[206:209], v145 offset:37888
	ds_read_b128 v[210:213], v145 offset:38912
	ds_read_b128 v[214:217], v145 offset:39936
	global_load_lds_dwordx4 v128, s[66:67]
	s_mov_b32 m0, s72
	s_nop 0
	global_load_lds_dwordx4 v130, s[66:67]
	s_waitcnt vmcnt(8)
	s_waitcnt lgkmcnt(0)
	s_barrier
	v_mfma_f32_16x16x32_bf16 v[124:127], v[138:141], v[186:189], v[124:127]
	v_mfma_f32_16x16x32_bf16 v[120:123], v[150:153], v[186:189], v[120:123]
	v_mfma_f32_16x16x32_bf16 v[108:111], v[138:141], v[194:197], v[108:111]
	v_mfma_f32_16x16x32_bf16 v[104:107], v[150:153], v[194:197], v[104:107]
	v_mfma_f32_16x16x32_bf16 v[92:95], v[138:141], v[202:205], v[92:95]
	v_mfma_f32_16x16x32_bf16 v[88:91], v[150:153], v[202:205], v[88:91]
	v_mfma_f32_16x16x32_bf16 v[76:79], v[138:141], v[210:213], v[76:79]
	v_mfma_f32_16x16x32_bf16 v[72:75], v[150:153], v[210:213], v[72:75]
	v_mfma_f32_16x16x32_bf16 v[124:127], v[146:149], v[190:193], v[124:127]
	v_mfma_f32_16x16x32_bf16 v[120:123], v[154:157], v[190:193], v[120:123]
	v_mfma_f32_16x16x32_bf16 v[108:111], v[146:149], v[198:201], v[108:111]
	v_mfma_f32_16x16x32_bf16 v[104:107], v[154:157], v[198:201], v[104:107]
	v_mfma_f32_16x16x32_bf16 v[92:95], v[146:149], v[206:209], v[92:95]
	v_mfma_f32_16x16x32_bf16 v[88:91], v[154:157], v[206:209], v[88:91]
	v_mfma_f32_16x16x32_bf16 v[76:79], v[146:149], v[214:217], v[76:79]
	v_mfma_f32_16x16x32_bf16 v[72:75], v[154:157], v[214:217], v[72:75]
	v_mfma_f32_16x16x32_bf16 v[116:119], v[170:173], v[186:189], v[116:119]
	v_mfma_f32_16x16x32_bf16 v[112:115], v[178:181], v[186:189], v[112:115]
	v_mfma_f32_16x16x32_bf16 v[100:103], v[170:173], v[194:197], v[100:103]
	v_mfma_f32_16x16x32_bf16 v[96:99], v[178:181], v[194:197], v[96:99]
	v_mfma_f32_16x16x32_bf16 v[84:87], v[170:173], v[202:205], v[84:87]
	v_mfma_f32_16x16x32_bf16 v[80:83], v[178:181], v[202:205], v[80:83]
	v_mfma_f32_16x16x32_bf16 v[68:71], v[170:173], v[210:213], v[68:71]
	v_mfma_f32_16x16x32_bf16 v[64:67], v[178:181], v[210:213], v[64:67]
	v_mfma_f32_16x16x32_bf16 v[116:119], v[174:177], v[190:193], v[116:119]
	v_mfma_f32_16x16x32_bf16 v[112:115], v[182:185], v[190:193], v[112:115]
	v_mfma_f32_16x16x32_bf16 v[100:103], v[174:177], v[198:201], v[100:103]
	v_mfma_f32_16x16x32_bf16 v[96:99], v[182:185], v[198:201], v[96:99]
	v_mfma_f32_16x16x32_bf16 v[84:87], v[174:177], v[206:209], v[84:87]
	v_mfma_f32_16x16x32_bf16 v[80:83], v[182:185], v[206:209], v[80:83]
	v_mfma_f32_16x16x32_bf16 v[68:71], v[174:177], v[214:217], v[68:71]
	v_mfma_f32_16x16x32_bf16 v[64:67], v[182:185], v[214:217], v[64:67]
	s_barrier
	s_add_i32 s46, s46, s43
	s_mov_b32 m0, s46
	ds_read_b128 v[186:189], v145 offset:49152
	ds_read_b128 v[190:193], v145 offset:50176
	ds_read_b128 v[194:197], v145 offset:51200
	ds_read_b128 v[198:201], v145 offset:52224
	ds_read_b128 v[202:205], v145 offset:53248
	ds_read_b128 v[206:209], v145 offset:54272
	ds_read_b128 v[210:213], v145 offset:55296
	ds_read_b128 v[214:217], v145 offset:56320
	s_add_u32 s98, s24, 0x80
	s_addc_u32 s99, s25, 0
	global_load_lds_dwordx4 v160, s[98:99]
	s_add_i32 m0, s46, 0x2000
	s_add_u32 s24, s24, 0x80080
	s_addc_u32 s25, s25, 0
	s_add_i32 s46, s47, s43
	global_load_lds_dwordx4 v132, s[98:99]
	s_mov_b32 m0, s46
	s_nop 0
	global_load_lds_dwordx4 v160, s[24:25]
	s_add_i32 m0, s46, 0x2000
	s_nop 0
	global_load_lds_dwordx4 v132, s[24:25]
	s_mov_b32 m0, s73
	s_nop 0
	s_add_u32 s98, s66, 0xfff80080
	s_addc_u32 s99, s67, -1
	global_load_lds_dwordx4 v128, s[98:99]
	s_mov_b32 m0, s79
	s_nop 0
	global_load_lds_dwordx4 v130, s[98:99]
	s_waitcnt vmcnt(8)
	s_waitcnt lgkmcnt(0)
	s_barrier
	v_mfma_f32_16x16x32_bf16 v[60:63], v[138:141], v[186:189], v[60:63]
	v_mfma_f32_16x16x32_bf16 v[56:59], v[150:153], v[186:189], v[56:59]
	v_mfma_f32_16x16x32_bf16 v[44:47], v[138:141], v[194:197], v[44:47]
	v_mfma_f32_16x16x32_bf16 v[40:43], v[150:153], v[194:197], v[40:43]
	v_mfma_f32_16x16x32_bf16 v[28:31], v[138:141], v[202:205], v[28:31]
	v_mfma_f32_16x16x32_bf16 v[24:27], v[150:153], v[202:205], v[24:27]
	v_mfma_f32_16x16x32_bf16 v[12:15], v[138:141], v[210:213], v[12:15]
	v_mfma_f32_16x16x32_bf16 v[8:11], v[150:153], v[210:213], v[8:11]
	v_mfma_f32_16x16x32_bf16 v[60:63], v[146:149], v[190:193], v[60:63]
	v_mfma_f32_16x16x32_bf16 v[56:59], v[154:157], v[190:193], v[56:59]
	v_mfma_f32_16x16x32_bf16 v[44:47], v[146:149], v[198:201], v[44:47]
	v_mfma_f32_16x16x32_bf16 v[40:43], v[154:157], v[198:201], v[40:43]
	v_mfma_f32_16x16x32_bf16 v[28:31], v[146:149], v[206:209], v[28:31]
	v_mfma_f32_16x16x32_bf16 v[24:27], v[154:157], v[206:209], v[24:27]
	v_mfma_f32_16x16x32_bf16 v[12:15], v[146:149], v[214:217], v[12:15]
	v_mfma_f32_16x16x32_bf16 v[8:11], v[154:157], v[214:217], v[8:11]
	v_mfma_f32_16x16x32_bf16 v[52:55], v[170:173], v[186:189], v[52:55]
	v_mfma_f32_16x16x32_bf16 v[48:51], v[178:181], v[186:189], v[48:51]
	v_mfma_f32_16x16x32_bf16 v[36:39], v[170:173], v[194:197], v[36:39]
	v_mfma_f32_16x16x32_bf16 v[32:35], v[178:181], v[194:197], v[32:35]
	v_mfma_f32_16x16x32_bf16 v[20:23], v[170:173], v[202:205], v[20:23]
	v_mfma_f32_16x16x32_bf16 v[16:19], v[178:181], v[202:205], v[16:19]
	v_mfma_f32_16x16x32_bf16 v[4:7], v[170:173], v[210:213], v[4:7]
	v_mfma_f32_16x16x32_bf16 v[0:3], v[178:181], v[210:213], v[0:3]
	v_mfma_f32_16x16x32_bf16 v[52:55], v[174:177], v[190:193], v[52:55]
	v_mfma_f32_16x16x32_bf16 v[48:51], v[182:185], v[190:193], v[48:51]
	v_mfma_f32_16x16x32_bf16 v[36:39], v[174:177], v[198:201], v[36:39]
	v_mfma_f32_16x16x32_bf16 v[32:35], v[182:185], v[198:201], v[32:35]
	v_mfma_f32_16x16x32_bf16 v[20:23], v[174:177], v[206:209], v[20:23]
	v_mfma_f32_16x16x32_bf16 v[16:19], v[182:185], v[206:209], v[16:19]
	v_mfma_f32_16x16x32_bf16 v[4:7], v[174:177], v[214:217], v[4:7]
	v_mfma_f32_16x16x32_bf16 v[0:3], v[182:185], v[214:217], v[0:3]
	s_barrier
	s_add_i32 s93, s93, 2
	s_add_u32 s62, s62, 0x100
	s_addc_u32 s63, s63, 0
	s_add_u32 s91, s91, 0x100
	s_addc_u32 s92, s92, 0
	s_cmp_gt_u32 s93, 29
	s_cbranch_scc0 .LBB0_93
	s_setprio 0
	s_and_b64 vcc, exec, s[16:17]
	s_movk_i32 s91, 0x161
	s_movk_i32 s92, 0x7ff
	s_cbranch_vccz .LBB0_96
	s_barrier

; #define PG8_STAGE(bufoff, gbase, voff) do { _Pragma("unroll") for (int _i = 0; _i < 2; ++_i) \
;         __builtin_amdgcn_global_load_lds((const unsigned*)((const char*)(gbase) + (voff)[_i]), (LAS unsigned*)(lds + (bufoff) + ldsw + _i * 8192), 16, 0, 0); } while (0)
; #define PG8_LDA(dst, b, h) do { _Pragma("unroll") for (int m = 0; m < 4; ++m) _Pragma("unroll") for (int k = 0; k < 2; ++k) dst[m][k] = *(const LAS bf16x8*)(lds + PG8_SA(b, h) + aoff + m * 2048 + k * 1024); } while (0)
; #define PG8_LDB(dst, b, h) do { _Pragma("unroll") for (int n = 0; n < 2; ++n) _Pragma("unroll") for (int k = 0; k < 2; ++k) dst[n][k] = *(const LAS bf16x8*)(lds + PG8_SB(b, h) + boff + n * 2048 + k * 1024); } while (0)
; #define PG8_MMA(ai, bj, At, Bt) do { __builtin_amdgcn_s_setprio(1); _Pragma("unroll") for (int m = 0; m < 4; ++m) _Pragma("unroll") for (int n = 0; n < 2; ++n) _Pragma("unroll") for (int k = 0; k < 2; ++k) \
;         acc[ai][bj][m][n] = __builtin_amdgcn_mfma_f32_16x16x32_bf16(Bt[n][k], At[m][k], acc[ai][bj][m][n], 0, 0, 0); __builtin_amdgcn_s_setprio(0); } while (0)
; #define PG8_WAIT_V(n) asm volatile("s_waitcnt vmcnt(" #n ")" ::: "memory")
; #define PG8_WAIT_L(n) asm volatile("s_waitcnt lgkmcnt(" #n ")" ::: "memory")
; #define PG8_BAR __builtin_amdgcn_s_barrier()
; #define PG8_SCHED __builtin_amdgcn_sched_barrier(0)
; template <class Epi, class Sched, bool ALIGN_EPI = true, bool SP2 = true>
; __device__ __forceinline__ void gemm_phase(LAS unsigned char* lds, const Gemm g, const Sched& S, const Epi& E) {
;     ...
;             const char* a1 = cA + (size_t)(t + 1) * kstep;
;             const char* a2 = last ? nA : cA + (size_t)(t + 2) * kstep; const char* b2 = last ? nB : cB + (size_t)(t + 2) * kstep;
;             const char* a3 = a2 + kstep; const char* b3 = b2 + kstep;
;             if constexpr (SP2) {
;             PG8_LDB(B0, 0, 0); PG8_LDB(B1, 0, 1); PG8_SCHED; PG8_LDA(At, 0, 0); PG8_STAGE(PG8_SA(1, 1), a1 + hstep, voffA);
;             PG8_WAIT_V(8); PG8_WAIT_L(0); PG8_BAR; PG8_MMA(0, 0, At, B0); PG8_MMA(0, 1, At, B1); PG8_BAR; PG8_SCHED;
;             PG8_LDA(At, 0, 1); PG8_STAGE(PG8_SB(0, 0), b2, voffB); PG8_STAGE(PG8_SB(0, 1), b2 + hstep, voffB); PG8_STAGE(PG8_SA(0, 0), a2, voffA);
;             PG8_WAIT_V(8); PG8_WAIT_L(0); PG8_BAR; PG8_MMA(1, 0, At, B0); PG8_MMA(1, 1, At, B1); PG8_BAR; PG8_SCHED;
.Lprio_skip_117:
.LBB0_117:
	s_add_u32 s24, s62, 0xfff80080
	s_addc_u32 s25, s63, -1
	s_add_i32 s46, 0, 0x10000
	s_cmp_eq_u32 s96, 28
	s_cselect_b32 s67, s2, s25
	s_cselect_b32 s66, s3, s24
	s_cselect_b32 s25, s17, s95
	s_cselect_b32 s24, s19, s94
	s_add_i32 s47, 0, 0x14000
	v_add_u32_e32 v154, s46, v143
	v_add_u32_e32 v158, s47, v143
	ds_read_b128 v[138:141], v154
	ds_read_b128 v[146:149], v154 offset:1024
	ds_read_b128 v[150:153], v154 offset:2048
	ds_read_b128 v[154:157], v154 offset:3072
	ds_read_b128 v[170:173], v158
	ds_read_b128 v[174:177], v158 offset:1024
	ds_read_b128 v[178:181], v158 offset:2048
	ds_read_b128 v[182:185], v158 offset:3072
	s_add_i32 m0, s61, 0xc000
	ds_read_b128 v[186:189], v145
	ds_read_b128 v[190:193], v145 offset:1024
	ds_read_b128 v[194:197], v145 offset:2048
	ds_read_b128 v[198:201], v145 offset:3072
	ds_read_b128 v[202:205], v145 offset:4096
	ds_read_b128 v[206:209], v145 offset:5120
	ds_read_b128 v[210:213], v145 offset:6144
	ds_read_b128 v[214:217], v145 offset:7168
	global_load_lds_dwordx4 v134, s[62:63]
	s_add_i32 m0, s61, 0xe000
	s_nop 0
	global_load_lds_dwordx4 v136, s[62:63]
	s_waitcnt vmcnt(8)
	s_waitcnt lgkmcnt(0)
	s_barrier
	v_mfma_f32_16x16x32_bf16 v[124:127], v[138:141], v[186:189], v[124:127]
	v_mfma_f32_16x16x32_bf16 v[120:123], v[150:153], v[186:189], v[120:123]
	v_mfma_f32_16x16x32_bf16 v[108:111], v[138:141], v[194:197], v[108:111]
	v_mfma_f32_16x16x32_bf16 v[104:107], v[150:153], v[194:197], v[104:107]
	v_mfma_f32_16x16x32_bf16 v[92:95], v[138:141], v[202:205], v[92:95]
	v_mfma_f32_16x16x32_bf16 v[88:91], v[150:153], v[202:205], v[88:91]
	v_mfma_f32_16x16x32_bf16 v[76:79], v[138:141], v[210:213], v[76:79]
	v_mfma_f32_16x16x32_bf16 v[72:75], v[150:153], v[210:213], v[72:75]
	v_mfma_f32_16x16x32_bf16 v[124:127], v[146:149], v[190:193], v[124:127]
	v_mfma_f32_16x16x32_bf16 v[120:123], v[154:157], v[190:193], v[120:123]
	v_mfma_f32_16x16x32_bf16 v[108:111], v[146:149], v[198:201], v[108:111]
	v_mfma_f32_16x16x32_bf16 v[104:107], v[154:157], v[198:201], v[104:107]
	v_mfma_f32_16x16x32_bf16 v[92:95], v[146:149], v[206:209], v[92:95]
	v_mfma_f32_16x16x32_bf16 v[88:91], v[154:157], v[206:209], v[88:91]
	v_mfma_f32_16x16x32_bf16 v[76:79], v[146:149], v[214:217], v[76:79]
	v_mfma_f32_16x16x32_bf16 v[72:75], v[154:157], v[214:217], v[72:75]
	v_mfma_f32_16x16x32_bf16 v[116:119], v[170:173], v[186:189], v[116:119]
	v_mfma_f32_16x16x32_bf16 v[112:115], v[178:181], v[186:189], v[112:115]
	v_mfma_f32_16x16x32_bf16 v[100:103], v[170:173], v[194:197], v[100:103]
	v_mfma_f32_16x16x32_bf16 v[96:99], v[178:181], v[194:197], v[96:99]
	v_mfma_f32_16x16x32_bf16 v[84:87], v[170:173], v[202:205], v[84:87]
	v_mfma_f32_16x16x32_bf16 v[80:83], v[178:181], v[202:205], v[80:83]
	v_mfma_f32_16x16x32_bf16 v[68:71], v[170:173], v[210:213], v[68:71]
	v_mfma_f32_16x16x32_bf16 v[64:67], v[178:181], v[210:213], v[64:67]
	v_mfma_f32_16x16x32_bf16 v[116:119], v[174:177], v[190:193], v[116:119]
	v_mfma_f32_16x16x32_bf16 v[112:115], v[182:185], v[190:193], v[112:115]
	v_mfma_f32_16x16x32_bf16 v[100:103], v[174:177], v[198:201], v[100:103]
	v_mfma_f32_16x16x32_bf16 v[96:99], v[182:185], v[198:201], v[96:99]
	v_mfma_f32_16x16x32_bf16 v[84:87], v[174:177], v[206:209], v[84:87]
	v_mfma_f32_16x16x32_bf16 v[80:83], v[182:185], v[206:209], v[80:83]
	v_mfma_f32_16x16x32_bf16 v[68:71], v[174:177], v[214:217], v[68:71]
	v_mfma_f32_16x16x32_bf16 v[64:67], v[182:185], v[214:217], v[64:67]
	s_barrier
	s_add_i32 s46, s46, s44
	s_mov_b32 m0, s46
	ds_read_b128 v[186:189], v145 offset:16384
	ds_read_b128 v[190:193], v145 offset:17408
	ds_read_b128 v[194:197], v145 offset:18432
	ds_read_b128 v[198:201], v145 offset:19456
	ds_read_b128 v[202:205], v145 offset:20480
	ds_read_b128 v[206:209], v145 offset:21504
	ds_read_b128 v[210:213], v145 offset:22528
	ds_read_b128 v[214:217], v145 offset:23552
	global_load_lds_dwordx4 v160, s[24:25]
	s_add_i32 m0, s46, 0x2000
	s_add_u32 vcc_lo, s24, 0x80000
	s_addc_u32 vcc_hi, s25, 0
	s_add_i32 s46, s47, s44
	global_load_lds_dwordx4 v132, s[24:25]
	v_lshl_add_u64 v[218:219], vcc, 0, v[160:161]
	s_mov_b32 m0, s46
	s_nop 0
	global_load_lds_dwordx4 v[218:219], off
	v_lshl_add_u64 v[218:219], vcc, 0, v[132:133]
	s_add_i32 m0, s46, 0x2000
	s_nop 0
	global_load_lds_dwordx4 v[218:219], off
	s_mov_b32 m0, s61
	s_nop 0
	global_load_lds_dwordx4 v128, s[66:67]
	s_mov_b32 m0, s73
	s_nop 0
	global_load_lds_dwordx4 v130, s[66:67]
	s_waitcnt vmcnt(8)
	s_waitcnt lgkmcnt(0)
	s_barrier
	v_mfma_f32_16x16x32_bf16 v[60:63], v[138:141], v[186:189], v[60:63]
	v_mfma_f32_16x16x32_bf16 v[56:59], v[150:153], v[186:189], v[56:59]
	v_mfma_f32_16x16x32_bf16 v[44:47], v[138:141], v[194:197], v[44:47]
	v_mfma_f32_16x16x32_bf16 v[40:43], v[150:153], v[194:197], v[40:43]
	v_mfma_f32_16x16x32_bf16 v[28:31], v[138:141], v[202:205], v[28:31]
	v_mfma_f32_16x16x32_bf16 v[24:27], v[150:153], v[202:205], v[24:27]
	v_mfma_f32_16x16x32_bf16 v[12:15], v[138:141], v[210:213], v[12:15]
	v_mfma_f32_16x16x32_bf16 v[8:11], v[150:153], v[210:213], v[8:11]
	v_mfma_f32_16x16x32_bf16 v[60:63], v[146:149], v[190:193], v[60:63]
	v_mfma_f32_16x16x32_bf16 v[56:59], v[154:157], v[190:193], v[56:59]
	v_mfma_f32_16x16x32_bf16 v[44:47], v[146:149], v[198:201], v[44:47]
	v_mfma_f32_16x16x32_bf16 v[40:43], v[154:157], v[198:201], v[40:43]
	v_mfma_f32_16x16x32_bf16 v[28:31], v[146:149], v[206:209], v[28:31]
	v_mfma_f32_16x16x32_bf16 v[24:27], v[154:157], v[206:209], v[24:27]
	v_mfma_f32_16x16x32_bf16 v[12:15], v[146:149], v[214:217], v[12:15]
	v_mfma_f32_16x16x32_bf16 v[8:11], v[154:157], v[214:217], v[8:11]
	v_mfma_f32_16x16x32_bf16 v[52:55], v[170:173], v[186:189], v[52:55]
	v_mfma_f32_16x16x32_bf16 v[48:51], v[178:181], v[186:189], v[48:51]
	v_mfma_f32_16x16x32_bf16 v[36:39], v[170:173], v[194:197], v[36:39]
	v_mfma_f32_16x16x32_bf16 v[32:35], v[178:181], v[194:197], v[32:35]
	v_mfma_f32_16x16x32_bf16 v[20:23], v[170:173], v[202:205], v[20:23]
	v_mfma_f32_16x16x32_bf16 v[16:19], v[178:181], v[202:205], v[16:19]
	v_mfma_f32_16x16x32_bf16 v[4:7], v[170:173], v[210:213], v[4:7]
	v_mfma_f32_16x16x32_bf16 v[0:3], v[178:181], v[210:213], v[0:3]
	v_mfma_f32_16x16x32_bf16 v[52:55], v[174:177], v[190:193], v[52:55]
	v_mfma_f32_16x16x32_bf16 v[48:51], v[182:185], v[190:193], v[48:51]
	v_mfma_f32_16x16x32_bf16 v[36:39], v[174:177], v[198:201], v[36:39]
	v_mfma_f32_16x16x32_bf16 v[32:35], v[182:185], v[198:201], v[32:35]
	v_mfma_f32_16x16x32_bf16 v[20:23], v[174:177], v[206:209], v[20:23]
	v_mfma_f32_16x16x32_bf16 v[16:19], v[182:185], v[206:209], v[16:19]
	v_mfma_f32_16x16x32_bf16 v[4:7], v[174:177], v[214:217], v[4:7]
	v_mfma_f32_16x16x32_bf16 v[0:3], v[182:185], v[214:217], v[0:3]
	s_barrier
; #define PG8_STAGE(bufoff, gbase, voff) do { _Pragma("unroll") for (int _i = 0; _i < 2; ++_i) \
;         __builtin_amdgcn_global_load_lds((const unsigned*)((const char*)(gbase) + (voff)[_i]), (LAS unsigned*)(lds + (bufoff) + ldsw + _i * 8192), 16, 0, 0); } while (0)
; #define PG8_LDA(dst, b, h) do { _Pragma("unroll") for (int m = 0; m < 4; ++m) _Pragma("unroll") for (int k = 0; k < 2; ++k) dst[m][k] = *(const LAS bf16x8*)(lds + PG8_SA(b, h) + aoff + m * 2048 + k * 1024); } while (0)
; #define PG8_LDB(dst, b, h) do { _Pragma("unroll") for (int n = 0; n < 2; ++n) _Pragma("unroll") for (int k = 0; k < 2; ++k) dst[n][k] = *(const LAS bf16x8*)(lds + PG8_SB(b, h) + boff + n * 2048 + k * 1024); } while (0)
; #define PG8_MMA(ai, bj, At, Bt) do { __builtin_amdgcn_s_setprio(1); _Pragma("unroll") for (int m = 0; m < 4; ++m) _Pragma("unroll") for (int n = 0; n < 2; ++n) _Pragma("unroll") for (int k = 0; k < 2; ++k) \
;         acc[ai][bj][m][n] = __builtin_amdgcn_mfma_f32_16x16x32_bf16(Bt[n][k], At[m][k], acc[ai][bj][m][n], 0, 0, 0); __builtin_amdgcn_s_setprio(0); } while (0)
; #define PG8_WAIT_V(n) asm volatile("s_waitcnt vmcnt(" #n ")" ::: "memory")
; #define PG8_WAIT_L(n) asm volatile("s_waitcnt lgkmcnt(" #n ")" ::: "memory")
; #define PG8_BAR __builtin_amdgcn_s_barrier()
; #define PG8_SCHED __builtin_amdgcn_sched_barrier(0)
; template <class Epi, class Sched, bool ALIGN_EPI = true, bool SP2 = true>
; __device__ __forceinline__ void gemm_phase(LAS unsigned char* lds, const Gemm g, const Sched& S, const Epi& E) {
;     ...
;             PG8_LDB(B0, 1, 0); PG8_LDB(B1, 1, 1); PG8_SCHED; PG8_LDA(At, 1, 0); PG8_STAGE(PG8_SA(0, 1), a2 + hstep, voffA);
;             PG8_WAIT_V(8); PG8_WAIT_L(0); PG8_BAR; PG8_MMA(0, 0, At, B0); PG8_MMA(0, 1, At, B1); PG8_BAR; PG8_SCHED;
;             PG8_LDA(At, 1, 1); PG8_STAGE(PG8_SB(1, 0), b3, voffB); PG8_STAGE(PG8_SB(1, 1), b3 + hstep, voffB); PG8_STAGE(PG8_SA(1, 0), a3, voffA);
;             PG8_WAIT_V(8); PG8_WAIT_L(0); PG8_BAR; PG8_MMA(1, 0, At, B0); PG8_MMA(1, 1, At, B1); PG8_BAR; PG8_SCHED;
;     ...
;         if constexpr (ALIGN_EPI) { if (wr == 0) PG8_BAR; }
	s_add_i32 s46, 0, 0x18000
	s_add_i32 s47, 0, 0x1c000
	v_add_u32_e32 v154, s46, v143
	v_add_u32_e32 v182, s47, v143
	ds_read_b128 v[138:141], v154
	ds_read_b128 v[146:149], v154 offset:1024
	ds_read_b128 v[150:153], v154 offset:2048
	ds_read_b128 v[154:157], v154 offset:3072
	ds_read_b128 v[170:173], v182
	ds_read_b128 v[174:177], v182 offset:1024
	ds_read_b128 v[178:181], v182 offset:2048
	ds_read_b128 v[182:185], v182 offset:3072
	s_add_u32 s66, s66, 0x80000
	s_addc_u32 s67, s67, 0
	s_mov_b32 m0, s79
	ds_read_b128 v[186:189], v145 offset:32768
	ds_read_b128 v[190:193], v145 offset:33792
	ds_read_b128 v[194:197], v145 offset:34816
	ds_read_b128 v[198:201], v145 offset:35840
	ds_read_b128 v[202:205], v145 offset:36864
	ds_read_b128 v[206:209], v145 offset:37888
	ds_read_b128 v[210:213], v145 offset:38912
	ds_read_b128 v[214:217], v145 offset:39936
	global_load_lds_dwordx4 v128, s[66:67]
	s_mov_b32 m0, s82
	s_nop 0
	global_load_lds_dwordx4 v130, s[66:67]
	s_waitcnt vmcnt(8)
	s_waitcnt lgkmcnt(0)
	s_barrier
	v_mfma_f32_16x16x32_bf16 v[124:127], v[138:141], v[186:189], v[124:127]
	v_mfma_f32_16x16x32_bf16 v[120:123], v[150:153], v[186:189], v[120:123]
	v_mfma_f32_16x16x32_bf16 v[108:111], v[138:141], v[194:197], v[108:111]
	v_mfma_f32_16x16x32_bf16 v[104:107], v[150:153], v[194:197], v[104:107]
	v_mfma_f32_16x16x32_bf16 v[92:95], v[138:141], v[202:205], v[92:95]
	v_mfma_f32_16x16x32_bf16 v[88:91], v[150:153], v[202:205], v[88:91]
	v_mfma_f32_16x16x32_bf16 v[76:79], v[138:141], v[210:213], v[76:79]
	v_mfma_f32_16x16x32_bf16 v[72:75], v[150:153], v[210:213], v[72:75]
	v_mfma_f32_16x16x32_bf16 v[124:127], v[146:149], v[190:193], v[124:127]
	v_mfma_f32_16x16x32_bf16 v[120:123], v[154:157], v[190:193], v[120:123]
	v_mfma_f32_16x16x32_bf16 v[108:111], v[146:149], v[198:201], v[108:111]
	v_mfma_f32_16x16x32_bf16 v[104:107], v[154:157], v[198:201], v[104:107]
	v_mfma_f32_16x16x32_bf16 v[92:95], v[146:149], v[206:209], v[92:95]
	v_mfma_f32_16x16x32_bf16 v[88:91], v[154:157], v[206:209], v[88:91]
	v_mfma_f32_16x16x32_bf16 v[76:79], v[146:149], v[214:217], v[76:79]
	v_mfma_f32_16x16x32_bf16 v[72:75], v[154:157], v[214:217], v[72:75]
	v_mfma_f32_16x16x32_bf16 v[116:119], v[170:173], v[186:189], v[116:119]
	v_mfma_f32_16x16x32_bf16 v[112:115], v[178:181], v[186:189], v[112:115]
	v_mfma_f32_16x16x32_bf16 v[100:103], v[170:173], v[194:197], v[100:103]
	v_mfma_f32_16x16x32_bf16 v[96:99], v[178:181], v[194:197], v[96:99]
	v_mfma_f32_16x16x32_bf16 v[84:87], v[170:173], v[202:205], v[84:87]
	v_mfma_f32_16x16x32_bf16 v[80:83], v[178:181], v[202:205], v[80:83]
	v_mfma_f32_16x16x32_bf16 v[68:71], v[170:173], v[210:213], v[68:71]
	v_mfma_f32_16x16x32_bf16 v[64:67], v[178:181], v[210:213], v[64:67]
	v_mfma_f32_16x16x32_bf16 v[116:119], v[174:177], v[190:193], v[116:119]
	v_mfma_f32_16x16x32_bf16 v[112:115], v[182:185], v[190:193], v[112:115]
	v_mfma_f32_16x16x32_bf16 v[100:103], v[174:177], v[198:201], v[100:103]
	v_mfma_f32_16x16x32_bf16 v[96:99], v[182:185], v[198:201], v[96:99]
	v_mfma_f32_16x16x32_bf16 v[84:87], v[174:177], v[206:209], v[84:87]
	v_mfma_f32_16x16x32_bf16 v[80:83], v[182:185], v[206:209], v[80:83]
	v_mfma_f32_16x16x32_bf16 v[68:71], v[174:177], v[214:217], v[68:71]
	v_mfma_f32_16x16x32_bf16 v[64:67], v[182:185], v[214:217], v[64:67]
	s_barrier
	s_add_i32 s46, s46, s44
	s_mov_b32 m0, s46
	ds_read_b128 v[186:189], v145 offset:49152
	ds_read_b128 v[190:193], v145 offset:50176
	ds_read_b128 v[194:197], v145 offset:51200
	ds_read_b128 v[198:201], v145 offset:52224
	ds_read_b128 v[202:205], v145 offset:53248
	ds_read_b128 v[206:209], v145 offset:54272
	ds_read_b128 v[210:213], v145 offset:55296
	ds_read_b128 v[214:217], v145 offset:56320
	s_add_u32 s98, s24, 0x80
	s_addc_u32 s99, s25, 0
	global_load_lds_dwordx4 v160, s[98:99]
	s_add_i32 m0, s46, 0x2000
	s_add_u32 s24, s24, 0x80080
	s_addc_u32 s25, s25, 0
	s_add_i32 s46, s47, s44
	global_load_lds_dwordx4 v132, s[98:99]
	s_mov_b32 m0, s46
	s_nop 0
	global_load_lds_dwordx4 v160, s[24:25]
	s_add_i32 m0, s46, 0x2000
	s_nop 0
	global_load_lds_dwordx4 v132, s[24:25]
	s_mov_b32 m0, s83
	s_nop 0
	s_add_u32 s98, s66, 0xfff80080
	s_addc_u32 s99, s67, -1
	global_load_lds_dwordx4 v128, s[98:99]
	s_mov_b32 m0, s90
	s_nop 0
	global_load_lds_dwordx4 v130, s[98:99]
	s_waitcnt vmcnt(8)
	s_waitcnt lgkmcnt(0)
	s_barrier
	v_mfma_f32_16x16x32_bf16 v[60:63], v[138:141], v[186:189], v[60:63]
	v_mfma_f32_16x16x32_bf16 v[56:59], v[150:153], v[186:189], v[56:59]
	v_mfma_f32_16x16x32_bf16 v[44:47], v[138:141], v[194:197], v[44:47]
	v_mfma_f32_16x16x32_bf16 v[40:43], v[150:153], v[194:197], v[40:43]
	v_mfma_f32_16x16x32_bf16 v[28:31], v[138:141], v[202:205], v[28:31]
	v_mfma_f32_16x16x32_bf16 v[24:27], v[150:153], v[202:205], v[24:27]
	v_mfma_f32_16x16x32_bf16 v[12:15], v[138:141], v[210:213], v[12:15]
	v_mfma_f32_16x16x32_bf16 v[8:11], v[150:153], v[210:213], v[8:11]
	v_mfma_f32_16x16x32_bf16 v[60:63], v[146:149], v[190:193], v[60:63]
	v_mfma_f32_16x16x32_bf16 v[56:59], v[154:157], v[190:193], v[56:59]
	v_mfma_f32_16x16x32_bf16 v[44:47], v[146:149], v[198:201], v[44:47]
	v_mfma_f32_16x16x32_bf16 v[40:43], v[154:157], v[198:201], v[40:43]
	v_mfma_f32_16x16x32_bf16 v[28:31], v[146:149], v[206:209], v[28:31]
	v_mfma_f32_16x16x32_bf16 v[24:27], v[154:157], v[206:209], v[24:27]
	v_mfma_f32_16x16x32_bf16 v[12:15], v[146:149], v[214:217], v[12:15]
	v_mfma_f32_16x16x32_bf16 v[8:11], v[154:157], v[214:217], v[8:11]
	v_mfma_f32_16x16x32_bf16 v[52:55], v[170:173], v[186:189], v[52:55]
	v_mfma_f32_16x16x32_bf16 v[48:51], v[178:181], v[186:189], v[48:51]
	v_mfma_f32_16x16x32_bf16 v[36:39], v[170:173], v[194:197], v[36:39]
	v_mfma_f32_16x16x32_bf16 v[32:35], v[178:181], v[194:197], v[32:35]
	v_mfma_f32_16x16x32_bf16 v[20:23], v[170:173], v[202:205], v[20:23]
	v_mfma_f32_16x16x32_bf16 v[16:19], v[178:181], v[202:205], v[16:19]
	v_mfma_f32_16x16x32_bf16 v[4:7], v[170:173], v[210:213], v[4:7]
	v_mfma_f32_16x16x32_bf16 v[0:3], v[178:181], v[210:213], v[0:3]
	v_mfma_f32_16x16x32_bf16 v[52:55], v[174:177], v[190:193], v[52:55]
	v_mfma_f32_16x16x32_bf16 v[48:51], v[182:185], v[190:193], v[48:51]
	v_mfma_f32_16x16x32_bf16 v[36:39], v[174:177], v[198:201], v[36:39]
	v_mfma_f32_16x16x32_bf16 v[32:35], v[182:185], v[198:201], v[32:35]
	v_mfma_f32_16x16x32_bf16 v[20:23], v[174:177], v[206:209], v[20:23]
	v_mfma_f32_16x16x32_bf16 v[16:19], v[182:185], v[206:209], v[16:19]
	v_mfma_f32_16x16x32_bf16 v[4:7], v[174:177], v[214:217], v[4:7]
	v_mfma_f32_16x16x32_bf16 v[0:3], v[182:185], v[214:217], v[0:3]
	s_barrier
	s_add_i32 s96, s96, 2
	s_add_u32 s62, s62, 0x100
	s_addc_u32 s63, s63, 0
	s_add_u32 s94, s94, 0x100
	s_addc_u32 s95, s95, 0
	s_cmp_gt_u32 s96, 29
	s_cbranch_scc0 .LBB0_117
	s_setprio 0
	s_and_b64 vcc, exec, s[10:11]
	s_mov_b64 s[96:97], 0x80000
	s_cbranch_vccz .LBB0_120
	s_barrier

; #define PG8_STAGE(bufoff, gbase, voff) do { _Pragma("unroll") for (int _i = 0; _i < 2; ++_i) \
;         __builtin_amdgcn_global_load_lds((const unsigned*)((const char*)(gbase) + (voff)[_i]), (LAS unsigned*)(lds + (bufoff) + ldsw + _i * 8192), 16, 0, 0); } while (0)
; #define PG8_LDA(dst, b, h) do { _Pragma("unroll") for (int m = 0; m < 4; ++m) _Pragma("unroll") for (int k = 0; k < 2; ++k) dst[m][k] = *(const LAS bf16x8*)(lds + PG8_SA(b, h) + aoff + m * 2048 + k * 1024); } while (0)
; #define PG8_LDB(dst, b, h) do { _Pragma("unroll") for (int n = 0; n < 2; ++n) _Pragma("unroll") for (int k = 0; k < 2; ++k) dst[n][k] = *(const LAS bf16x8*)(lds + PG8_SB(b, h) + boff + n * 2048 + k * 1024); } while (0)
; #define PG8_MMA(ai, bj, At, Bt) do { __builtin_amdgcn_s_setprio(1); _Pragma("unroll") for (int m = 0; m < 4; ++m) _Pragma("unroll") for (int n = 0; n < 2; ++n) _Pragma("unroll") for (int k = 0; k < 2; ++k) \
;         acc[ai][bj][m][n] = __builtin_amdgcn_mfma_f32_16x16x32_bf16(Bt[n][k], At[m][k], acc[ai][bj][m][n], 0, 0, 0); __builtin_amdgcn_s_setprio(0); } while (0)
; #define PG8_WAIT_V(n) asm volatile("s_waitcnt vmcnt(" #n ")" ::: "memory")
; #define PG8_WAIT_L(n) asm volatile("s_waitcnt lgkmcnt(" #n ")" ::: "memory")
; #define PG8_BAR __builtin_amdgcn_s_barrier()
; #define PG8_SCHED __builtin_amdgcn_sched_barrier(0)
; template <class Epi, class Sched, bool ALIGN_EPI = true, bool SP2 = true>
; __device__ __forceinline__ void gemm_phase(LAS unsigned char* lds, const Gemm g, const Sched& S, const Epi& E) {
;     ...
;             const char* a1 = cA + (size_t)(t + 1) * kstep;
;             const char* a2 = last ? nA : cA + (size_t)(t + 2) * kstep; const char* b2 = last ? nB : cB + (size_t)(t + 2) * kstep;
;             const char* a3 = a2 + kstep; const char* b3 = b2 + kstep;
;             if constexpr (SP2) {
;             PG8_LDB(B0, 0, 0); PG8_LDB(B1, 0, 1); PG8_SCHED; PG8_LDA(At, 0, 0); PG8_STAGE(PG8_SA(1, 1), a1 + hstep, voffA);
;             PG8_WAIT_V(8); PG8_WAIT_L(0); PG8_BAR; PG8_MMA(0, 0, At, B0); PG8_MMA(0, 1, At, B1); PG8_BAR; PG8_SCHED;
;             PG8_LDA(At, 0, 1); PG8_STAGE(PG8_SB(0, 0), b2, voffB); PG8_STAGE(PG8_SB(0, 1), b2 + hstep, voffB); PG8_STAGE(PG8_SA(0, 0), a2, voffA);
;             PG8_WAIT_V(8); PG8_WAIT_L(0); PG8_BAR; PG8_MMA(1, 0, At, B0); PG8_MMA(1, 1, At, B1); PG8_BAR; PG8_SCHED;
.Lprio_skip_145:
.LBB0_145:
	s_add_u32 s24, s72, 0xfff80080
	s_addc_u32 s25, s73, -1
	s_add_i32 s46, 0, 0x10000
	s_cmp_eq_u32 s95, 28
	s_cselect_b32 s83, s2, s25
	s_cselect_b32 s82, s3, s24
	v_add_u32_e32 v142, s46, v145
	s_cselect_b32 s25, s31, s53
	s_cselect_b32 s24, s44, s45
	s_add_i32 s47, 0, 0x14000
	ds_read_b128 v[138:141], v142
	ds_read_b128 v[148:151], v142 offset:1024
	ds_read_b128 v[152:155], v142 offset:2048
	ds_read_b128 v[156:159], v142 offset:3072
	v_add_u32_e32 v142, s47, v145
	ds_read_b128 v[170:173], v142
	ds_read_b128 v[174:177], v142 offset:1024
	ds_read_b128 v[178:181], v142 offset:2048
	ds_read_b128 v[182:185], v142 offset:3072
	s_add_i32 m0, s63, 0xc000
	ds_read_b128 v[186:189], v147
	ds_read_b128 v[190:193], v147 offset:1024
	ds_read_b128 v[194:197], v147 offset:2048
	ds_read_b128 v[198:201], v147 offset:3072
	ds_read_b128 v[202:205], v147 offset:4096
	ds_read_b128 v[206:209], v147 offset:5120
	ds_read_b128 v[210:213], v147 offset:6144
	ds_read_b128 v[214:217], v147 offset:7168
	global_load_lds_dwordx4 v134, s[72:73]
	s_add_i32 m0, s63, 0xe000
	s_nop 0
	global_load_lds_dwordx4 v136, s[72:73]
	s_waitcnt vmcnt(8)
	s_waitcnt lgkmcnt(0)
	s_barrier
	v_mfma_f32_16x16x32_bf16 v[124:127], v[138:141], v[186:189], v[124:127]
	v_mfma_f32_16x16x32_bf16 v[120:123], v[152:155], v[186:189], v[120:123]
	v_mfma_f32_16x16x32_bf16 v[108:111], v[138:141], v[194:197], v[108:111]
	v_mfma_f32_16x16x32_bf16 v[104:107], v[152:155], v[194:197], v[104:107]
	v_mfma_f32_16x16x32_bf16 v[92:95], v[138:141], v[202:205], v[92:95]
	v_mfma_f32_16x16x32_bf16 v[88:91], v[152:155], v[202:205], v[88:91]
	v_mfma_f32_16x16x32_bf16 v[76:79], v[138:141], v[210:213], v[76:79]
	v_mfma_f32_16x16x32_bf16 v[72:75], v[152:155], v[210:213], v[72:75]
	v_mfma_f32_16x16x32_bf16 v[124:127], v[148:151], v[190:193], v[124:127]
	v_mfma_f32_16x16x32_bf16 v[120:123], v[156:159], v[190:193], v[120:123]
	v_mfma_f32_16x16x32_bf16 v[108:111], v[148:151], v[198:201], v[108:111]
	v_mfma_f32_16x16x32_bf16 v[104:107], v[156:159], v[198:201], v[104:107]
	v_mfma_f32_16x16x32_bf16 v[92:95], v[148:151], v[206:209], v[92:95]
	v_mfma_f32_16x16x32_bf16 v[88:91], v[156:159], v[206:209], v[88:91]
	v_mfma_f32_16x16x32_bf16 v[76:79], v[148:151], v[214:217], v[76:79]
	v_mfma_f32_16x16x32_bf16 v[72:75], v[156:159], v[214:217], v[72:75]
	v_mfma_f32_16x16x32_bf16 v[116:119], v[170:173], v[186:189], v[116:119]
	v_mfma_f32_16x16x32_bf16 v[112:115], v[178:181], v[186:189], v[112:115]
	v_mfma_f32_16x16x32_bf16 v[100:103], v[170:173], v[194:197], v[100:103]
	v_mfma_f32_16x16x32_bf16 v[96:99], v[178:181], v[194:197], v[96:99]
	v_mfma_f32_16x16x32_bf16 v[84:87], v[170:173], v[202:205], v[84:87]
	v_mfma_f32_16x16x32_bf16 v[80:83], v[178:181], v[202:205], v[80:83]
	v_mfma_f32_16x16x32_bf16 v[68:71], v[170:173], v[210:213], v[68:71]
	v_mfma_f32_16x16x32_bf16 v[64:67], v[178:181], v[210:213], v[64:67]
	v_mfma_f32_16x16x32_bf16 v[116:119], v[174:177], v[190:193], v[116:119]
	v_mfma_f32_16x16x32_bf16 v[112:115], v[182:185], v[190:193], v[112:115]
	v_mfma_f32_16x16x32_bf16 v[100:103], v[174:177], v[198:201], v[100:103]
	v_mfma_f32_16x16x32_bf16 v[96:99], v[182:185], v[198:201], v[96:99]
	v_mfma_f32_16x16x32_bf16 v[84:87], v[174:177], v[206:209], v[84:87]
	v_mfma_f32_16x16x32_bf16 v[80:83], v[182:185], v[206:209], v[80:83]
	v_mfma_f32_16x16x32_bf16 v[68:71], v[174:177], v[214:217], v[68:71]
	v_mfma_f32_16x16x32_bf16 v[64:67], v[182:185], v[214:217], v[64:67]
	s_barrier
	s_add_i32 s46, s46, s79
	s_mov_b32 m0, s46
	ds_read_b128 v[186:189], v147 offset:16384
	ds_read_b128 v[190:193], v147 offset:17408
	ds_read_b128 v[194:197], v147 offset:18432
	ds_read_b128 v[198:201], v147 offset:19456
	ds_read_b128 v[202:205], v147 offset:20480
	ds_read_b128 v[206:209], v147 offset:21504
	ds_read_b128 v[210:213], v147 offset:22528
	ds_read_b128 v[214:217], v147 offset:23552
	global_load_lds_dwordx4 v160, s[24:25]
	s_add_i32 m0, s46, 0x2000
	s_add_u32 s96, s24, 0x80000
	s_addc_u32 s97, s25, 0
	s_add_i32 s46, s47, s79
	global_load_lds_dwordx4 v132, s[24:25]
	s_mov_b32 m0, s46
	s_nop 0
	global_load_lds_dwordx4 v160, s[96:97]
	s_add_i32 m0, s46, 0x2000
	s_nop 0
	global_load_lds_dwordx4 v132, s[96:97]
	s_mov_b32 m0, s63
	s_nop 0
	global_load_lds_dwordx4 v128, s[82:83]
	s_mov_b32 m0, s67
	s_nop 0
	global_load_lds_dwordx4 v130, s[82:83]
	s_waitcnt vmcnt(8)
	s_waitcnt lgkmcnt(0)
	s_barrier
	v_mfma_f32_16x16x32_bf16 v[60:63], v[138:141], v[186:189], v[60:63]
	v_mfma_f32_16x16x32_bf16 v[56:59], v[152:155], v[186:189], v[56:59]
	v_mfma_f32_16x16x32_bf16 v[44:47], v[138:141], v[194:197], v[44:47]
	v_mfma_f32_16x16x32_bf16 v[40:43], v[152:155], v[194:197], v[40:43]
	v_mfma_f32_16x16x32_bf16 v[28:31], v[138:141], v[202:205], v[28:31]
	v_mfma_f32_16x16x32_bf16 v[24:27], v[152:155], v[202:205], v[24:27]
	v_mfma_f32_16x16x32_bf16 v[12:15], v[138:141], v[210:213], v[12:15]
	v_mfma_f32_16x16x32_bf16 v[8:11], v[152:155], v[210:213], v[8:11]
	v_mfma_f32_16x16x32_bf16 v[60:63], v[148:151], v[190:193], v[60:63]
	v_mfma_f32_16x16x32_bf16 v[56:59], v[156:159], v[190:193], v[56:59]
	v_mfma_f32_16x16x32_bf16 v[44:47], v[148:151], v[198:201], v[44:47]
	v_mfma_f32_16x16x32_bf16 v[40:43], v[156:159], v[198:201], v[40:43]
	v_mfma_f32_16x16x32_bf16 v[28:31], v[148:151], v[206:209], v[28:31]
	v_mfma_f32_16x16x32_bf16 v[24:27], v[156:159], v[206:209], v[24:27]
	v_mfma_f32_16x16x32_bf16 v[12:15], v[148:151], v[214:217], v[12:15]
	v_mfma_f32_16x16x32_bf16 v[8:11], v[156:159], v[214:217], v[8:11]
	v_mfma_f32_16x16x32_bf16 v[52:55], v[170:173], v[186:189], v[52:55]
	v_mfma_f32_16x16x32_bf16 v[48:51], v[178:181], v[186:189], v[48:51]
	v_mfma_f32_16x16x32_bf16 v[36:39], v[170:173], v[194:197], v[36:39]
	v_mfma_f32_16x16x32_bf16 v[32:35], v[178:181], v[194:197], v[32:35]
	v_mfma_f32_16x16x32_bf16 v[20:23], v[170:173], v[202:205], v[20:23]
	v_mfma_f32_16x16x32_bf16 v[16:19], v[178:181], v[202:205], v[16:19]
	v_mfma_f32_16x16x32_bf16 v[4:7], v[170:173], v[210:213], v[4:7]
	v_mfma_f32_16x16x32_bf16 v[0:3], v[178:181], v[210:213], v[0:3]
	v_mfma_f32_16x16x32_bf16 v[52:55], v[174:177], v[190:193], v[52:55]
	v_mfma_f32_16x16x32_bf16 v[48:51], v[182:185], v[190:193], v[48:51]
	v_mfma_f32_16x16x32_bf16 v[36:39], v[174:177], v[198:201], v[36:39]
	v_mfma_f32_16x16x32_bf16 v[32:35], v[182:185], v[198:201], v[32:35]
	v_mfma_f32_16x16x32_bf16 v[20:23], v[174:177], v[206:209], v[20:23]
	v_mfma_f32_16x16x32_bf16 v[16:19], v[182:185], v[206:209], v[16:19]
	v_mfma_f32_16x16x32_bf16 v[4:7], v[174:177], v[214:217], v[4:7]
	v_mfma_f32_16x16x32_bf16 v[0:3], v[182:185], v[214:217], v[0:3]
	s_barrier
; #define PG8_STAGE(bufoff, gbase, voff) do { _Pragma("unroll") for (int _i = 0; _i < 2; ++_i) \
;         __builtin_amdgcn_global_load_lds((const unsigned*)((const char*)(gbase) + (voff)[_i]), (LAS unsigned*)(lds + (bufoff) + ldsw + _i * 8192), 16, 0, 0); } while (0)
; #define PG8_LDA(dst, b, h) do { _Pragma("unroll") for (int m = 0; m < 4; ++m) _Pragma("unroll") for (int k = 0; k < 2; ++k) dst[m][k] = *(const LAS bf16x8*)(lds + PG8_SA(b, h) + aoff + m * 2048 + k * 1024); } while (0)
; #define PG8_LDB(dst, b, h) do { _Pragma("unroll") for (int n = 0; n < 2; ++n) _Pragma("unroll") for (int k = 0; k < 2; ++k) dst[n][k] = *(const LAS bf16x8*)(lds + PG8_SB(b, h) + boff + n * 2048 + k * 1024); } while (0)
; #define PG8_MMA(ai, bj, At, Bt) do { __builtin_amdgcn_s_setprio(1); _Pragma("unroll") for (int m = 0; m < 4; ++m) _Pragma("unroll") for (int n = 0; n < 2; ++n) _Pragma("unroll") for (int k = 0; k < 2; ++k) \
;         acc[ai][bj][m][n] = __builtin_amdgcn_mfma_f32_16x16x32_bf16(Bt[n][k], At[m][k], acc[ai][bj][m][n], 0, 0, 0); __builtin_amdgcn_s_setprio(0); } while (0)
; #define PG8_WAIT_V(n) asm volatile("s_waitcnt vmcnt(" #n ")" ::: "memory")
; #define PG8_WAIT_L(n) asm volatile("s_waitcnt lgkmcnt(" #n ")" ::: "memory")
; #define PG8_BAR __builtin_amdgcn_s_barrier()
; #define PG8_SCHED __builtin_amdgcn_sched_barrier(0)
; template <class Epi, class Sched, bool ALIGN_EPI = true, bool SP2 = true>
; __device__ __forceinline__ void gemm_phase(LAS unsigned char* lds, const Gemm g, const Sched& S, const Epi& E) {
;     ...
;             PG8_LDB(B0, 1, 0); PG8_LDB(B1, 1, 1); PG8_SCHED; PG8_LDA(At, 1, 0); PG8_STAGE(PG8_SA(0, 1), a2 + hstep, voffA);
;             PG8_WAIT_V(8); PG8_WAIT_L(0); PG8_BAR; PG8_MMA(0, 0, At, B0); PG8_MMA(0, 1, At, B1); PG8_BAR; PG8_SCHED;
;             PG8_LDA(At, 1, 1); PG8_STAGE(PG8_SB(1, 0), b3, voffB); PG8_STAGE(PG8_SB(1, 1), b3 + hstep, voffB); PG8_STAGE(PG8_SA(1, 0), a3, voffA);
;             PG8_WAIT_V(8); PG8_WAIT_L(0); PG8_BAR; PG8_MMA(1, 0, At, B0); PG8_MMA(1, 1, At, B1); PG8_BAR; PG8_SCHED;
;     ...
;         if constexpr (ALIGN_EPI) { if (wr == 0) PG8_BAR; }
	s_add_i32 s46, 0, 0x18000
	s_add_i32 s47, 0, 0x1c000
	v_add_u32_e32 v156, s46, v145
	v_add_u32_e32 v182, s47, v145
	ds_read_b128 v[138:141], v156
	ds_read_b128 v[148:151], v156 offset:1024
	ds_read_b128 v[152:155], v156 offset:2048
	ds_read_b128 v[156:159], v156 offset:3072
	ds_read_b128 v[170:173], v182
	ds_read_b128 v[174:177], v182 offset:1024
	ds_read_b128 v[178:181], v182 offset:2048
	ds_read_b128 v[182:185], v182 offset:3072
	s_add_u32 s82, s82, 0x80000
	s_addc_u32 s83, s83, 0
	s_mov_b32 m0, s90
	ds_read_b128 v[186:189], v147 offset:32768
	ds_read_b128 v[190:193], v147 offset:33792
	ds_read_b128 v[194:197], v147 offset:34816
	ds_read_b128 v[198:201], v147 offset:35840
	ds_read_b128 v[202:205], v147 offset:36864
	ds_read_b128 v[206:209], v147 offset:37888
	ds_read_b128 v[210:213], v147 offset:38912
	ds_read_b128 v[214:217], v147 offset:39936
	global_load_lds_dwordx4 v128, s[82:83]
	s_mov_b32 m0, s91
	s_nop 0
	global_load_lds_dwordx4 v130, s[82:83]
	s_waitcnt vmcnt(8)
	s_waitcnt lgkmcnt(0)
	s_barrier
	v_mfma_f32_16x16x32_bf16 v[124:127], v[138:141], v[186:189], v[124:127]
	v_mfma_f32_16x16x32_bf16 v[120:123], v[152:155], v[186:189], v[120:123]
	v_mfma_f32_16x16x32_bf16 v[108:111], v[138:141], v[194:197], v[108:111]
	v_mfma_f32_16x16x32_bf16 v[104:107], v[152:155], v[194:197], v[104:107]
	v_mfma_f32_16x16x32_bf16 v[92:95], v[138:141], v[202:205], v[92:95]
	v_mfma_f32_16x16x32_bf16 v[88:91], v[152:155], v[202:205], v[88:91]
	v_mfma_f32_16x16x32_bf16 v[76:79], v[138:141], v[210:213], v[76:79]
	v_mfma_f32_16x16x32_bf16 v[72:75], v[152:155], v[210:213], v[72:75]
	v_mfma_f32_16x16x32_bf16 v[124:127], v[148:151], v[190:193], v[124:127]
	v_mfma_f32_16x16x32_bf16 v[120:123], v[156:159], v[190:193], v[120:123]
	v_mfma_f32_16x16x32_bf16 v[108:111], v[148:151], v[198:201], v[108:111]
	v_mfma_f32_16x16x32_bf16 v[104:107], v[156:159], v[198:201], v[104:107]
	v_mfma_f32_16x16x32_bf16 v[92:95], v[148:151], v[206:209], v[92:95]
	v_mfma_f32_16x16x32_bf16 v[88:91], v[156:159], v[206:209], v[88:91]
	v_mfma_f32_16x16x32_bf16 v[76:79], v[148:151], v[214:217], v[76:79]
	v_mfma_f32_16x16x32_bf16 v[72:75], v[156:159], v[214:217], v[72:75]
	v_mfma_f32_16x16x32_bf16 v[116:119], v[170:173], v[186:189], v[116:119]
	v_mfma_f32_16x16x32_bf16 v[112:115], v[178:181], v[186:189], v[112:115]
	v_mfma_f32_16x16x32_bf16 v[100:103], v[170:173], v[194:197], v[100:103]
	v_mfma_f32_16x16x32_bf16 v[96:99], v[178:181], v[194:197], v[96:99]
	v_mfma_f32_16x16x32_bf16 v[84:87], v[170:173], v[202:205], v[84:87]
	v_mfma_f32_16x16x32_bf16 v[80:83], v[178:181], v[202:205], v[80:83]
	v_mfma_f32_16x16x32_bf16 v[68:71], v[170:173], v[210:213], v[68:71]
	v_mfma_f32_16x16x32_bf16 v[64:67], v[178:181], v[210:213], v[64:67]
	v_mfma_f32_16x16x32_bf16 v[116:119], v[174:177], v[190:193], v[116:119]
	v_mfma_f32_16x16x32_bf16 v[112:115], v[182:185], v[190:193], v[112:115]
	v_mfma_f32_16x16x32_bf16 v[100:103], v[174:177], v[198:201], v[100:103]
	v_mfma_f32_16x16x32_bf16 v[96:99], v[182:185], v[198:201], v[96:99]
	v_mfma_f32_16x16x32_bf16 v[84:87], v[174:177], v[206:209], v[84:87]
	v_mfma_f32_16x16x32_bf16 v[80:83], v[182:185], v[206:209], v[80:83]
	v_mfma_f32_16x16x32_bf16 v[68:71], v[174:177], v[214:217], v[68:71]
	v_mfma_f32_16x16x32_bf16 v[64:67], v[182:185], v[214:217], v[64:67]
	s_barrier
	s_add_i32 s46, s46, s79
	s_mov_b32 m0, s46
	ds_read_b128 v[186:189], v147 offset:49152
	ds_read_b128 v[190:193], v147 offset:50176
	ds_read_b128 v[194:197], v147 offset:51200
	ds_read_b128 v[198:201], v147 offset:52224
	ds_read_b128 v[202:205], v147 offset:53248
	ds_read_b128 v[206:209], v147 offset:54272
	ds_read_b128 v[210:213], v147 offset:55296
	ds_read_b128 v[214:217], v147 offset:56320
	s_add_u32 s98, s24, 0x80
	s_addc_u32 s99, s25, 0
	global_load_lds_dwordx4 v160, s[98:99]
	s_add_i32 m0, s46, 0x2000
	s_add_u32 s24, s24, 0x80080
	s_addc_u32 s25, s25, 0
	s_add_i32 s46, s47, s79
	global_load_lds_dwordx4 v132, s[98:99]
	s_mov_b32 m0, s46
	s_nop 0
	global_load_lds_dwordx4 v160, s[24:25]
	s_add_i32 m0, s46, 0x2000
	s_nop 0
	global_load_lds_dwordx4 v132, s[24:25]
	s_mov_b32 m0, s92
	s_nop 0
	s_add_u32 s98, s82, 0xfff80080
	s_addc_u32 s99, s83, -1
	global_load_lds_dwordx4 v128, s[98:99]
	s_mov_b32 m0, s93
	s_nop 0
	global_load_lds_dwordx4 v130, s[98:99]
	s_waitcnt vmcnt(8)
	s_waitcnt lgkmcnt(0)
	s_barrier
	v_mfma_f32_16x16x32_bf16 v[60:63], v[138:141], v[186:189], v[60:63]
	v_mfma_f32_16x16x32_bf16 v[56:59], v[152:155], v[186:189], v[56:59]
	v_mfma_f32_16x16x32_bf16 v[44:47], v[138:141], v[194:197], v[44:47]
	v_mfma_f32_16x16x32_bf16 v[40:43], v[152:155], v[194:197], v[40:43]
	v_mfma_f32_16x16x32_bf16 v[28:31], v[138:141], v[202:205], v[28:31]
	v_mfma_f32_16x16x32_bf16 v[24:27], v[152:155], v[202:205], v[24:27]
	v_mfma_f32_16x16x32_bf16 v[12:15], v[138:141], v[210:213], v[12:15]
	v_mfma_f32_16x16x32_bf16 v[8:11], v[152:155], v[210:213], v[8:11]
	v_mfma_f32_16x16x32_bf16 v[60:63], v[148:151], v[190:193], v[60:63]
	v_mfma_f32_16x16x32_bf16 v[56:59], v[156:159], v[190:193], v[56:59]
	v_mfma_f32_16x16x32_bf16 v[44:47], v[148:151], v[198:201], v[44:47]
	v_mfma_f32_16x16x32_bf16 v[40:43], v[156:159], v[198:201], v[40:43]
	v_mfma_f32_16x16x32_bf16 v[28:31], v[148:151], v[206:209], v[28:31]
	v_mfma_f32_16x16x32_bf16 v[24:27], v[156:159], v[206:209], v[24:27]
	v_mfma_f32_16x16x32_bf16 v[12:15], v[148:151], v[214:217], v[12:15]
	v_mfma_f32_16x16x32_bf16 v[8:11], v[156:159], v[214:217], v[8:11]
	v_mfma_f32_16x16x32_bf16 v[52:55], v[170:173], v[186:189], v[52:55]
	v_mfma_f32_16x16x32_bf16 v[48:51], v[178:181], v[186:189], v[48:51]
	v_mfma_f32_16x16x32_bf16 v[36:39], v[170:173], v[194:197], v[36:39]
	v_mfma_f32_16x16x32_bf16 v[32:35], v[178:181], v[194:197], v[32:35]
	v_mfma_f32_16x16x32_bf16 v[20:23], v[170:173], v[202:205], v[20:23]
	v_mfma_f32_16x16x32_bf16 v[16:19], v[178:181], v[202:205], v[16:19]
	v_mfma_f32_16x16x32_bf16 v[4:7], v[170:173], v[210:213], v[4:7]
	v_mfma_f32_16x16x32_bf16 v[0:3], v[178:181], v[210:213], v[0:3]
	v_mfma_f32_16x16x32_bf16 v[52:55], v[174:177], v[190:193], v[52:55]
	v_mfma_f32_16x16x32_bf16 v[48:51], v[182:185], v[190:193], v[48:51]
	v_mfma_f32_16x16x32_bf16 v[36:39], v[174:177], v[198:201], v[36:39]
	v_mfma_f32_16x16x32_bf16 v[32:35], v[182:185], v[198:201], v[32:35]
	v_mfma_f32_16x16x32_bf16 v[20:23], v[174:177], v[206:209], v[20:23]
	v_mfma_f32_16x16x32_bf16 v[16:19], v[182:185], v[206:209], v[16:19]
	v_mfma_f32_16x16x32_bf16 v[4:7], v[174:177], v[214:217], v[4:7]
	v_mfma_f32_16x16x32_bf16 v[0:3], v[182:185], v[214:217], v[0:3]
	s_barrier
	s_add_i32 s95, s95, 2
	s_add_u32 s72, s72, 0x100
	s_addc_u32 s73, s73, 0
	s_add_u32 s45, s45, 0x100
	s_addc_u32 s53, s53, 0
	s_cmp_gt_u32 s95, 29
	s_cbranch_scc0 .LBB0_145
	s_setprio 0
	s_and_b64 vcc, exec, s[18:19]
	s_cbranch_vccz .LBB0_148
	s_barrier

; #define PG8_STAGE(bufoff, gbase, voff) do { _Pragma("unroll") for (int _i = 0; _i < 2; ++_i) \
;         __builtin_amdgcn_global_load_lds((const unsigned*)((const char*)(gbase) + (voff)[_i]), (LAS unsigned*)(lds + (bufoff) + ldsw + _i * 8192), 16, 0, 0); } while (0)
; #define PG8_LDA(dst, b, h) do { _Pragma("unroll") for (int m = 0; m < 4; ++m) _Pragma("unroll") for (int k = 0; k < 2; ++k) dst[m][k] = *(const LAS bf16x8*)(lds + PG8_SA(b, h) + aoff + m * 2048 + k * 1024); } while (0)
; #define PG8_LDB(dst, b, h) do { _Pragma("unroll") for (int n = 0; n < 2; ++n) _Pragma("unroll") for (int k = 0; k < 2; ++k) dst[n][k] = *(const LAS bf16x8*)(lds + PG8_SB(b, h) + boff + n * 2048 + k * 1024); } while (0)
; #define PG8_MMA(ai, bj, At, Bt) do { __builtin_amdgcn_s_setprio(1); _Pragma("unroll") for (int m = 0; m < 4; ++m) _Pragma("unroll") for (int n = 0; n < 2; ++n) _Pragma("unroll") for (int k = 0; k < 2; ++k) \
;         acc[ai][bj][m][n] = __builtin_amdgcn_mfma_f32_16x16x32_bf16(Bt[n][k], At[m][k], acc[ai][bj][m][n], 0, 0, 0); __builtin_amdgcn_s_setprio(0); } while (0)
; #define PG8_WAIT_V(n) asm volatile("s_waitcnt vmcnt(" #n ")" ::: "memory")
; #define PG8_WAIT_L(n) asm volatile("s_waitcnt lgkmcnt(" #n ")" ::: "memory")
; #define PG8_BAR __builtin_amdgcn_s_barrier()
; #define PG8_SCHED __builtin_amdgcn_sched_barrier(0)
; template <class Epi, class Sched, bool ALIGN_EPI = true, bool SP2 = true>
; __device__ __forceinline__ void gemm_phase(LAS unsigned char* lds, const Gemm g, const Sched& S, const Epi& E) {
;     ...
;             const char* a1 = cA + (size_t)(t + 1) * kstep;
;             const char* a2 = last ? nA : cA + (size_t)(t + 2) * kstep; const char* b2 = last ? nB : cB + (size_t)(t + 2) * kstep;
;             const char* a3 = a2 + kstep; const char* b3 = b2 + kstep;
;             if constexpr (SP2) {
;             PG8_LDB(B0, 0, 0); PG8_LDB(B1, 0, 1); PG8_SCHED; PG8_LDA(At, 0, 0); PG8_STAGE(PG8_SA(1, 1), a1 + hstep, voffA);
;             PG8_WAIT_V(8); PG8_WAIT_L(0); PG8_BAR; PG8_MMA(0, 0, At, B0); PG8_MMA(0, 1, At, B1); PG8_BAR; PG8_SCHED;
;             PG8_LDA(At, 0, 1); PG8_STAGE(PG8_SB(0, 0), b2, voffB); PG8_STAGE(PG8_SB(0, 1), b2 + hstep, voffB); PG8_STAGE(PG8_SA(0, 0), a2, voffA);
;             PG8_WAIT_V(8); PG8_WAIT_L(0); PG8_BAR; PG8_MMA(1, 0, At, B0); PG8_MMA(1, 1, At, B1); PG8_BAR; PG8_SCHED;
.Lprio_skip_187:
.LBB0_187:
	s_add_u32 s24, s66, 0xfffc0080
	s_addc_u32 s25, s67, -1
	s_add_i32 s46, 0, 0x10000
	s_cmp_eq_u32 s53, 12
	s_cselect_b32 s73, s2, s25
	s_cselect_b32 s72, s3, s24
	s_cselect_b32 s25, s31, s45
	s_cselect_b32 s24, s43, s44
	s_add_i32 s47, 0, 0x14000
	v_add_u32_e32 v154, s46, v147
	v_add_u32_e32 v158, s47, v147
	ds_read_b128 v[138:141], v154
	ds_read_b128 v[142:145], v154 offset:1024
	ds_read_b128 v[150:153], v154 offset:2048
	ds_read_b128 v[154:157], v154 offset:3072
	ds_read_b128 v[170:173], v158
	ds_read_b128 v[174:177], v158 offset:1024
	ds_read_b128 v[178:181], v158 offset:2048
	ds_read_b128 v[182:185], v158 offset:3072
	s_add_i32 m0, s63, 0xc000
	ds_read_b128 v[186:189], v149
	ds_read_b128 v[190:193], v149 offset:1024
	ds_read_b128 v[194:197], v149 offset:2048
	ds_read_b128 v[198:201], v149 offset:3072
	ds_read_b128 v[202:205], v149 offset:4096
	ds_read_b128 v[206:209], v149 offset:5120
	ds_read_b128 v[210:213], v149 offset:6144
	ds_read_b128 v[214:217], v149 offset:7168
	global_load_lds_dwordx4 v134, s[66:67]
	s_add_i32 m0, s63, 0xe000
	s_nop 0
	global_load_lds_dwordx4 v136, s[66:67]
	s_waitcnt vmcnt(8)
	s_waitcnt lgkmcnt(0)
	s_barrier
	v_mfma_f32_16x16x32_bf16 v[124:127], v[138:141], v[186:189], v[124:127]
	v_mfma_f32_16x16x32_bf16 v[120:123], v[150:153], v[186:189], v[120:123]
	v_mfma_f32_16x16x32_bf16 v[108:111], v[138:141], v[194:197], v[108:111]
	v_mfma_f32_16x16x32_bf16 v[104:107], v[150:153], v[194:197], v[104:107]
	v_mfma_f32_16x16x32_bf16 v[92:95], v[138:141], v[202:205], v[92:95]
	v_mfma_f32_16x16x32_bf16 v[88:91], v[150:153], v[202:205], v[88:91]
	v_mfma_f32_16x16x32_bf16 v[76:79], v[138:141], v[210:213], v[76:79]
	v_mfma_f32_16x16x32_bf16 v[72:75], v[150:153], v[210:213], v[72:75]
	v_mfma_f32_16x16x32_bf16 v[124:127], v[142:145], v[190:193], v[124:127]
	v_mfma_f32_16x16x32_bf16 v[120:123], v[154:157], v[190:193], v[120:123]
	v_mfma_f32_16x16x32_bf16 v[108:111], v[142:145], v[198:201], v[108:111]
	v_mfma_f32_16x16x32_bf16 v[104:107], v[154:157], v[198:201], v[104:107]
	v_mfma_f32_16x16x32_bf16 v[92:95], v[142:145], v[206:209], v[92:95]
	v_mfma_f32_16x16x32_bf16 v[88:91], v[154:157], v[206:209], v[88:91]
	v_mfma_f32_16x16x32_bf16 v[76:79], v[142:145], v[214:217], v[76:79]
	v_mfma_f32_16x16x32_bf16 v[72:75], v[154:157], v[214:217], v[72:75]
	v_mfma_f32_16x16x32_bf16 v[116:119], v[170:173], v[186:189], v[116:119]
	v_mfma_f32_16x16x32_bf16 v[112:115], v[178:181], v[186:189], v[112:115]
	v_mfma_f32_16x16x32_bf16 v[100:103], v[170:173], v[194:197], v[100:103]
	v_mfma_f32_16x16x32_bf16 v[96:99], v[178:181], v[194:197], v[96:99]
	v_mfma_f32_16x16x32_bf16 v[84:87], v[170:173], v[202:205], v[84:87]
	v_mfma_f32_16x16x32_bf16 v[80:83], v[178:181], v[202:205], v[80:83]
	v_mfma_f32_16x16x32_bf16 v[68:71], v[170:173], v[210:213], v[68:71]
	v_mfma_f32_16x16x32_bf16 v[64:67], v[178:181], v[210:213], v[64:67]
	v_mfma_f32_16x16x32_bf16 v[116:119], v[174:177], v[190:193], v[116:119]
	v_mfma_f32_16x16x32_bf16 v[112:115], v[182:185], v[190:193], v[112:115]
	v_mfma_f32_16x16x32_bf16 v[100:103], v[174:177], v[198:201], v[100:103]
	v_mfma_f32_16x16x32_bf16 v[96:99], v[182:185], v[198:201], v[96:99]
	v_mfma_f32_16x16x32_bf16 v[84:87], v[174:177], v[206:209], v[84:87]
	v_mfma_f32_16x16x32_bf16 v[80:83], v[182:185], v[206:209], v[80:83]
	v_mfma_f32_16x16x32_bf16 v[68:71], v[174:177], v[214:217], v[68:71]
	v_mfma_f32_16x16x32_bf16 v[64:67], v[182:185], v[214:217], v[64:67]
	s_barrier
	s_add_i32 s46, s46, s90
	s_mov_b32 m0, s46
	ds_read_b128 v[186:189], v149 offset:16384
	ds_read_b128 v[190:193], v149 offset:17408
	ds_read_b128 v[194:197], v149 offset:18432
	ds_read_b128 v[198:201], v149 offset:19456
	ds_read_b128 v[202:205], v149 offset:20480
	ds_read_b128 v[206:209], v149 offset:21504
	ds_read_b128 v[210:213], v149 offset:22528
	ds_read_b128 v[214:217], v149 offset:23552
	global_load_lds_dwordx4 v160, s[24:25]
	s_add_i32 m0, s46, 0x2000
	s_add_u32 vcc_lo, s24, 0x40000
	s_addc_u32 vcc_hi, s25, 0
	s_add_i32 s46, s47, s90
	global_load_lds_dwordx4 v132, s[24:25]
	v_lshl_add_u64 v[218:219], vcc, 0, v[160:161]
	s_mov_b32 m0, s46
	s_nop 0
	global_load_lds_dwordx4 v[218:219], off
	v_lshl_add_u64 v[218:219], vcc, 0, v[132:133]
	s_add_i32 m0, s46, 0x2000
	s_nop 0
	global_load_lds_dwordx4 v[218:219], off
	s_mov_b32 m0, s63
	s_nop 0
	global_load_lds_dwordx4 v128, s[72:73]
	s_mov_b32 m0, s91
	s_nop 0
	global_load_lds_dwordx4 v130, s[72:73]
	s_waitcnt vmcnt(8)
	s_waitcnt lgkmcnt(0)
	s_barrier
	v_mfma_f32_16x16x32_bf16 v[60:63], v[138:141], v[186:189], v[60:63]
	v_mfma_f32_16x16x32_bf16 v[56:59], v[150:153], v[186:189], v[56:59]
	v_mfma_f32_16x16x32_bf16 v[44:47], v[138:141], v[194:197], v[44:47]
	v_mfma_f32_16x16x32_bf16 v[40:43], v[150:153], v[194:197], v[40:43]
	v_mfma_f32_16x16x32_bf16 v[28:31], v[138:141], v[202:205], v[28:31]
	v_mfma_f32_16x16x32_bf16 v[24:27], v[150:153], v[202:205], v[24:27]
	v_mfma_f32_16x16x32_bf16 v[12:15], v[138:141], v[210:213], v[12:15]
	v_mfma_f32_16x16x32_bf16 v[8:11], v[150:153], v[210:213], v[8:11]
	v_mfma_f32_16x16x32_bf16 v[60:63], v[142:145], v[190:193], v[60:63]
	v_mfma_f32_16x16x32_bf16 v[56:59], v[154:157], v[190:193], v[56:59]
	v_mfma_f32_16x16x32_bf16 v[44:47], v[142:145], v[198:201], v[44:47]
	v_mfma_f32_16x16x32_bf16 v[40:43], v[154:157], v[198:201], v[40:43]
	v_mfma_f32_16x16x32_bf16 v[28:31], v[142:145], v[206:209], v[28:31]
	v_mfma_f32_16x16x32_bf16 v[24:27], v[154:157], v[206:209], v[24:27]
	v_mfma_f32_16x16x32_bf16 v[12:15], v[142:145], v[214:217], v[12:15]
	v_mfma_f32_16x16x32_bf16 v[8:11], v[154:157], v[214:217], v[8:11]
	v_mfma_f32_16x16x32_bf16 v[52:55], v[170:173], v[186:189], v[52:55]
	v_mfma_f32_16x16x32_bf16 v[48:51], v[178:181], v[186:189], v[48:51]
	v_mfma_f32_16x16x32_bf16 v[36:39], v[170:173], v[194:197], v[36:39]
	v_mfma_f32_16x16x32_bf16 v[32:35], v[178:181], v[194:197], v[32:35]
	v_mfma_f32_16x16x32_bf16 v[20:23], v[170:173], v[202:205], v[20:23]
	v_mfma_f32_16x16x32_bf16 v[16:19], v[178:181], v[202:205], v[16:19]
	v_mfma_f32_16x16x32_bf16 v[4:7], v[170:173], v[210:213], v[4:7]
	v_mfma_f32_16x16x32_bf16 v[0:3], v[178:181], v[210:213], v[0:3]
	v_mfma_f32_16x16x32_bf16 v[52:55], v[174:177], v[190:193], v[52:55]
	v_mfma_f32_16x16x32_bf16 v[48:51], v[182:185], v[190:193], v[48:51]
	v_mfma_f32_16x16x32_bf16 v[36:39], v[174:177], v[198:201], v[36:39]
	v_mfma_f32_16x16x32_bf16 v[32:35], v[182:185], v[198:201], v[32:35]
	v_mfma_f32_16x16x32_bf16 v[20:23], v[174:177], v[206:209], v[20:23]
	v_mfma_f32_16x16x32_bf16 v[16:19], v[182:185], v[206:209], v[16:19]
	v_mfma_f32_16x16x32_bf16 v[4:7], v[174:177], v[214:217], v[4:7]
	v_mfma_f32_16x16x32_bf16 v[0:3], v[182:185], v[214:217], v[0:3]
	s_barrier
; #define PG8_STAGE(bufoff, gbase, voff) do { _Pragma("unroll") for (int _i = 0; _i < 2; ++_i) \
;         __builtin_amdgcn_global_load_lds((const unsigned*)((const char*)(gbase) + (voff)[_i]), (LAS unsigned*)(lds + (bufoff) + ldsw + _i * 8192), 16, 0, 0); } while (0)
; #define PG8_LDA(dst, b, h) do { _Pragma("unroll") for (int m = 0; m < 4; ++m) _Pragma("unroll") for (int k = 0; k < 2; ++k) dst[m][k] = *(const LAS bf16x8*)(lds + PG8_SA(b, h) + aoff + m * 2048 + k * 1024); } while (0)
; #define PG8_LDB(dst, b, h) do { _Pragma("unroll") for (int n = 0; n < 2; ++n) _Pragma("unroll") for (int k = 0; k < 2; ++k) dst[n][k] = *(const LAS bf16x8*)(lds + PG8_SB(b, h) + boff + n * 2048 + k * 1024); } while (0)
; #define PG8_MMA(ai, bj, At, Bt) do { __builtin_amdgcn_s_setprio(1); _Pragma("unroll") for (int m = 0; m < 4; ++m) _Pragma("unroll") for (int n = 0; n < 2; ++n) _Pragma("unroll") for (int k = 0; k < 2; ++k) \
;         acc[ai][bj][m][n] = __builtin_amdgcn_mfma_f32_16x16x32_bf16(Bt[n][k], At[m][k], acc[ai][bj][m][n], 0, 0, 0); __builtin_amdgcn_s_setprio(0); } while (0)
; #define PG8_WAIT_V(n) asm volatile("s_waitcnt vmcnt(" #n ")" ::: "memory")
; #define PG8_WAIT_L(n) asm volatile("s_waitcnt lgkmcnt(" #n ")" ::: "memory")
; #define PG8_BAR __builtin_amdgcn_s_barrier()
; #define PG8_SCHED __builtin_amdgcn_sched_barrier(0)
; template <class Epi, class Sched, bool ALIGN_EPI = true, bool SP2 = true>
; __device__ __forceinline__ void gemm_phase(LAS unsigned char* lds, const Gemm g, const Sched& S, const Epi& E) {
;     ...
;             PG8_LDB(B0, 1, 0); PG8_LDB(B1, 1, 1); PG8_SCHED; PG8_LDA(At, 1, 0); PG8_STAGE(PG8_SA(0, 1), a2 + hstep, voffA);
;             PG8_WAIT_V(8); PG8_WAIT_L(0); PG8_BAR; PG8_MMA(0, 0, At, B0); PG8_MMA(0, 1, At, B1); PG8_BAR; PG8_SCHED;
;             PG8_LDA(At, 1, 1); PG8_STAGE(PG8_SB(1, 0), b3, voffB); PG8_STAGE(PG8_SB(1, 1), b3 + hstep, voffB); PG8_STAGE(PG8_SA(1, 0), a3, voffA);
;             PG8_WAIT_V(8); PG8_WAIT_L(0); PG8_BAR; PG8_MMA(1, 0, At, B0); PG8_MMA(1, 1, At, B1); PG8_BAR; PG8_SCHED;
;     ...
;         if constexpr (ALIGN_EPI) { if (wr == 0) PG8_BAR; }
	s_add_i32 s46, 0, 0x18000
	s_add_i32 s47, 0, 0x1c000
	v_add_u32_e32 v154, s46, v147
	v_add_u32_e32 v182, s47, v147
	ds_read_b128 v[138:141], v154
	ds_read_b128 v[142:145], v154 offset:1024
	ds_read_b128 v[150:153], v154 offset:2048
	ds_read_b128 v[154:157], v154 offset:3072
	ds_read_b128 v[170:173], v182
	ds_read_b128 v[174:177], v182 offset:1024
	ds_read_b128 v[178:181], v182 offset:2048
	ds_read_b128 v[182:185], v182 offset:3072
	s_add_u32 s72, s72, 0x40000
	s_addc_u32 s73, s73, 0
	s_mov_b32 m0, s92
	ds_read_b128 v[186:189], v149 offset:32768
	ds_read_b128 v[190:193], v149 offset:33792
	ds_read_b128 v[194:197], v149 offset:34816
	ds_read_b128 v[198:201], v149 offset:35840
	ds_read_b128 v[202:205], v149 offset:36864
	ds_read_b128 v[206:209], v149 offset:37888
	ds_read_b128 v[210:213], v149 offset:38912
	ds_read_b128 v[214:217], v149 offset:39936
	global_load_lds_dwordx4 v128, s[72:73]
	s_mov_b32 m0, s93
	s_nop 0
	global_load_lds_dwordx4 v130, s[72:73]
	s_waitcnt vmcnt(8)
	s_waitcnt lgkmcnt(0)
	s_barrier
	v_mfma_f32_16x16x32_bf16 v[124:127], v[138:141], v[186:189], v[124:127]
	v_mfma_f32_16x16x32_bf16 v[120:123], v[150:153], v[186:189], v[120:123]
	v_mfma_f32_16x16x32_bf16 v[108:111], v[138:141], v[194:197], v[108:111]
	v_mfma_f32_16x16x32_bf16 v[104:107], v[150:153], v[194:197], v[104:107]
	v_mfma_f32_16x16x32_bf16 v[92:95], v[138:141], v[202:205], v[92:95]
	v_mfma_f32_16x16x32_bf16 v[88:91], v[150:153], v[202:205], v[88:91]
	v_mfma_f32_16x16x32_bf16 v[76:79], v[138:141], v[210:213], v[76:79]
	v_mfma_f32_16x16x32_bf16 v[72:75], v[150:153], v[210:213], v[72:75]
	v_mfma_f32_16x16x32_bf16 v[124:127], v[142:145], v[190:193], v[124:127]
	v_mfma_f32_16x16x32_bf16 v[120:123], v[154:157], v[190:193], v[120:123]
	v_mfma_f32_16x16x32_bf16 v[108:111], v[142:145], v[198:201], v[108:111]
	v_mfma_f32_16x16x32_bf16 v[104:107], v[154:157], v[198:201], v[104:107]
	v_mfma_f32_16x16x32_bf16 v[92:95], v[142:145], v[206:209], v[92:95]
	v_mfma_f32_16x16x32_bf16 v[88:91], v[154:157], v[206:209], v[88:91]
	v_mfma_f32_16x16x32_bf16 v[76:79], v[142:145], v[214:217], v[76:79]
	v_mfma_f32_16x16x32_bf16 v[72:75], v[154:157], v[214:217], v[72:75]
	v_mfma_f32_16x16x32_bf16 v[116:119], v[170:173], v[186:189], v[116:119]
	v_mfma_f32_16x16x32_bf16 v[112:115], v[178:181], v[186:189], v[112:115]
	v_mfma_f32_16x16x32_bf16 v[100:103], v[170:173], v[194:197], v[100:103]
	v_mfma_f32_16x16x32_bf16 v[96:99], v[178:181], v[194:197], v[96:99]
	v_mfma_f32_16x16x32_bf16 v[84:87], v[170:173], v[202:205], v[84:87]
	v_mfma_f32_16x16x32_bf16 v[80:83], v[178:181], v[202:205], v[80:83]
	v_mfma_f32_16x16x32_bf16 v[68:71], v[170:173], v[210:213], v[68:71]
	v_mfma_f32_16x16x32_bf16 v[64:67], v[178:181], v[210:213], v[64:67]
	v_mfma_f32_16x16x32_bf16 v[116:119], v[174:177], v[190:193], v[116:119]
	v_mfma_f32_16x16x32_bf16 v[112:115], v[182:185], v[190:193], v[112:115]
	v_mfma_f32_16x16x32_bf16 v[100:103], v[174:177], v[198:201], v[100:103]
	v_mfma_f32_16x16x32_bf16 v[96:99], v[182:185], v[198:201], v[96:99]
	v_mfma_f32_16x16x32_bf16 v[84:87], v[174:177], v[206:209], v[84:87]
	v_mfma_f32_16x16x32_bf16 v[80:83], v[182:185], v[206:209], v[80:83]
	v_mfma_f32_16x16x32_bf16 v[68:71], v[174:177], v[214:217], v[68:71]
	v_mfma_f32_16x16x32_bf16 v[64:67], v[182:185], v[214:217], v[64:67]
	s_barrier
	s_add_i32 s46, s46, s90
	s_mov_b32 m0, s46
	ds_read_b128 v[186:189], v149 offset:49152
	ds_read_b128 v[190:193], v149 offset:50176
	ds_read_b128 v[194:197], v149 offset:51200
	ds_read_b128 v[198:201], v149 offset:52224
	ds_read_b128 v[202:205], v149 offset:53248
	ds_read_b128 v[206:209], v149 offset:54272
	ds_read_b128 v[210:213], v149 offset:55296
	ds_read_b128 v[214:217], v149 offset:56320
	s_add_u32 s98, s24, 0x80
	s_addc_u32 s99, s25, 0
	global_load_lds_dwordx4 v160, s[98:99]
	s_add_i32 m0, s46, 0x2000
	s_add_u32 s24, s24, 0x40080
	s_addc_u32 s25, s25, 0
	s_add_i32 s46, s47, s90
	global_load_lds_dwordx4 v132, s[98:99]
	s_mov_b32 m0, s46
	s_nop 0
	global_load_lds_dwordx4 v160, s[24:25]
	s_add_i32 m0, s46, 0x2000
	s_nop 0
	global_load_lds_dwordx4 v132, s[24:25]
	s_mov_b32 m0, s94
	s_nop 0
	s_add_u32 s98, s72, 0xfffc0080
	s_addc_u32 s99, s73, -1
	global_load_lds_dwordx4 v128, s[98:99]
	s_mov_b32 m0, s95
	s_nop 0
	global_load_lds_dwordx4 v130, s[98:99]
	s_waitcnt vmcnt(8)
	s_waitcnt lgkmcnt(0)
	s_barrier
	v_mfma_f32_16x16x32_bf16 v[60:63], v[138:141], v[186:189], v[60:63]
	v_mfma_f32_16x16x32_bf16 v[56:59], v[150:153], v[186:189], v[56:59]
	v_mfma_f32_16x16x32_bf16 v[44:47], v[138:141], v[194:197], v[44:47]
	v_mfma_f32_16x16x32_bf16 v[40:43], v[150:153], v[194:197], v[40:43]
	v_mfma_f32_16x16x32_bf16 v[28:31], v[138:141], v[202:205], v[28:31]
	v_mfma_f32_16x16x32_bf16 v[24:27], v[150:153], v[202:205], v[24:27]
	v_mfma_f32_16x16x32_bf16 v[12:15], v[138:141], v[210:213], v[12:15]
	v_mfma_f32_16x16x32_bf16 v[8:11], v[150:153], v[210:213], v[8:11]
	v_mfma_f32_16x16x32_bf16 v[60:63], v[142:145], v[190:193], v[60:63]
	v_mfma_f32_16x16x32_bf16 v[56:59], v[154:157], v[190:193], v[56:59]
	v_mfma_f32_16x16x32_bf16 v[44:47], v[142:145], v[198:201], v[44:47]
	v_mfma_f32_16x16x32_bf16 v[40:43], v[154:157], v[198:201], v[40:43]
	v_mfma_f32_16x16x32_bf16 v[28:31], v[142:145], v[206:209], v[28:31]
	v_mfma_f32_16x16x32_bf16 v[24:27], v[154:157], v[206:209], v[24:27]
	v_mfma_f32_16x16x32_bf16 v[12:15], v[142:145], v[214:217], v[12:15]
	v_mfma_f32_16x16x32_bf16 v[8:11], v[154:157], v[214:217], v[8:11]
	v_mfma_f32_16x16x32_bf16 v[52:55], v[170:173], v[186:189], v[52:55]
	v_mfma_f32_16x16x32_bf16 v[48:51], v[178:181], v[186:189], v[48:51]
	v_mfma_f32_16x16x32_bf16 v[36:39], v[170:173], v[194:197], v[36:39]
	v_mfma_f32_16x16x32_bf16 v[32:35], v[178:181], v[194:197], v[32:35]
	v_mfma_f32_16x16x32_bf16 v[20:23], v[170:173], v[202:205], v[20:23]
	v_mfma_f32_16x16x32_bf16 v[16:19], v[178:181], v[202:205], v[16:19]
	v_mfma_f32_16x16x32_bf16 v[4:7], v[170:173], v[210:213], v[4:7]
	v_mfma_f32_16x16x32_bf16 v[0:3], v[178:181], v[210:213], v[0:3]
	v_mfma_f32_16x16x32_bf16 v[52:55], v[174:177], v[190:193], v[52:55]
	v_mfma_f32_16x16x32_bf16 v[48:51], v[182:185], v[190:193], v[48:51]
	v_mfma_f32_16x16x32_bf16 v[36:39], v[174:177], v[198:201], v[36:39]
	v_mfma_f32_16x16x32_bf16 v[32:35], v[182:185], v[198:201], v[32:35]
	v_mfma_f32_16x16x32_bf16 v[20:23], v[174:177], v[206:209], v[20:23]
	v_mfma_f32_16x16x32_bf16 v[16:19], v[182:185], v[206:209], v[16:19]
	v_mfma_f32_16x16x32_bf16 v[4:7], v[174:177], v[214:217], v[4:7]
	v_mfma_f32_16x16x32_bf16 v[0:3], v[182:185], v[214:217], v[0:3]
	s_barrier
	s_add_i32 s53, s53, 2
	s_add_u32 s66, s66, 0x100
	s_addc_u32 s67, s67, 0
	s_add_u32 s44, s44, 0x100
	s_addc_u32 s45, s45, 0
	s_cmp_gt_u32 s53, 13
	s_cbranch_scc0 .LBB0_187
	s_setprio 0
	s_and_b64 vcc, exec, s[18:19]
	s_cbranch_vccz .LBB0_190
	s_barrier

; #define PG8_STAGE(bufoff, gbase, voff) do { _Pragma("unroll") for (int _i = 0; _i < 2; ++_i) \
;         __builtin_amdgcn_global_load_lds((const unsigned*)((const char*)(gbase) + (voff)[_i]), (LAS unsigned*)(lds + (bufoff) + ldsw + _i * 8192), 16, 0, 0); } while (0)
; #define PG8_LDA(dst, b, h) do { _Pragma("unroll") for (int m = 0; m < 4; ++m) _Pragma("unroll") for (int k = 0; k < 2; ++k) dst[m][k] = *(const LAS bf16x8*)(lds + PG8_SA(b, h) + aoff + m * 2048 + k * 1024); } while (0)
; #define PG8_LDB(dst, b, h) do { _Pragma("unroll") for (int n = 0; n < 2; ++n) _Pragma("unroll") for (int k = 0; k < 2; ++k) dst[n][k] = *(const LAS bf16x8*)(lds + PG8_SB(b, h) + boff + n * 2048 + k * 1024); } while (0)
; #define PG8_MMA(ai, bj, At, Bt) do { __builtin_amdgcn_s_setprio(1); _Pragma("unroll") for (int m = 0; m < 4; ++m) _Pragma("unroll") for (int n = 0; n < 2; ++n) _Pragma("unroll") for (int k = 0; k < 2; ++k) \
;         acc[ai][bj][m][n] = __builtin_amdgcn_mfma_f32_16x16x32_bf16(Bt[n][k], At[m][k], acc[ai][bj][m][n], 0, 0, 0); __builtin_amdgcn_s_setprio(0); } while (0)
; #define PG8_WAIT_V(n) asm volatile("s_waitcnt vmcnt(" #n ")" ::: "memory")
; #define PG8_WAIT_L(n) asm volatile("s_waitcnt lgkmcnt(" #n ")" ::: "memory")
; #define PG8_BAR __builtin_amdgcn_s_barrier()
; #define PG8_SCHED __builtin_amdgcn_sched_barrier(0)
; template <class Epi, class Sched, bool ALIGN_EPI = true, bool SP2 = true>
; __device__ __forceinline__ void gemm_phase(LAS unsigned char* lds, const Gemm g, const Sched& S, const Epi& E) {
;     ...
;             const char* a1 = cA + (size_t)(t + 1) * kstep;
;             const char* a2 = last ? nA : cA + (size_t)(t + 2) * kstep; const char* b2 = last ? nB : cB + (size_t)(t + 2) * kstep;
;             const char* a3 = a2 + kstep; const char* b3 = b2 + kstep;
;             if constexpr (SP2) {
;             PG8_LDB(B0, 0, 0); PG8_LDB(B1, 0, 1); PG8_SCHED; PG8_LDA(At, 0, 0); PG8_STAGE(PG8_SA(1, 1), a1 + hstep, voffA);
;             PG8_WAIT_V(8); PG8_WAIT_L(0); PG8_BAR; PG8_MMA(0, 0, At, B0); PG8_MMA(0, 1, At, B1); PG8_BAR; PG8_SCHED;
;             PG8_LDA(At, 0, 1); PG8_STAGE(PG8_SB(0, 0), b2, voffB); PG8_STAGE(PG8_SB(0, 1), b2 + hstep, voffB); PG8_STAGE(PG8_SA(0, 0), a2, voffA);
;             PG8_WAIT_V(8); PG8_WAIT_L(0); PG8_BAR; PG8_MMA(1, 0, At, B0); PG8_MMA(1, 1, At, B1); PG8_BAR; PG8_SCHED;
.Lprio_skip_211:
.LBB0_211:
	s_add_u32 s24, s60, 0xfffc0080
	s_addc_u32 s25, s61, -1
	s_add_i32 s46, 0, 0x10000
	s_cmp_eq_u32 s45, 12
	s_cselect_b32 s63, s2, s25
	s_cselect_b32 s62, s3, s24
	s_cselect_b32 s25, s17, s44
	s_cselect_b32 s24, s19, s43
	s_add_i32 s47, 0, 0x14000
	v_add_u32_e32 v154, s46, v147
	v_add_u32_e32 v158, s47, v147
	ds_read_b128 v[138:141], v154
	ds_read_b128 v[142:145], v154 offset:1024
	ds_read_b128 v[150:153], v154 offset:2048
	ds_read_b128 v[154:157], v154 offset:3072
	ds_read_b128 v[170:173], v158
	ds_read_b128 v[174:177], v158 offset:1024
	ds_read_b128 v[178:181], v158 offset:2048
	ds_read_b128 v[182:185], v158 offset:3072
	s_add_i32 m0, s55, 0xc000
	ds_read_b128 v[186:189], v149
	ds_read_b128 v[190:193], v149 offset:1024
	ds_read_b128 v[194:197], v149 offset:2048
	ds_read_b128 v[198:201], v149 offset:3072
	ds_read_b128 v[202:205], v149 offset:4096
	ds_read_b128 v[206:209], v149 offset:5120
	ds_read_b128 v[210:213], v149 offset:6144
	ds_read_b128 v[214:217], v149 offset:7168
	global_load_lds_dwordx4 v134, s[60:61]
	s_add_i32 m0, s55, 0xe000
	s_nop 0
	global_load_lds_dwordx4 v136, s[60:61]
	s_waitcnt vmcnt(8)
	s_waitcnt lgkmcnt(0)
	s_barrier
	v_mfma_f32_16x16x32_bf16 v[124:127], v[138:141], v[186:189], v[124:127]
	v_mfma_f32_16x16x32_bf16 v[120:123], v[150:153], v[186:189], v[120:123]
	v_mfma_f32_16x16x32_bf16 v[108:111], v[138:141], v[194:197], v[108:111]
	v_mfma_f32_16x16x32_bf16 v[104:107], v[150:153], v[194:197], v[104:107]
	v_mfma_f32_16x16x32_bf16 v[92:95], v[138:141], v[202:205], v[92:95]
	v_mfma_f32_16x16x32_bf16 v[88:91], v[150:153], v[202:205], v[88:91]
	v_mfma_f32_16x16x32_bf16 v[76:79], v[138:141], v[210:213], v[76:79]
	v_mfma_f32_16x16x32_bf16 v[72:75], v[150:153], v[210:213], v[72:75]
	v_mfma_f32_16x16x32_bf16 v[124:127], v[142:145], v[190:193], v[124:127]
	v_mfma_f32_16x16x32_bf16 v[120:123], v[154:157], v[190:193], v[120:123]
	v_mfma_f32_16x16x32_bf16 v[108:111], v[142:145], v[198:201], v[108:111]
	v_mfma_f32_16x16x32_bf16 v[104:107], v[154:157], v[198:201], v[104:107]
	v_mfma_f32_16x16x32_bf16 v[92:95], v[142:145], v[206:209], v[92:95]
	v_mfma_f32_16x16x32_bf16 v[88:91], v[154:157], v[206:209], v[88:91]
	v_mfma_f32_16x16x32_bf16 v[76:79], v[142:145], v[214:217], v[76:79]
	v_mfma_f32_16x16x32_bf16 v[72:75], v[154:157], v[214:217], v[72:75]
	v_mfma_f32_16x16x32_bf16 v[116:119], v[170:173], v[186:189], v[116:119]
	v_mfma_f32_16x16x32_bf16 v[112:115], v[178:181], v[186:189], v[112:115]
	v_mfma_f32_16x16x32_bf16 v[100:103], v[170:173], v[194:197], v[100:103]
	v_mfma_f32_16x16x32_bf16 v[96:99], v[178:181], v[194:197], v[96:99]
	v_mfma_f32_16x16x32_bf16 v[84:87], v[170:173], v[202:205], v[84:87]
	v_mfma_f32_16x16x32_bf16 v[80:83], v[178:181], v[202:205], v[80:83]
	v_mfma_f32_16x16x32_bf16 v[68:71], v[170:173], v[210:213], v[68:71]
	v_mfma_f32_16x16x32_bf16 v[64:67], v[178:181], v[210:213], v[64:67]
	v_mfma_f32_16x16x32_bf16 v[116:119], v[174:177], v[190:193], v[116:119]
	v_mfma_f32_16x16x32_bf16 v[112:115], v[182:185], v[190:193], v[112:115]
	v_mfma_f32_16x16x32_bf16 v[100:103], v[174:177], v[198:201], v[100:103]
	v_mfma_f32_16x16x32_bf16 v[96:99], v[182:185], v[198:201], v[96:99]
	v_mfma_f32_16x16x32_bf16 v[84:87], v[174:177], v[206:209], v[84:87]
	v_mfma_f32_16x16x32_bf16 v[80:83], v[182:185], v[206:209], v[80:83]
	v_mfma_f32_16x16x32_bf16 v[68:71], v[174:177], v[214:217], v[68:71]
	v_mfma_f32_16x16x32_bf16 v[64:67], v[182:185], v[214:217], v[64:67]
	s_barrier
	s_add_i32 s46, s46, s73
	s_mov_b32 m0, s46
	ds_read_b128 v[186:189], v149 offset:16384
	ds_read_b128 v[190:193], v149 offset:17408
	ds_read_b128 v[194:197], v149 offset:18432
	ds_read_b128 v[198:201], v149 offset:19456
	ds_read_b128 v[202:205], v149 offset:20480
	ds_read_b128 v[206:209], v149 offset:21504
	ds_read_b128 v[210:213], v149 offset:22528
	ds_read_b128 v[214:217], v149 offset:23552
	global_load_lds_dwordx4 v160, s[24:25]
	s_add_i32 m0, s46, 0x2000
	s_add_u32 s94, s24, 0x40000
	s_addc_u32 s95, s25, 0
	s_add_i32 s46, s47, s73
	global_load_lds_dwordx4 v132, s[24:25]
	s_mov_b32 m0, s46
	s_nop 0
	global_load_lds_dwordx4 v160, s[94:95]
	s_add_i32 m0, s46, 0x2000
	s_nop 0
	global_load_lds_dwordx4 v132, s[94:95]
	s_mov_b32 m0, s55
	s_nop 0
	global_load_lds_dwordx4 v128, s[62:63]
	s_mov_b32 m0, s79
	s_nop 0
	global_load_lds_dwordx4 v130, s[62:63]
	s_waitcnt vmcnt(8)
	s_waitcnt lgkmcnt(0)
	s_barrier
	v_mfma_f32_16x16x32_bf16 v[60:63], v[138:141], v[186:189], v[60:63]
	v_mfma_f32_16x16x32_bf16 v[56:59], v[150:153], v[186:189], v[56:59]
	v_mfma_f32_16x16x32_bf16 v[44:47], v[138:141], v[194:197], v[44:47]
	v_mfma_f32_16x16x32_bf16 v[40:43], v[150:153], v[194:197], v[40:43]
	v_mfma_f32_16x16x32_bf16 v[28:31], v[138:141], v[202:205], v[28:31]
	v_mfma_f32_16x16x32_bf16 v[24:27], v[150:153], v[202:205], v[24:27]
	v_mfma_f32_16x16x32_bf16 v[12:15], v[138:141], v[210:213], v[12:15]
	v_mfma_f32_16x16x32_bf16 v[8:11], v[150:153], v[210:213], v[8:11]
	v_mfma_f32_16x16x32_bf16 v[60:63], v[142:145], v[190:193], v[60:63]
	v_mfma_f32_16x16x32_bf16 v[56:59], v[154:157], v[190:193], v[56:59]
	v_mfma_f32_16x16x32_bf16 v[44:47], v[142:145], v[198:201], v[44:47]
	v_mfma_f32_16x16x32_bf16 v[40:43], v[154:157], v[198:201], v[40:43]
	v_mfma_f32_16x16x32_bf16 v[28:31], v[142:145], v[206:209], v[28:31]
	v_mfma_f32_16x16x32_bf16 v[24:27], v[154:157], v[206:209], v[24:27]
	v_mfma_f32_16x16x32_bf16 v[12:15], v[142:145], v[214:217], v[12:15]
	v_mfma_f32_16x16x32_bf16 v[8:11], v[154:157], v[214:217], v[8:11]
	v_mfma_f32_16x16x32_bf16 v[52:55], v[170:173], v[186:189], v[52:55]
	v_mfma_f32_16x16x32_bf16 v[48:51], v[178:181], v[186:189], v[48:51]
	v_mfma_f32_16x16x32_bf16 v[36:39], v[170:173], v[194:197], v[36:39]
	v_mfma_f32_16x16x32_bf16 v[32:35], v[178:181], v[194:197], v[32:35]
	v_mfma_f32_16x16x32_bf16 v[20:23], v[170:173], v[202:205], v[20:23]
	v_mfma_f32_16x16x32_bf16 v[16:19], v[178:181], v[202:205], v[16:19]
	v_mfma_f32_16x16x32_bf16 v[4:7], v[170:173], v[210:213], v[4:7]
	v_mfma_f32_16x16x32_bf16 v[0:3], v[178:181], v[210:213], v[0:3]
	v_mfma_f32_16x16x32_bf16 v[52:55], v[174:177], v[190:193], v[52:55]
	v_mfma_f32_16x16x32_bf16 v[48:51], v[182:185], v[190:193], v[48:51]
	v_mfma_f32_16x16x32_bf16 v[36:39], v[174:177], v[198:201], v[36:39]
	v_mfma_f32_16x16x32_bf16 v[32:35], v[182:185], v[198:201], v[32:35]
	v_mfma_f32_16x16x32_bf16 v[20:23], v[174:177], v[206:209], v[20:23]
	v_mfma_f32_16x16x32_bf16 v[16:19], v[182:185], v[206:209], v[16:19]
	v_mfma_f32_16x16x32_bf16 v[4:7], v[174:177], v[214:217], v[4:7]
	v_mfma_f32_16x16x32_bf16 v[0:3], v[182:185], v[214:217], v[0:3]
	s_barrier
; #define PG8_STAGE(bufoff, gbase, voff) do { _Pragma("unroll") for (int _i = 0; _i < 2; ++_i) \
;         __builtin_amdgcn_global_load_lds((const unsigned*)((const char*)(gbase) + (voff)[_i]), (LAS unsigned*)(lds + (bufoff) + ldsw + _i * 8192), 16, 0, 0); } while (0)
; #define PG8_LDA(dst, b, h) do { _Pragma("unroll") for (int m = 0; m < 4; ++m) _Pragma("unroll") for (int k = 0; k < 2; ++k) dst[m][k] = *(const LAS bf16x8*)(lds + PG8_SA(b, h) + aoff + m * 2048 + k * 1024); } while (0)
; #define PG8_LDB(dst, b, h) do { _Pragma("unroll") for (int n = 0; n < 2; ++n) _Pragma("unroll") for (int k = 0; k < 2; ++k) dst[n][k] = *(const LAS bf16x8*)(lds + PG8_SB(b, h) + boff + n * 2048 + k * 1024); } while (0)
; #define PG8_MMA(ai, bj, At, Bt) do { __builtin_amdgcn_s_setprio(1); _Pragma("unroll") for (int m = 0; m < 4; ++m) _Pragma("unroll") for (int n = 0; n < 2; ++n) _Pragma("unroll") for (int k = 0; k < 2; ++k) \
;         acc[ai][bj][m][n] = __builtin_amdgcn_mfma_f32_16x16x32_bf16(Bt[n][k], At[m][k], acc[ai][bj][m][n], 0, 0, 0); __builtin_amdgcn_s_setprio(0); } while (0)
; #define PG8_WAIT_V(n) asm volatile("s_waitcnt vmcnt(" #n ")" ::: "memory")
; #define PG8_WAIT_L(n) asm volatile("s_waitcnt lgkmcnt(" #n ")" ::: "memory")
; #define PG8_BAR __builtin_amdgcn_s_barrier()
; #define PG8_SCHED __builtin_amdgcn_sched_barrier(0)
; template <class Epi, class Sched, bool ALIGN_EPI = true, bool SP2 = true>
; __device__ __forceinline__ void gemm_phase(LAS unsigned char* lds, const Gemm g, const Sched& S, const Epi& E) {
;     ...
;             PG8_LDB(B0, 1, 0); PG8_LDB(B1, 1, 1); PG8_SCHED; PG8_LDA(At, 1, 0); PG8_STAGE(PG8_SA(0, 1), a2 + hstep, voffA);
;             PG8_WAIT_V(8); PG8_WAIT_L(0); PG8_BAR; PG8_MMA(0, 0, At, B0); PG8_MMA(0, 1, At, B1); PG8_BAR; PG8_SCHED;
;             PG8_LDA(At, 1, 1); PG8_STAGE(PG8_SB(1, 0), b3, voffB); PG8_STAGE(PG8_SB(1, 1), b3 + hstep, voffB); PG8_STAGE(PG8_SA(1, 0), a3, voffA);
;             PG8_WAIT_V(8); PG8_WAIT_L(0); PG8_BAR; PG8_MMA(1, 0, At, B0); PG8_MMA(1, 1, At, B1); PG8_BAR; PG8_SCHED;
;     ...
;         if constexpr (ALIGN_EPI) { if (wr == 0) PG8_BAR; }
	s_add_i32 s46, 0, 0x18000
	s_add_i32 s47, 0, 0x1c000
	v_add_u32_e32 v154, s46, v147
	v_add_u32_e32 v182, s47, v147
	ds_read_b128 v[138:141], v154
	ds_read_b128 v[142:145], v154 offset:1024
	ds_read_b128 v[150:153], v154 offset:2048
	ds_read_b128 v[154:157], v154 offset:3072
	ds_read_b128 v[170:173], v182
	ds_read_b128 v[174:177], v182 offset:1024
	ds_read_b128 v[178:181], v182 offset:2048
	ds_read_b128 v[182:185], v182 offset:3072
	s_add_u32 s62, s62, 0x40000
	s_addc_u32 s63, s63, 0
	s_mov_b32 m0, s82
	ds_read_b128 v[186:189], v149 offset:32768
	ds_read_b128 v[190:193], v149 offset:33792
	ds_read_b128 v[194:197], v149 offset:34816
	ds_read_b128 v[198:201], v149 offset:35840
	ds_read_b128 v[202:205], v149 offset:36864
	ds_read_b128 v[206:209], v149 offset:37888
	ds_read_b128 v[210:213], v149 offset:38912
	ds_read_b128 v[214:217], v149 offset:39936
	global_load_lds_dwordx4 v128, s[62:63]
	s_mov_b32 m0, s83
	s_nop 0
	global_load_lds_dwordx4 v130, s[62:63]
	s_waitcnt vmcnt(8)
	s_waitcnt lgkmcnt(0)
	s_barrier
	v_mfma_f32_16x16x32_bf16 v[124:127], v[138:141], v[186:189], v[124:127]
	v_mfma_f32_16x16x32_bf16 v[120:123], v[150:153], v[186:189], v[120:123]
	v_mfma_f32_16x16x32_bf16 v[108:111], v[138:141], v[194:197], v[108:111]
	v_mfma_f32_16x16x32_bf16 v[104:107], v[150:153], v[194:197], v[104:107]
	v_mfma_f32_16x16x32_bf16 v[92:95], v[138:141], v[202:205], v[92:95]
	v_mfma_f32_16x16x32_bf16 v[88:91], v[150:153], v[202:205], v[88:91]
	v_mfma_f32_16x16x32_bf16 v[76:79], v[138:141], v[210:213], v[76:79]
	v_mfma_f32_16x16x32_bf16 v[72:75], v[150:153], v[210:213], v[72:75]
	v_mfma_f32_16x16x32_bf16 v[124:127], v[142:145], v[190:193], v[124:127]
	v_mfma_f32_16x16x32_bf16 v[120:123], v[154:157], v[190:193], v[120:123]
	v_mfma_f32_16x16x32_bf16 v[108:111], v[142:145], v[198:201], v[108:111]
	v_mfma_f32_16x16x32_bf16 v[104:107], v[154:157], v[198:201], v[104:107]
	v_mfma_f32_16x16x32_bf16 v[92:95], v[142:145], v[206:209], v[92:95]
	v_mfma_f32_16x16x32_bf16 v[88:91], v[154:157], v[206:209], v[88:91]
	v_mfma_f32_16x16x32_bf16 v[76:79], v[142:145], v[214:217], v[76:79]
	v_mfma_f32_16x16x32_bf16 v[72:75], v[154:157], v[214:217], v[72:75]
	v_mfma_f32_16x16x32_bf16 v[116:119], v[170:173], v[186:189], v[116:119]
	v_mfma_f32_16x16x32_bf16 v[112:115], v[178:181], v[186:189], v[112:115]
	v_mfma_f32_16x16x32_bf16 v[100:103], v[170:173], v[194:197], v[100:103]
	v_mfma_f32_16x16x32_bf16 v[96:99], v[178:181], v[194:197], v[96:99]
	v_mfma_f32_16x16x32_bf16 v[84:87], v[170:173], v[202:205], v[84:87]
	v_mfma_f32_16x16x32_bf16 v[80:83], v[178:181], v[202:205], v[80:83]
	v_mfma_f32_16x16x32_bf16 v[68:71], v[170:173], v[210:213], v[68:71]
	v_mfma_f32_16x16x32_bf16 v[64:67], v[178:181], v[210:213], v[64:67]
	v_mfma_f32_16x16x32_bf16 v[116:119], v[174:177], v[190:193], v[116:119]
	v_mfma_f32_16x16x32_bf16 v[112:115], v[182:185], v[190:193], v[112:115]
	v_mfma_f32_16x16x32_bf16 v[100:103], v[174:177], v[198:201], v[100:103]
	v_mfma_f32_16x16x32_bf16 v[96:99], v[182:185], v[198:201], v[96:99]
	v_mfma_f32_16x16x32_bf16 v[84:87], v[174:177], v[206:209], v[84:87]
	v_mfma_f32_16x16x32_bf16 v[80:83], v[182:185], v[206:209], v[80:83]
	v_mfma_f32_16x16x32_bf16 v[68:71], v[174:177], v[214:217], v[68:71]
	v_mfma_f32_16x16x32_bf16 v[64:67], v[182:185], v[214:217], v[64:67]
	s_barrier
	s_add_i32 s46, s46, s73
	s_mov_b32 m0, s46
	ds_read_b128 v[186:189], v149 offset:49152
	ds_read_b128 v[190:193], v149 offset:50176
	ds_read_b128 v[194:197], v149 offset:51200
	ds_read_b128 v[198:201], v149 offset:52224
	ds_read_b128 v[202:205], v149 offset:53248
	ds_read_b128 v[206:209], v149 offset:54272
	ds_read_b128 v[210:213], v149 offset:55296
	ds_read_b128 v[214:217], v149 offset:56320
	s_add_u32 s98, s24, 0x80
	s_addc_u32 s99, s25, 0
	global_load_lds_dwordx4 v160, s[98:99]
	s_add_i32 m0, s46, 0x2000
	s_add_u32 s24, s24, 0x40080
	s_addc_u32 s25, s25, 0
	s_add_i32 s46, s47, s73
	global_load_lds_dwordx4 v132, s[98:99]
	s_mov_b32 m0, s46
	s_nop 0
	global_load_lds_dwordx4 v160, s[24:25]
	s_add_i32 m0, s46, 0x2000
	s_nop 0
	global_load_lds_dwordx4 v132, s[24:25]
	s_mov_b32 m0, s90
	s_nop 0
	s_add_u32 s98, s62, 0xfffc0080
	s_addc_u32 s99, s63, -1
	global_load_lds_dwordx4 v128, s[98:99]
	s_mov_b32 m0, s91
	s_nop 0
	global_load_lds_dwordx4 v130, s[98:99]
	s_waitcnt vmcnt(8)
	s_waitcnt lgkmcnt(0)
	s_barrier
	v_mfma_f32_16x16x32_bf16 v[60:63], v[138:141], v[186:189], v[60:63]
	v_mfma_f32_16x16x32_bf16 v[56:59], v[150:153], v[186:189], v[56:59]
	v_mfma_f32_16x16x32_bf16 v[44:47], v[138:141], v[194:197], v[44:47]
	v_mfma_f32_16x16x32_bf16 v[40:43], v[150:153], v[194:197], v[40:43]
	v_mfma_f32_16x16x32_bf16 v[28:31], v[138:141], v[202:205], v[28:31]
	v_mfma_f32_16x16x32_bf16 v[24:27], v[150:153], v[202:205], v[24:27]
	v_mfma_f32_16x16x32_bf16 v[12:15], v[138:141], v[210:213], v[12:15]
	v_mfma_f32_16x16x32_bf16 v[8:11], v[150:153], v[210:213], v[8:11]
	v_mfma_f32_16x16x32_bf16 v[60:63], v[142:145], v[190:193], v[60:63]
	v_mfma_f32_16x16x32_bf16 v[56:59], v[154:157], v[190:193], v[56:59]
	v_mfma_f32_16x16x32_bf16 v[44:47], v[142:145], v[198:201], v[44:47]
	v_mfma_f32_16x16x32_bf16 v[40:43], v[154:157], v[198:201], v[40:43]
	v_mfma_f32_16x16x32_bf16 v[28:31], v[142:145], v[206:209], v[28:31]
	v_mfma_f32_16x16x32_bf16 v[24:27], v[154:157], v[206:209], v[24:27]
	v_mfma_f32_16x16x32_bf16 v[12:15], v[142:145], v[214:217], v[12:15]
	v_mfma_f32_16x16x32_bf16 v[8:11], v[154:157], v[214:217], v[8:11]
	v_mfma_f32_16x16x32_bf16 v[52:55], v[170:173], v[186:189], v[52:55]
	v_mfma_f32_16x16x32_bf16 v[48:51], v[178:181], v[186:189], v[48:51]
	v_mfma_f32_16x16x32_bf16 v[36:39], v[170:173], v[194:197], v[36:39]
	v_mfma_f32_16x16x32_bf16 v[32:35], v[178:181], v[194:197], v[32:35]
	v_mfma_f32_16x16x32_bf16 v[20:23], v[170:173], v[202:205], v[20:23]
	v_mfma_f32_16x16x32_bf16 v[16:19], v[178:181], v[202:205], v[16:19]
	v_mfma_f32_16x16x32_bf16 v[4:7], v[170:173], v[210:213], v[4:7]
	v_mfma_f32_16x16x32_bf16 v[0:3], v[178:181], v[210:213], v[0:3]
	v_mfma_f32_16x16x32_bf16 v[52:55], v[174:177], v[190:193], v[52:55]
	v_mfma_f32_16x16x32_bf16 v[48:51], v[182:185], v[190:193], v[48:51]
	v_mfma_f32_16x16x32_bf16 v[36:39], v[174:177], v[198:201], v[36:39]
	v_mfma_f32_16x16x32_bf16 v[32:35], v[182:185], v[198:201], v[32:35]
	v_mfma_f32_16x16x32_bf16 v[20:23], v[174:177], v[206:209], v[20:23]
	v_mfma_f32_16x16x32_bf16 v[16:19], v[182:185], v[206:209], v[16:19]
	v_mfma_f32_16x16x32_bf16 v[4:7], v[174:177], v[214:217], v[4:7]
	v_mfma_f32_16x16x32_bf16 v[0:3], v[182:185], v[214:217], v[0:3]
	s_barrier
	s_add_i32 s45, s45, 2
	s_add_u32 s60, s60, 0x100
	s_addc_u32 s61, s61, 0
	s_add_u32 s43, s43, 0x100
	s_addc_u32 s44, s44, 0
	s_cmp_gt_u32 s45, 13
	s_cbranch_scc0 .LBB0_211
	s_setprio 0
	s_and_b64 vcc, exec, s[14:15]
	s_cbranch_vccz .LBB0_214
	s_barrier

; #define PG8_STAGE(bufoff, gbase, voff) do { _Pragma("unroll") for (int _i = 0; _i < 2; ++_i) \
;         __builtin_amdgcn_global_load_lds((const unsigned*)((const char*)(gbase) + (voff)[_i]), (LAS unsigned*)(lds + (bufoff) + ldsw + _i * 8192), 16, 0, 0); } while (0)
; #define PG8_LDA(dst, b, h) do { _Pragma("unroll") for (int m = 0; m < 4; ++m) _Pragma("unroll") for (int k = 0; k < 2; ++k) dst[m][k] = *(const LAS bf16x8*)(lds + PG8_SA(b, h) + aoff + m * 2048 + k * 1024); } while (0)
; #define PG8_LDB(dst, b, h) do { _Pragma("unroll") for (int n = 0; n < 2; ++n) _Pragma("unroll") for (int k = 0; k < 2; ++k) dst[n][k] = *(const LAS bf16x8*)(lds + PG8_SB(b, h) + boff + n * 2048 + k * 1024); } while (0)
; #define PG8_MMA(ai, bj, At, Bt) do { __builtin_amdgcn_s_setprio(1); _Pragma("unroll") for (int m = 0; m < 4; ++m) _Pragma("unroll") for (int n = 0; n < 2; ++n) _Pragma("unroll") for (int k = 0; k < 2; ++k) \
;         acc[ai][bj][m][n] = __builtin_amdgcn_mfma_f32_16x16x32_bf16(Bt[n][k], At[m][k], acc[ai][bj][m][n], 0, 0, 0); __builtin_amdgcn_s_setprio(0); } while (0)
; #define PG8_WAIT_V(n) asm volatile("s_waitcnt vmcnt(" #n ")" ::: "memory")
; #define PG8_WAIT_L(n) asm volatile("s_waitcnt lgkmcnt(" #n ")" ::: "memory")
; #define PG8_BAR __builtin_amdgcn_s_barrier()
; #define PG8_SCHED __builtin_amdgcn_sched_barrier(0)
; template <class Epi, class Sched, bool ALIGN_EPI = true, bool SP2 = true>
; __device__ __forceinline__ void gemm_phase(LAS unsigned char* lds, const Gemm g, const Sched& S, const Epi& E) {
;     ...
;             const char* a1 = cA + (size_t)(t + 1) * kstep;
;             const char* a2 = last ? nA : cA + (size_t)(t + 2) * kstep; const char* b2 = last ? nB : cB + (size_t)(t + 2) * kstep;
;             const char* a3 = a2 + kstep; const char* b3 = b2 + kstep;
;             if constexpr (SP2) {
;             PG8_LDB(B0, 0, 0); PG8_LDB(B1, 0, 1); PG8_SCHED; PG8_LDA(At, 0, 0); PG8_STAGE(PG8_SA(1, 1), a1 + hstep, voffA);
;             PG8_WAIT_V(8); PG8_WAIT_L(0); PG8_BAR; PG8_MMA(0, 0, At, B0); PG8_MMA(0, 1, At, B1); PG8_BAR; PG8_SCHED;
;             PG8_LDA(At, 0, 1); PG8_STAGE(PG8_SB(0, 0), b2, voffB); PG8_STAGE(PG8_SB(0, 1), b2 + hstep, voffB); PG8_STAGE(PG8_SA(0, 0), a2, voffA);
;             PG8_WAIT_V(8); PG8_WAIT_L(0); PG8_BAR; PG8_MMA(1, 0, At, B0); PG8_MMA(1, 1, At, B1); PG8_BAR; PG8_SCHED;
.Lprio_skip_237:
.LBB0_237:
	s_add_u32 s24, s54, 0xfffc0080
	s_addc_u32 s25, s55, -1
	s_add_i32 s46, 0, 0x10000
	s_cmp_eq_u32 s92, 12
	s_cselect_b32 s61, s2, s25
	s_cselect_b32 s60, s3, s24
	v_add_u32_e32 v142, s46, v145
	s_cselect_b32 s25, s17, s91
	s_cselect_b32 s24, s19, s90
	s_add_i32 s47, 0, 0x14000
	ds_read_b128 v[138:141], v142
	ds_read_b128 v[148:151], v142 offset:1024
	ds_read_b128 v[152:155], v142 offset:2048
	ds_read_b128 v[156:159], v142 offset:3072
	v_add_u32_e32 v142, s47, v145
	ds_read_b128 v[170:173], v142
	ds_read_b128 v[174:177], v142 offset:1024
	ds_read_b128 v[178:181], v142 offset:2048
	ds_read_b128 v[182:185], v142 offset:3072
	s_add_i32 m0, s44, 0xc000
	ds_read_b128 v[186:189], v147
	ds_read_b128 v[190:193], v147 offset:1024
	ds_read_b128 v[194:197], v147 offset:2048
	ds_read_b128 v[198:201], v147 offset:3072
	ds_read_b128 v[202:205], v147 offset:4096
	ds_read_b128 v[206:209], v147 offset:5120
	ds_read_b128 v[210:213], v147 offset:6144
	ds_read_b128 v[214:217], v147 offset:7168
	global_load_lds_dwordx4 v134, s[54:55]
	s_add_i32 m0, s44, 0xe000
	s_nop 0
	global_load_lds_dwordx4 v136, s[54:55]
	s_waitcnt vmcnt(8)
	s_waitcnt lgkmcnt(0)
	s_barrier
	v_mfma_f32_16x16x32_bf16 v[124:127], v[138:141], v[186:189], v[124:127]
	v_mfma_f32_16x16x32_bf16 v[120:123], v[152:155], v[186:189], v[120:123]
	v_mfma_f32_16x16x32_bf16 v[108:111], v[138:141], v[194:197], v[108:111]
	v_mfma_f32_16x16x32_bf16 v[104:107], v[152:155], v[194:197], v[104:107]
	v_mfma_f32_16x16x32_bf16 v[92:95], v[138:141], v[202:205], v[92:95]
	v_mfma_f32_16x16x32_bf16 v[88:91], v[152:155], v[202:205], v[88:91]
	v_mfma_f32_16x16x32_bf16 v[76:79], v[138:141], v[210:213], v[76:79]
	v_mfma_f32_16x16x32_bf16 v[72:75], v[152:155], v[210:213], v[72:75]
	v_mfma_f32_16x16x32_bf16 v[124:127], v[148:151], v[190:193], v[124:127]
	v_mfma_f32_16x16x32_bf16 v[120:123], v[156:159], v[190:193], v[120:123]
	v_mfma_f32_16x16x32_bf16 v[108:111], v[148:151], v[198:201], v[108:111]
	v_mfma_f32_16x16x32_bf16 v[104:107], v[156:159], v[198:201], v[104:107]
	v_mfma_f32_16x16x32_bf16 v[92:95], v[148:151], v[206:209], v[92:95]
	v_mfma_f32_16x16x32_bf16 v[88:91], v[156:159], v[206:209], v[88:91]
	v_mfma_f32_16x16x32_bf16 v[76:79], v[148:151], v[214:217], v[76:79]
	v_mfma_f32_16x16x32_bf16 v[72:75], v[156:159], v[214:217], v[72:75]
	v_mfma_f32_16x16x32_bf16 v[116:119], v[170:173], v[186:189], v[116:119]
	v_mfma_f32_16x16x32_bf16 v[112:115], v[178:181], v[186:189], v[112:115]
	v_mfma_f32_16x16x32_bf16 v[100:103], v[170:173], v[194:197], v[100:103]
	v_mfma_f32_16x16x32_bf16 v[96:99], v[178:181], v[194:197], v[96:99]
	v_mfma_f32_16x16x32_bf16 v[84:87], v[170:173], v[202:205], v[84:87]
	v_mfma_f32_16x16x32_bf16 v[80:83], v[178:181], v[202:205], v[80:83]
	v_mfma_f32_16x16x32_bf16 v[68:71], v[170:173], v[210:213], v[68:71]
	v_mfma_f32_16x16x32_bf16 v[64:67], v[178:181], v[210:213], v[64:67]
	v_mfma_f32_16x16x32_bf16 v[116:119], v[174:177], v[190:193], v[116:119]
	v_mfma_f32_16x16x32_bf16 v[112:115], v[182:185], v[190:193], v[112:115]
	v_mfma_f32_16x16x32_bf16 v[100:103], v[174:177], v[198:201], v[100:103]
	v_mfma_f32_16x16x32_bf16 v[96:99], v[182:185], v[198:201], v[96:99]
	v_mfma_f32_16x16x32_bf16 v[84:87], v[174:177], v[206:209], v[84:87]
	v_mfma_f32_16x16x32_bf16 v[80:83], v[182:185], v[206:209], v[80:83]
	v_mfma_f32_16x16x32_bf16 v[68:71], v[174:177], v[214:217], v[68:71]
	v_mfma_f32_16x16x32_bf16 v[64:67], v[182:185], v[214:217], v[64:67]
	s_barrier
	s_add_i32 s46, s46, s43
	s_mov_b32 m0, s46
	ds_read_b128 v[186:189], v147 offset:16384
	ds_read_b128 v[190:193], v147 offset:17408
	ds_read_b128 v[194:197], v147 offset:18432
	ds_read_b128 v[198:201], v147 offset:19456
	ds_read_b128 v[202:205], v147 offset:20480
	ds_read_b128 v[206:209], v147 offset:21504
	ds_read_b128 v[210:213], v147 offset:22528
	ds_read_b128 v[214:217], v147 offset:23552
	global_load_lds_dwordx4 v160, s[24:25]
	s_add_i32 m0, s46, 0x2000
	s_add_u32 s94, s24, 0x40000
	s_addc_u32 s95, s25, 0
	s_add_i32 s46, s47, s43
	global_load_lds_dwordx4 v128, s[24:25]
	s_mov_b32 m0, s46
	s_nop 0
	global_load_lds_dwordx4 v160, s[94:95]
	s_add_i32 m0, s46, 0x2000
	s_nop 0
	global_load_lds_dwordx4 v128, s[94:95]
	s_mov_b32 m0, s44
	s_nop 0
	global_load_lds_dwordx4 v132, s[60:61]
	s_mov_b32 m0, s45
	s_nop 0
	global_load_lds_dwordx4 v130, s[60:61]
	s_waitcnt vmcnt(8)
	s_waitcnt lgkmcnt(0)
	s_barrier
	v_mfma_f32_16x16x32_bf16 v[60:63], v[138:141], v[186:189], v[60:63]
	v_mfma_f32_16x16x32_bf16 v[56:59], v[152:155], v[186:189], v[56:59]
	v_mfma_f32_16x16x32_bf16 v[44:47], v[138:141], v[194:197], v[44:47]
	v_mfma_f32_16x16x32_bf16 v[40:43], v[152:155], v[194:197], v[40:43]
	v_mfma_f32_16x16x32_bf16 v[28:31], v[138:141], v[202:205], v[28:31]
	v_mfma_f32_16x16x32_bf16 v[24:27], v[152:155], v[202:205], v[24:27]
	v_mfma_f32_16x16x32_bf16 v[12:15], v[138:141], v[210:213], v[12:15]
	v_mfma_f32_16x16x32_bf16 v[8:11], v[152:155], v[210:213], v[8:11]
	v_mfma_f32_16x16x32_bf16 v[60:63], v[148:151], v[190:193], v[60:63]
	v_mfma_f32_16x16x32_bf16 v[56:59], v[156:159], v[190:193], v[56:59]
	v_mfma_f32_16x16x32_bf16 v[44:47], v[148:151], v[198:201], v[44:47]
	v_mfma_f32_16x16x32_bf16 v[40:43], v[156:159], v[198:201], v[40:43]
	v_mfma_f32_16x16x32_bf16 v[28:31], v[148:151], v[206:209], v[28:31]
	v_mfma_f32_16x16x32_bf16 v[24:27], v[156:159], v[206:209], v[24:27]
	v_mfma_f32_16x16x32_bf16 v[12:15], v[148:151], v[214:217], v[12:15]
	v_mfma_f32_16x16x32_bf16 v[8:11], v[156:159], v[214:217], v[8:11]
	v_mfma_f32_16x16x32_bf16 v[52:55], v[170:173], v[186:189], v[52:55]
	v_mfma_f32_16x16x32_bf16 v[48:51], v[178:181], v[186:189], v[48:51]
	v_mfma_f32_16x16x32_bf16 v[36:39], v[170:173], v[194:197], v[36:39]
	v_mfma_f32_16x16x32_bf16 v[32:35], v[178:181], v[194:197], v[32:35]
	v_mfma_f32_16x16x32_bf16 v[20:23], v[170:173], v[202:205], v[20:23]
	v_mfma_f32_16x16x32_bf16 v[16:19], v[178:181], v[202:205], v[16:19]
	v_mfma_f32_16x16x32_bf16 v[4:7], v[170:173], v[210:213], v[4:7]
	v_mfma_f32_16x16x32_bf16 v[0:3], v[178:181], v[210:213], v[0:3]
	v_mfma_f32_16x16x32_bf16 v[52:55], v[174:177], v[190:193], v[52:55]
	v_mfma_f32_16x16x32_bf16 v[48:51], v[182:185], v[190:193], v[48:51]
	v_mfma_f32_16x16x32_bf16 v[36:39], v[174:177], v[198:201], v[36:39]
	v_mfma_f32_16x16x32_bf16 v[32:35], v[182:185], v[198:201], v[32:35]
	v_mfma_f32_16x16x32_bf16 v[20:23], v[174:177], v[206:209], v[20:23]
	v_mfma_f32_16x16x32_bf16 v[16:19], v[182:185], v[206:209], v[16:19]
	v_mfma_f32_16x16x32_bf16 v[4:7], v[174:177], v[214:217], v[4:7]
	v_mfma_f32_16x16x32_bf16 v[0:3], v[182:185], v[214:217], v[0:3]
	s_barrier
; #define PG8_STAGE(bufoff, gbase, voff) do { _Pragma("unroll") for (int _i = 0; _i < 2; ++_i) \
;         __builtin_amdgcn_global_load_lds((const unsigned*)((const char*)(gbase) + (voff)[_i]), (LAS unsigned*)(lds + (bufoff) + ldsw + _i * 8192), 16, 0, 0); } while (0)
; #define PG8_LDA(dst, b, h) do { _Pragma("unroll") for (int m = 0; m < 4; ++m) _Pragma("unroll") for (int k = 0; k < 2; ++k) dst[m][k] = *(const LAS bf16x8*)(lds + PG8_SA(b, h) + aoff + m * 2048 + k * 1024); } while (0)
; #define PG8_LDB(dst, b, h) do { _Pragma("unroll") for (int n = 0; n < 2; ++n) _Pragma("unroll") for (int k = 0; k < 2; ++k) dst[n][k] = *(const LAS bf16x8*)(lds + PG8_SB(b, h) + boff + n * 2048 + k * 1024); } while (0)
; #define PG8_MMA(ai, bj, At, Bt) do { __builtin_amdgcn_s_setprio(1); _Pragma("unroll") for (int m = 0; m < 4; ++m) _Pragma("unroll") for (int n = 0; n < 2; ++n) _Pragma("unroll") for (int k = 0; k < 2; ++k) \
;         acc[ai][bj][m][n] = __builtin_amdgcn_mfma_f32_16x16x32_bf16(Bt[n][k], At[m][k], acc[ai][bj][m][n], 0, 0, 0); __builtin_amdgcn_s_setprio(0); } while (0)
; #define PG8_WAIT_V(n) asm volatile("s_waitcnt vmcnt(" #n ")" ::: "memory")
; #define PG8_WAIT_L(n) asm volatile("s_waitcnt lgkmcnt(" #n ")" ::: "memory")
; #define PG8_BAR __builtin_amdgcn_s_barrier()
; #define PG8_SCHED __builtin_amdgcn_sched_barrier(0)
; template <class Epi, class Sched, bool ALIGN_EPI = true, bool SP2 = true>
; __device__ __forceinline__ void gemm_phase(LAS unsigned char* lds, const Gemm g, const Sched& S, const Epi& E) {
;     ...
;             PG8_LDB(B0, 1, 0); PG8_LDB(B1, 1, 1); PG8_SCHED; PG8_LDA(At, 1, 0); PG8_STAGE(PG8_SA(0, 1), a2 + hstep, voffA);
;             PG8_WAIT_V(8); PG8_WAIT_L(0); PG8_BAR; PG8_MMA(0, 0, At, B0); PG8_MMA(0, 1, At, B1); PG8_BAR; PG8_SCHED;
;             PG8_LDA(At, 1, 1); PG8_STAGE(PG8_SB(1, 0), b3, voffB); PG8_STAGE(PG8_SB(1, 1), b3 + hstep, voffB); PG8_STAGE(PG8_SA(1, 0), a3, voffA);
;             PG8_WAIT_V(8); PG8_WAIT_L(0); PG8_BAR; PG8_MMA(1, 0, At, B0); PG8_MMA(1, 1, At, B1); PG8_BAR; PG8_SCHED;
;     ...
;         if constexpr (ALIGN_EPI) { if (wr == 0) PG8_BAR; }
	s_add_i32 s46, 0, 0x18000
	s_add_i32 s47, 0, 0x1c000
	v_add_u32_e32 v156, s46, v145
	v_add_u32_e32 v182, s47, v145
	ds_read_b128 v[138:141], v156
	ds_read_b128 v[148:151], v156 offset:1024
	ds_read_b128 v[152:155], v156 offset:2048
	ds_read_b128 v[156:159], v156 offset:3072
	ds_read_b128 v[170:173], v182
	ds_read_b128 v[174:177], v182 offset:1024
	ds_read_b128 v[178:181], v182 offset:2048
	ds_read_b128 v[182:185], v182 offset:3072
	s_add_u32 s60, s60, 0x40000
	s_addc_u32 s61, s61, 0
	s_mov_b32 m0, s62
	ds_read_b128 v[186:189], v147 offset:32768
	ds_read_b128 v[190:193], v147 offset:33792
	ds_read_b128 v[194:197], v147 offset:34816
	ds_read_b128 v[198:201], v147 offset:35840
	ds_read_b128 v[202:205], v147 offset:36864
	ds_read_b128 v[206:209], v147 offset:37888
	ds_read_b128 v[210:213], v147 offset:38912
	ds_read_b128 v[214:217], v147 offset:39936
	global_load_lds_dwordx4 v132, s[60:61]
	s_mov_b32 m0, s63
	s_nop 0
	global_load_lds_dwordx4 v130, s[60:61]
	s_waitcnt vmcnt(8)
	s_waitcnt lgkmcnt(0)
	s_barrier
	v_mfma_f32_16x16x32_bf16 v[124:127], v[138:141], v[186:189], v[124:127]
	v_mfma_f32_16x16x32_bf16 v[120:123], v[152:155], v[186:189], v[120:123]
	v_mfma_f32_16x16x32_bf16 v[108:111], v[138:141], v[194:197], v[108:111]
	v_mfma_f32_16x16x32_bf16 v[104:107], v[152:155], v[194:197], v[104:107]
	v_mfma_f32_16x16x32_bf16 v[92:95], v[138:141], v[202:205], v[92:95]
	v_mfma_f32_16x16x32_bf16 v[88:91], v[152:155], v[202:205], v[88:91]
	v_mfma_f32_16x16x32_bf16 v[76:79], v[138:141], v[210:213], v[76:79]
	v_mfma_f32_16x16x32_bf16 v[72:75], v[152:155], v[210:213], v[72:75]
	v_mfma_f32_16x16x32_bf16 v[124:127], v[148:151], v[190:193], v[124:127]
	v_mfma_f32_16x16x32_bf16 v[120:123], v[156:159], v[190:193], v[120:123]
	v_mfma_f32_16x16x32_bf16 v[108:111], v[148:151], v[198:201], v[108:111]
	v_mfma_f32_16x16x32_bf16 v[104:107], v[156:159], v[198:201], v[104:107]
	v_mfma_f32_16x16x32_bf16 v[92:95], v[148:151], v[206:209], v[92:95]
	v_mfma_f32_16x16x32_bf16 v[88:91], v[156:159], v[206:209], v[88:91]
	v_mfma_f32_16x16x32_bf16 v[76:79], v[148:151], v[214:217], v[76:79]
	v_mfma_f32_16x16x32_bf16 v[72:75], v[156:159], v[214:217], v[72:75]
	v_mfma_f32_16x16x32_bf16 v[116:119], v[170:173], v[186:189], v[116:119]
	v_mfma_f32_16x16x32_bf16 v[112:115], v[178:181], v[186:189], v[112:115]
	v_mfma_f32_16x16x32_bf16 v[100:103], v[170:173], v[194:197], v[100:103]
	v_mfma_f32_16x16x32_bf16 v[96:99], v[178:181], v[194:197], v[96:99]
	v_mfma_f32_16x16x32_bf16 v[84:87], v[170:173], v[202:205], v[84:87]
	v_mfma_f32_16x16x32_bf16 v[80:83], v[178:181], v[202:205], v[80:83]
	v_mfma_f32_16x16x32_bf16 v[68:71], v[170:173], v[210:213], v[68:71]
	v_mfma_f32_16x16x32_bf16 v[64:67], v[178:181], v[210:213], v[64:67]
	v_mfma_f32_16x16x32_bf16 v[116:119], v[174:177], v[190:193], v[116:119]
	v_mfma_f32_16x16x32_bf16 v[112:115], v[182:185], v[190:193], v[112:115]
	v_mfma_f32_16x16x32_bf16 v[100:103], v[174:177], v[198:201], v[100:103]
	v_mfma_f32_16x16x32_bf16 v[96:99], v[182:185], v[198:201], v[96:99]
	v_mfma_f32_16x16x32_bf16 v[84:87], v[174:177], v[206:209], v[84:87]
	v_mfma_f32_16x16x32_bf16 v[80:83], v[182:185], v[206:209], v[80:83]
	v_mfma_f32_16x16x32_bf16 v[68:71], v[174:177], v[214:217], v[68:71]
	v_mfma_f32_16x16x32_bf16 v[64:67], v[182:185], v[214:217], v[64:67]
	s_barrier
	s_add_i32 s46, s46, s43
	s_mov_b32 m0, s46
	ds_read_b128 v[186:189], v147 offset:49152
	ds_read_b128 v[190:193], v147 offset:50176
	ds_read_b128 v[194:197], v147 offset:51200
	ds_read_b128 v[198:201], v147 offset:52224
	ds_read_b128 v[202:205], v147 offset:53248
	ds_read_b128 v[206:209], v147 offset:54272
	ds_read_b128 v[210:213], v147 offset:55296
	ds_read_b128 v[214:217], v147 offset:56320
	s_add_u32 s98, s24, 0x80
	s_addc_u32 s99, s25, 0
	global_load_lds_dwordx4 v160, s[98:99]
	s_add_i32 m0, s46, 0x2000
	s_add_u32 s24, s24, 0x40080
	s_addc_u32 s25, s25, 0
	s_add_i32 s46, s47, s43
	global_load_lds_dwordx4 v128, s[98:99]
	s_mov_b32 m0, s46
	s_nop 0
	global_load_lds_dwordx4 v160, s[24:25]
	s_add_i32 m0, s46, 0x2000
	s_nop 0
	global_load_lds_dwordx4 v128, s[24:25]
	s_mov_b32 m0, s67
	s_nop 0
	s_add_u32 s98, s60, 0xfffc0080
	s_addc_u32 s99, s61, -1
	global_load_lds_dwordx4 v132, s[98:99]
	s_mov_b32 m0, s72
	s_nop 0
	global_load_lds_dwordx4 v130, s[98:99]
	s_waitcnt vmcnt(8)
	s_waitcnt lgkmcnt(0)
	s_barrier
	v_mfma_f32_16x16x32_bf16 v[60:63], v[138:141], v[186:189], v[60:63]
	v_mfma_f32_16x16x32_bf16 v[56:59], v[152:155], v[186:189], v[56:59]
	v_mfma_f32_16x16x32_bf16 v[44:47], v[138:141], v[194:197], v[44:47]
	v_mfma_f32_16x16x32_bf16 v[40:43], v[152:155], v[194:197], v[40:43]
	v_mfma_f32_16x16x32_bf16 v[28:31], v[138:141], v[202:205], v[28:31]
	v_mfma_f32_16x16x32_bf16 v[24:27], v[152:155], v[202:205], v[24:27]
	v_mfma_f32_16x16x32_bf16 v[12:15], v[138:141], v[210:213], v[12:15]
	v_mfma_f32_16x16x32_bf16 v[8:11], v[152:155], v[210:213], v[8:11]
	v_mfma_f32_16x16x32_bf16 v[60:63], v[148:151], v[190:193], v[60:63]
	v_mfma_f32_16x16x32_bf16 v[56:59], v[156:159], v[190:193], v[56:59]
	v_mfma_f32_16x16x32_bf16 v[44:47], v[148:151], v[198:201], v[44:47]
	v_mfma_f32_16x16x32_bf16 v[40:43], v[156:159], v[198:201], v[40:43]
	v_mfma_f32_16x16x32_bf16 v[28:31], v[148:151], v[206:209], v[28:31]
	v_mfma_f32_16x16x32_bf16 v[24:27], v[156:159], v[206:209], v[24:27]
	v_mfma_f32_16x16x32_bf16 v[12:15], v[148:151], v[214:217], v[12:15]
	v_mfma_f32_16x16x32_bf16 v[8:11], v[156:159], v[214:217], v[8:11]
	v_mfma_f32_16x16x32_bf16 v[52:55], v[170:173], v[186:189], v[52:55]
	v_mfma_f32_16x16x32_bf16 v[48:51], v[178:181], v[186:189], v[48:51]
	v_mfma_f32_16x16x32_bf16 v[36:39], v[170:173], v[194:197], v[36:39]
	v_mfma_f32_16x16x32_bf16 v[32:35], v[178:181], v[194:197], v[32:35]
	v_mfma_f32_16x16x32_bf16 v[20:23], v[170:173], v[202:205], v[20:23]
	v_mfma_f32_16x16x32_bf16 v[16:19], v[178:181], v[202:205], v[16:19]
	v_mfma_f32_16x16x32_bf16 v[4:7], v[170:173], v[210:213], v[4:7]
	v_mfma_f32_16x16x32_bf16 v[0:3], v[178:181], v[210:213], v[0:3]
	v_mfma_f32_16x16x32_bf16 v[52:55], v[174:177], v[190:193], v[52:55]
	v_mfma_f32_16x16x32_bf16 v[48:51], v[182:185], v[190:193], v[48:51]
	v_mfma_f32_16x16x32_bf16 v[36:39], v[174:177], v[198:201], v[36:39]
	v_mfma_f32_16x16x32_bf16 v[32:35], v[182:185], v[198:201], v[32:35]
	v_mfma_f32_16x16x32_bf16 v[20:23], v[174:177], v[206:209], v[20:23]
	v_mfma_f32_16x16x32_bf16 v[16:19], v[182:185], v[206:209], v[16:19]
	v_mfma_f32_16x16x32_bf16 v[4:7], v[174:177], v[214:217], v[4:7]
	v_mfma_f32_16x16x32_bf16 v[0:3], v[182:185], v[214:217], v[0:3]
	s_barrier
	s_add_i32 s92, s92, 2
	s_add_u32 s54, s54, 0x100
	s_addc_u32 s55, s55, 0
	s_add_u32 s90, s90, 0x100
	s_addc_u32 s91, s91, 0
	s_cmp_gt_u32 s92, 13
	s_cbranch_scc0 .LBB0_237
	s_setprio 0
	s_and_b64 vcc, exec, s[14:15]
	s_cbranch_vccz .LBB0_240
	s_barrier

; #define LAS __attribute__((address_space(3)))
; __global__ void __launch_bounds__(NTHREADS, 2) fwd_kernel(Args a) {
;     ...
;                     LAS int* slot = (LAS int*)(lds + MISC_OFF);
;                     for (;;) {
;                         const int q = queue_pop(qctr + 2 + l + (dry ? 4 : 0), slot);
;                         if (q >= 512) break;
;                         const int qb = 7 - (q >> 6), bh = q & 63, b = bh >> 3, h = bh & 7;
;                         const size_t rb = (size_t)b * SEQ;
;                         bf16_t* FQ = (bf16_t*)(ws + Z_FQ); const bf16_t* FK = (const bf16_t*)(ws + Z_FK); const bf16_t* FV = (const bf16_t*)(ws + Z_FV);
;                         attn_unit<true>(lds, FQ + (rb + qb * 256) * 1024 + h * 128, 1024, FK + rb * 1024 + h * 128, FV + rb * 1024 + h * 128, 1024,
;                                         FQ + (rb + qb * 256) * 1024 + h * 128, 1024, (qb + 1) * 4, qb * 256, (const float*)(ws + WS_LOGF) + rb * 8 + h, dry);
;                     }
.LBB0_244:
	v_lshrrev_b32_e32 v254, 8, v238
	v_cmp_ne_u32_e64 s[98:99], 0, v254
	s_nop 3
	s_and_b64 s[98:99], s[98:99], exec
	s_cbranch_scc0 .Lprio_skip_fox
	s_setprio 1

; __global__ void __launch_bounds__(NTHREADS, 2) fwd_kernel(Args a) {
;     ...
;                     for (;;) {
;                         const int q = queue_pop(qctr + 2 + l + (dry ? 4 : 0), slot);
;                         if (q >= 512) break;
.LBB0_283:
	s_setprio 0
	s_mov_b64 s[2:3], 0

; #define PG8_STAGE(bufoff, gbase, voff) do { _Pragma("unroll") for (int _i = 0; _i < 2; ++_i) \
;         __builtin_amdgcn_global_load_lds((const unsigned*)((const char*)(gbase) + (voff)[_i]), (LAS unsigned*)(lds + (bufoff) + ldsw + _i * 8192), 16, 0, 0); } while (0)
; #define PG8_LDA(dst, b, h) do { _Pragma("unroll") for (int m = 0; m < 4; ++m) _Pragma("unroll") for (int k = 0; k < 2; ++k) dst[m][k] = *(const LAS bf16x8*)(lds + PG8_SA(b, h) + aoff + m * 2048 + k * 1024); } while (0)
; #define PG8_LDB(dst, b, h) do { _Pragma("unroll") for (int n = 0; n < 2; ++n) _Pragma("unroll") for (int k = 0; k < 2; ++k) dst[n][k] = *(const LAS bf16x8*)(lds + PG8_SB(b, h) + boff + n * 2048 + k * 1024); } while (0)
; #define PG8_MMA(ai, bj, At, Bt) do { __builtin_amdgcn_s_setprio(1); _Pragma("unroll") for (int m = 0; m < 4; ++m) _Pragma("unroll") for (int n = 0; n < 2; ++n) _Pragma("unroll") for (int k = 0; k < 2; ++k) \
;         acc[ai][bj][m][n] = __builtin_amdgcn_mfma_f32_16x16x32_bf16(Bt[n][k], At[m][k], acc[ai][bj][m][n], 0, 0, 0); __builtin_amdgcn_s_setprio(0); } while (0)
; #define PG8_WAIT_V(n) asm volatile("s_waitcnt vmcnt(" #n ")" ::: "memory")
; #define PG8_WAIT_L(n) asm volatile("s_waitcnt lgkmcnt(" #n ")" ::: "memory")
; #define PG8_BAR __builtin_amdgcn_s_barrier()
; #define PG8_SCHED __builtin_amdgcn_sched_barrier(0)
; template <class Epi, class Sched, bool ALIGN_EPI = true, bool SP2 = true>
; __device__ __forceinline__ void gemm_phase(LAS unsigned char* lds, const Gemm g, const Sched& S, const Epi& E) {
;     ...
;             const char* a1 = cA + (size_t)(t + 1) * kstep;
;             const char* a2 = last ? nA : cA + (size_t)(t + 2) * kstep; const char* b2 = last ? nB : cB + (size_t)(t + 2) * kstep;
;             const char* a3 = a2 + kstep; const char* b3 = b2 + kstep;
;             if constexpr (SP2) {
;             PG8_LDB(B0, 0, 0); PG8_LDB(B1, 0, 1); PG8_SCHED; PG8_LDA(At, 0, 0); PG8_STAGE(PG8_SA(1, 1), a1 + hstep, voffA);
;             PG8_WAIT_V(8); PG8_WAIT_L(0); PG8_BAR; PG8_MMA(0, 0, At, B0); PG8_MMA(0, 1, At, B1); PG8_BAR; PG8_SCHED;
;             PG8_LDA(At, 0, 1); PG8_STAGE(PG8_SB(0, 0), b2, voffB); PG8_STAGE(PG8_SB(0, 1), b2 + hstep, voffB); PG8_STAGE(PG8_SA(0, 0), a2, voffA);
;             PG8_WAIT_V(8); PG8_WAIT_L(0); PG8_BAR; PG8_MMA(1, 0, At, B0); PG8_MMA(1, 1, At, B1); PG8_BAR; PG8_SCHED;
.Lprio_skip_354:
.LBB0_354:
	s_add_u32 s24, s62, 0xfff80080
	s_addc_u32 s25, s63, -1
	s_add_i32 s43, 0, 0x10000
	s_cmp_eq_u32 s42, 28
	s_cselect_b32 s83, s2, s25
	s_cselect_b32 s82, s3, s24
	s_cselect_b32 s25, s7, s19
	s_cselect_b32 s24, s9, s18
	s_add_i32 s46, 0, 0x14000
	v_add_u32_e32 v150, s43, v155
	v_add_u32_e32 v158, s46, v155
	ds_read_b128 v[138:141], v150
	ds_read_b128 v[142:145], v150 offset:1024
	ds_read_b128 v[146:149], v150 offset:2048
	ds_read_b128 v[150:153], v150 offset:3072
	ds_read_b128 v[170:173], v158
	ds_read_b128 v[174:177], v158 offset:1024
	ds_read_b128 v[178:181], v158 offset:2048
	ds_read_b128 v[182:185], v158 offset:3072
	s_add_i32 m0, s16, 0xc000
	ds_read_b128 v[186:189], v157
	ds_read_b128 v[190:193], v157 offset:1024
	ds_read_b128 v[194:197], v157 offset:2048
	ds_read_b128 v[198:201], v157 offset:3072
	ds_read_b128 v[202:205], v157 offset:4096
	ds_read_b128 v[206:209], v157 offset:5120
	ds_read_b128 v[210:213], v157 offset:6144
	ds_read_b128 v[214:217], v157 offset:7168
	global_load_lds_dwordx4 v134, s[62:63]
	s_add_i32 m0, s16, 0xe000
	s_nop 0
	global_load_lds_dwordx4 v136, s[62:63]
	s_waitcnt vmcnt(8)
	s_waitcnt lgkmcnt(0)
	s_barrier
	v_mfma_f32_16x16x32_bf16 v[124:127], v[138:141], v[186:189], v[124:127]
	v_mfma_f32_16x16x32_bf16 v[120:123], v[146:149], v[186:189], v[120:123]
	v_mfma_f32_16x16x32_bf16 v[108:111], v[138:141], v[194:197], v[108:111]
	v_mfma_f32_16x16x32_bf16 v[104:107], v[146:149], v[194:197], v[104:107]
	v_mfma_f32_16x16x32_bf16 v[92:95], v[138:141], v[202:205], v[92:95]
	v_mfma_f32_16x16x32_bf16 v[88:91], v[146:149], v[202:205], v[88:91]
	v_mfma_f32_16x16x32_bf16 v[76:79], v[138:141], v[210:213], v[76:79]
	v_mfma_f32_16x16x32_bf16 v[72:75], v[146:149], v[210:213], v[72:75]
	v_mfma_f32_16x16x32_bf16 v[124:127], v[142:145], v[190:193], v[124:127]
	v_mfma_f32_16x16x32_bf16 v[120:123], v[150:153], v[190:193], v[120:123]
	v_mfma_f32_16x16x32_bf16 v[108:111], v[142:145], v[198:201], v[108:111]
	v_mfma_f32_16x16x32_bf16 v[104:107], v[150:153], v[198:201], v[104:107]
	v_mfma_f32_16x16x32_bf16 v[92:95], v[142:145], v[206:209], v[92:95]
	v_mfma_f32_16x16x32_bf16 v[88:91], v[150:153], v[206:209], v[88:91]
	v_mfma_f32_16x16x32_bf16 v[76:79], v[142:145], v[214:217], v[76:79]
	v_mfma_f32_16x16x32_bf16 v[72:75], v[150:153], v[214:217], v[72:75]
	v_mfma_f32_16x16x32_bf16 v[116:119], v[170:173], v[186:189], v[116:119]
	v_mfma_f32_16x16x32_bf16 v[112:115], v[178:181], v[186:189], v[112:115]
	v_mfma_f32_16x16x32_bf16 v[100:103], v[170:173], v[194:197], v[100:103]
	v_mfma_f32_16x16x32_bf16 v[96:99], v[178:181], v[194:197], v[96:99]
	v_mfma_f32_16x16x32_bf16 v[84:87], v[170:173], v[202:205], v[84:87]
	v_mfma_f32_16x16x32_bf16 v[80:83], v[178:181], v[202:205], v[80:83]
	v_mfma_f32_16x16x32_bf16 v[68:71], v[170:173], v[210:213], v[68:71]
	v_mfma_f32_16x16x32_bf16 v[64:67], v[178:181], v[210:213], v[64:67]
	v_mfma_f32_16x16x32_bf16 v[116:119], v[174:177], v[190:193], v[116:119]
	v_mfma_f32_16x16x32_bf16 v[112:115], v[182:185], v[190:193], v[112:115]
	v_mfma_f32_16x16x32_bf16 v[100:103], v[174:177], v[198:201], v[100:103]
	v_mfma_f32_16x16x32_bf16 v[96:99], v[182:185], v[198:201], v[96:99]
	v_mfma_f32_16x16x32_bf16 v[84:87], v[174:177], v[206:209], v[84:87]
	v_mfma_f32_16x16x32_bf16 v[80:83], v[182:185], v[206:209], v[80:83]
	v_mfma_f32_16x16x32_bf16 v[68:71], v[174:177], v[214:217], v[68:71]
	v_mfma_f32_16x16x32_bf16 v[64:67], v[182:185], v[214:217], v[64:67]
	s_barrier
	s_add_i32 s43, s43, s41
	s_mov_b32 m0, s43
	ds_read_b128 v[186:189], v157 offset:16384
	ds_read_b128 v[190:193], v157 offset:17408
	ds_read_b128 v[194:197], v157 offset:18432
	ds_read_b128 v[198:201], v157 offset:19456
	ds_read_b128 v[202:205], v157 offset:20480
	ds_read_b128 v[206:209], v157 offset:21504
	ds_read_b128 v[210:213], v157 offset:22528
	ds_read_b128 v[214:217], v157 offset:23552
	global_load_lds_dwordx4 v160, s[24:25]
	s_add_i32 m0, s43, 0x2000
	s_add_u32 s44, s24, 0x80000
	s_addc_u32 s45, s25, 0
	s_add_i32 s43, s46, s41
	global_load_lds_dwordx4 v132, s[24:25]
	s_mov_b32 m0, s43
	s_nop 0
	global_load_lds_dwordx4 v160, s[44:45]
	s_add_i32 m0, s43, 0x2000
	s_nop 0
	global_load_lds_dwordx4 v132, s[44:45]
	s_mov_b32 m0, s16
	s_nop 0
	global_load_lds_dwordx4 v128, s[82:83]
	s_mov_b32 m0, s17
	s_nop 0
	global_load_lds_dwordx4 v130, s[82:83]
	s_waitcnt vmcnt(8)
	s_waitcnt lgkmcnt(0)
	s_barrier
	v_mfma_f32_16x16x32_bf16 v[60:63], v[138:141], v[186:189], v[60:63]
	v_mfma_f32_16x16x32_bf16 v[56:59], v[146:149], v[186:189], v[56:59]
	v_mfma_f32_16x16x32_bf16 v[44:47], v[138:141], v[194:197], v[44:47]
	v_mfma_f32_16x16x32_bf16 v[40:43], v[146:149], v[194:197], v[40:43]
	v_mfma_f32_16x16x32_bf16 v[28:31], v[138:141], v[202:205], v[28:31]
	v_mfma_f32_16x16x32_bf16 v[24:27], v[146:149], v[202:205], v[24:27]
	v_mfma_f32_16x16x32_bf16 v[12:15], v[138:141], v[210:213], v[12:15]
	v_mfma_f32_16x16x32_bf16 v[8:11], v[146:149], v[210:213], v[8:11]
	v_mfma_f32_16x16x32_bf16 v[60:63], v[142:145], v[190:193], v[60:63]
	v_mfma_f32_16x16x32_bf16 v[56:59], v[150:153], v[190:193], v[56:59]
	v_mfma_f32_16x16x32_bf16 v[44:47], v[142:145], v[198:201], v[44:47]
	v_mfma_f32_16x16x32_bf16 v[40:43], v[150:153], v[198:201], v[40:43]
	v_mfma_f32_16x16x32_bf16 v[28:31], v[142:145], v[206:209], v[28:31]
	v_mfma_f32_16x16x32_bf16 v[24:27], v[150:153], v[206:209], v[24:27]
	v_mfma_f32_16x16x32_bf16 v[12:15], v[142:145], v[214:217], v[12:15]
	v_mfma_f32_16x16x32_bf16 v[8:11], v[150:153], v[214:217], v[8:11]
	v_mfma_f32_16x16x32_bf16 v[52:55], v[170:173], v[186:189], v[52:55]
	v_mfma_f32_16x16x32_bf16 v[48:51], v[178:181], v[186:189], v[48:51]
	v_mfma_f32_16x16x32_bf16 v[36:39], v[170:173], v[194:197], v[36:39]
	v_mfma_f32_16x16x32_bf16 v[32:35], v[178:181], v[194:197], v[32:35]
	v_mfma_f32_16x16x32_bf16 v[20:23], v[170:173], v[202:205], v[20:23]
	v_mfma_f32_16x16x32_bf16 v[16:19], v[178:181], v[202:205], v[16:19]
	v_mfma_f32_16x16x32_bf16 v[4:7], v[170:173], v[210:213], v[4:7]
	v_mfma_f32_16x16x32_bf16 v[0:3], v[178:181], v[210:213], v[0:3]
	v_mfma_f32_16x16x32_bf16 v[52:55], v[174:177], v[190:193], v[52:55]
	v_mfma_f32_16x16x32_bf16 v[48:51], v[182:185], v[190:193], v[48:51]
	v_mfma_f32_16x16x32_bf16 v[36:39], v[174:177], v[198:201], v[36:39]
	v_mfma_f32_16x16x32_bf16 v[32:35], v[182:185], v[198:201], v[32:35]
	v_mfma_f32_16x16x32_bf16 v[20:23], v[174:177], v[206:209], v[20:23]
	v_mfma_f32_16x16x32_bf16 v[16:19], v[182:185], v[206:209], v[16:19]
	v_mfma_f32_16x16x32_bf16 v[4:7], v[174:177], v[214:217], v[4:7]
	v_mfma_f32_16x16x32_bf16 v[0:3], v[182:185], v[214:217], v[0:3]
	s_barrier
; #define PG8_STAGE(bufoff, gbase, voff) do { _Pragma("unroll") for (int _i = 0; _i < 2; ++_i) \
;         __builtin_amdgcn_global_load_lds((const unsigned*)((const char*)(gbase) + (voff)[_i]), (LAS unsigned*)(lds + (bufoff) + ldsw + _i * 8192), 16, 0, 0); } while (0)
; #define PG8_LDA(dst, b, h) do { _Pragma("unroll") for (int m = 0; m < 4; ++m) _Pragma("unroll") for (int k = 0; k < 2; ++k) dst[m][k] = *(const LAS bf16x8*)(lds + PG8_SA(b, h) + aoff + m * 2048 + k * 1024); } while (0)
; #define PG8_LDB(dst, b, h) do { _Pragma("unroll") for (int n = 0; n < 2; ++n) _Pragma("unroll") for (int k = 0; k < 2; ++k) dst[n][k] = *(const LAS bf16x8*)(lds + PG8_SB(b, h) + boff + n * 2048 + k * 1024); } while (0)
; #define PG8_MMA(ai, bj, At, Bt) do { __builtin_amdgcn_s_setprio(1); _Pragma("unroll") for (int m = 0; m < 4; ++m) _Pragma("unroll") for (int n = 0; n < 2; ++n) _Pragma("unroll") for (int k = 0; k < 2; ++k) \
;         acc[ai][bj][m][n] = __builtin_amdgcn_mfma_f32_16x16x32_bf16(Bt[n][k], At[m][k], acc[ai][bj][m][n], 0, 0, 0); __builtin_amdgcn_s_setprio(0); } while (0)
; #define PG8_WAIT_V(n) asm volatile("s_waitcnt vmcnt(" #n ")" ::: "memory")
; #define PG8_WAIT_L(n) asm volatile("s_waitcnt lgkmcnt(" #n ")" ::: "memory")
; #define PG8_BAR __builtin_amdgcn_s_barrier()
; #define PG8_SCHED __builtin_amdgcn_sched_barrier(0)
; template <class Epi, class Sched, bool ALIGN_EPI = true, bool SP2 = true>
; __device__ __forceinline__ void gemm_phase(LAS unsigned char* lds, const Gemm g, const Sched& S, const Epi& E) {
;     ...
;             PG8_LDB(B0, 1, 0); PG8_LDB(B1, 1, 1); PG8_SCHED; PG8_LDA(At, 1, 0); PG8_STAGE(PG8_SA(0, 1), a2 + hstep, voffA);
;             PG8_WAIT_V(8); PG8_WAIT_L(0); PG8_BAR; PG8_MMA(0, 0, At, B0); PG8_MMA(0, 1, At, B1); PG8_BAR; PG8_SCHED;
;             PG8_LDA(At, 1, 1); PG8_STAGE(PG8_SB(1, 0), b3, voffB); PG8_STAGE(PG8_SB(1, 1), b3 + hstep, voffB); PG8_STAGE(PG8_SA(1, 0), a3, voffA);
;             PG8_WAIT_V(8); PG8_WAIT_L(0); PG8_BAR; PG8_MMA(1, 0, At, B0); PG8_MMA(1, 1, At, B1); PG8_BAR; PG8_SCHED;
;     ...
;         if constexpr (ALIGN_EPI) { if (wr == 0) PG8_BAR; }
	s_add_i32 s43, 0, 0x18000
	s_add_i32 s46, 0, 0x1c000
	v_add_u32_e32 v150, s43, v155
	v_add_u32_e32 v166, s46, v155
	ds_read_b128 v[138:141], v150
	ds_read_b128 v[142:145], v150 offset:1024
	ds_read_b128 v[146:149], v150 offset:2048
	ds_read_b128 v[150:153], v150 offset:3072
	ds_read_b128 v[170:173], v166
	ds_read_b128 v[174:177], v166 offset:1024
	ds_read_b128 v[178:181], v166 offset:2048
	ds_read_b128 v[182:185], v166 offset:3072
	s_add_u32 s44, s82, 0x80000
	s_addc_u32 s45, s83, 0
	s_mov_b32 m0, s30
	ds_read_b128 v[186:189], v157 offset:32768
	ds_read_b128 v[190:193], v157 offset:33792
	ds_read_b128 v[194:197], v157 offset:34816
	ds_read_b128 v[198:201], v157 offset:35840
	ds_read_b128 v[202:205], v157 offset:36864
	ds_read_b128 v[206:209], v157 offset:37888
	ds_read_b128 v[210:213], v157 offset:38912
	ds_read_b128 v[214:217], v157 offset:39936
	global_load_lds_dwordx4 v128, s[44:45]
	s_mov_b32 m0, s31
	s_nop 0
	global_load_lds_dwordx4 v130, s[44:45]
	s_waitcnt vmcnt(8)
	s_waitcnt lgkmcnt(0)
	s_barrier
	v_mfma_f32_16x16x32_bf16 v[124:127], v[138:141], v[186:189], v[124:127]
	v_mfma_f32_16x16x32_bf16 v[120:123], v[146:149], v[186:189], v[120:123]
	v_mfma_f32_16x16x32_bf16 v[108:111], v[138:141], v[194:197], v[108:111]
	v_mfma_f32_16x16x32_bf16 v[104:107], v[146:149], v[194:197], v[104:107]
	v_mfma_f32_16x16x32_bf16 v[92:95], v[138:141], v[202:205], v[92:95]
	v_mfma_f32_16x16x32_bf16 v[88:91], v[146:149], v[202:205], v[88:91]
	v_mfma_f32_16x16x32_bf16 v[76:79], v[138:141], v[210:213], v[76:79]
	v_mfma_f32_16x16x32_bf16 v[72:75], v[146:149], v[210:213], v[72:75]
	v_mfma_f32_16x16x32_bf16 v[124:127], v[142:145], v[190:193], v[124:127]
	v_mfma_f32_16x16x32_bf16 v[120:123], v[150:153], v[190:193], v[120:123]
	v_mfma_f32_16x16x32_bf16 v[108:111], v[142:145], v[198:201], v[108:111]
	v_mfma_f32_16x16x32_bf16 v[104:107], v[150:153], v[198:201], v[104:107]
	v_mfma_f32_16x16x32_bf16 v[92:95], v[142:145], v[206:209], v[92:95]
	v_mfma_f32_16x16x32_bf16 v[88:91], v[150:153], v[206:209], v[88:91]
	v_mfma_f32_16x16x32_bf16 v[76:79], v[142:145], v[214:217], v[76:79]
	v_mfma_f32_16x16x32_bf16 v[72:75], v[150:153], v[214:217], v[72:75]
	v_mfma_f32_16x16x32_bf16 v[116:119], v[170:173], v[186:189], v[116:119]
	v_mfma_f32_16x16x32_bf16 v[112:115], v[178:181], v[186:189], v[112:115]
	v_mfma_f32_16x16x32_bf16 v[100:103], v[170:173], v[194:197], v[100:103]
	v_mfma_f32_16x16x32_bf16 v[96:99], v[178:181], v[194:197], v[96:99]
	v_mfma_f32_16x16x32_bf16 v[84:87], v[170:173], v[202:205], v[84:87]
	v_mfma_f32_16x16x32_bf16 v[80:83], v[178:181], v[202:205], v[80:83]
	v_mfma_f32_16x16x32_bf16 v[68:71], v[170:173], v[210:213], v[68:71]
	v_mfma_f32_16x16x32_bf16 v[64:67], v[178:181], v[210:213], v[64:67]
	v_mfma_f32_16x16x32_bf16 v[116:119], v[174:177], v[190:193], v[116:119]
	v_mfma_f32_16x16x32_bf16 v[112:115], v[182:185], v[190:193], v[112:115]
	v_mfma_f32_16x16x32_bf16 v[100:103], v[174:177], v[198:201], v[100:103]
	v_mfma_f32_16x16x32_bf16 v[96:99], v[182:185], v[198:201], v[96:99]
	v_mfma_f32_16x16x32_bf16 v[84:87], v[174:177], v[206:209], v[84:87]
	v_mfma_f32_16x16x32_bf16 v[80:83], v[182:185], v[206:209], v[80:83]
	v_mfma_f32_16x16x32_bf16 v[68:71], v[174:177], v[214:217], v[68:71]
	v_mfma_f32_16x16x32_bf16 v[64:67], v[182:185], v[214:217], v[64:67]
	s_barrier
	s_add_i32 s43, s43, s41
	s_mov_b32 m0, s43
	ds_read_b128 v[186:189], v157 offset:49152
	ds_read_b128 v[190:193], v157 offset:50176
	ds_read_b128 v[194:197], v157 offset:51200
	ds_read_b128 v[198:201], v157 offset:52224
	ds_read_b128 v[202:205], v157 offset:53248
	ds_read_b128 v[206:209], v157 offset:54272
	ds_read_b128 v[210:213], v157 offset:55296
	ds_read_b128 v[214:217], v157 offset:56320
	s_add_u32 s98, s24, 0x80
	s_addc_u32 s99, s25, 0
	global_load_lds_dwordx4 v160, s[98:99]
	s_add_i32 m0, s43, 0x2000
	s_add_u32 s24, s24, 0x80080
	s_addc_u32 s25, s25, 0
	s_add_i32 s43, s46, s41
	global_load_lds_dwordx4 v132, s[98:99]
	s_mov_b32 m0, s43
	s_nop 0
	global_load_lds_dwordx4 v160, s[24:25]
	s_add_i32 m0, s43, 0x2000
	s_nop 0
	global_load_lds_dwordx4 v132, s[24:25]
	s_mov_b32 m0, s60
	s_nop 0
	s_add_u32 s98, s82, 0x80
	s_addc_u32 s99, s83, 0
	global_load_lds_dwordx4 v128, s[98:99]
	s_mov_b32 m0, s61
	s_nop 0
	global_load_lds_dwordx4 v130, s[98:99]
	s_waitcnt vmcnt(8)
	s_waitcnt lgkmcnt(0)
	s_barrier
	v_mfma_f32_16x16x32_bf16 v[60:63], v[138:141], v[186:189], v[60:63]
	v_mfma_f32_16x16x32_bf16 v[56:59], v[146:149], v[186:189], v[56:59]
	v_mfma_f32_16x16x32_bf16 v[44:47], v[138:141], v[194:197], v[44:47]
	v_mfma_f32_16x16x32_bf16 v[40:43], v[146:149], v[194:197], v[40:43]
	v_mfma_f32_16x16x32_bf16 v[28:31], v[138:141], v[202:205], v[28:31]
	v_mfma_f32_16x16x32_bf16 v[24:27], v[146:149], v[202:205], v[24:27]
	v_mfma_f32_16x16x32_bf16 v[12:15], v[138:141], v[210:213], v[12:15]
	v_mfma_f32_16x16x32_bf16 v[8:11], v[146:149], v[210:213], v[8:11]
	v_mfma_f32_16x16x32_bf16 v[60:63], v[142:145], v[190:193], v[60:63]
	v_mfma_f32_16x16x32_bf16 v[56:59], v[150:153], v[190:193], v[56:59]
	v_mfma_f32_16x16x32_bf16 v[44:47], v[142:145], v[198:201], v[44:47]
	v_mfma_f32_16x16x32_bf16 v[40:43], v[150:153], v[198:201], v[40:43]
	v_mfma_f32_16x16x32_bf16 v[28:31], v[142:145], v[206:209], v[28:31]
	v_mfma_f32_16x16x32_bf16 v[24:27], v[150:153], v[206:209], v[24:27]
	v_mfma_f32_16x16x32_bf16 v[12:15], v[142:145], v[214:217], v[12:15]
	v_mfma_f32_16x16x32_bf16 v[8:11], v[150:153], v[214:217], v[8:11]
	v_mfma_f32_16x16x32_bf16 v[52:55], v[170:173], v[186:189], v[52:55]
	v_mfma_f32_16x16x32_bf16 v[48:51], v[178:181], v[186:189], v[48:51]
	v_mfma_f32_16x16x32_bf16 v[36:39], v[170:173], v[194:197], v[36:39]
	v_mfma_f32_16x16x32_bf16 v[32:35], v[178:181], v[194:197], v[32:35]
	v_mfma_f32_16x16x32_bf16 v[20:23], v[170:173], v[202:205], v[20:23]
	v_mfma_f32_16x16x32_bf16 v[16:19], v[178:181], v[202:205], v[16:19]
	v_mfma_f32_16x16x32_bf16 v[4:7], v[170:173], v[210:213], v[4:7]
	v_mfma_f32_16x16x32_bf16 v[0:3], v[178:181], v[210:213], v[0:3]
	v_mfma_f32_16x16x32_bf16 v[52:55], v[174:177], v[190:193], v[52:55]
	v_mfma_f32_16x16x32_bf16 v[48:51], v[182:185], v[190:193], v[48:51]
	v_mfma_f32_16x16x32_bf16 v[36:39], v[174:177], v[198:201], v[36:39]
	v_mfma_f32_16x16x32_bf16 v[32:35], v[182:185], v[198:201], v[32:35]
	v_mfma_f32_16x16x32_bf16 v[20:23], v[174:177], v[206:209], v[20:23]
	v_mfma_f32_16x16x32_bf16 v[16:19], v[182:185], v[206:209], v[16:19]
	v_mfma_f32_16x16x32_bf16 v[4:7], v[174:177], v[214:217], v[4:7]
	v_mfma_f32_16x16x32_bf16 v[0:3], v[182:185], v[214:217], v[0:3]
	s_barrier
	s_add_i32 s42, s42, 2
	s_add_u32 s62, s62, 0x100
	s_addc_u32 s63, s63, 0
	s_add_u32 s18, s18, 0x100
	s_addc_u32 s19, s19, 0
	s_cmp_gt_u32 s42, 29
	s_cbranch_scc0 .LBB0_354
	s_setprio 0
	s_and_b64 vcc, exec, s[14:15]
	s_cbranch_vccz .LBB0_357
	s_barrier

; #define PG8_STAGE(bufoff, gbase, voff) do { _Pragma("unroll") for (int _i = 0; _i < 2; ++_i) \
;         __builtin_amdgcn_global_load_lds((const unsigned*)((const char*)(gbase) + (voff)[_i]), (LAS unsigned*)(lds + (bufoff) + ldsw + _i * 8192), 16, 0, 0); } while (0)
; #define PG8_LDA(dst, b, h) do { _Pragma("unroll") for (int m = 0; m < 4; ++m) _Pragma("unroll") for (int k = 0; k < 2; ++k) dst[m][k] = *(const LAS bf16x8*)(lds + PG8_SA(b, h) + aoff + m * 2048 + k * 1024); } while (0)
; #define PG8_LDB(dst, b, h) do { _Pragma("unroll") for (int n = 0; n < 2; ++n) _Pragma("unroll") for (int k = 0; k < 2; ++k) dst[n][k] = *(const LAS bf16x8*)(lds + PG8_SB(b, h) + boff + n * 2048 + k * 1024); } while (0)
; #define PG8_MMA(ai, bj, At, Bt) do { __builtin_amdgcn_s_setprio(1); _Pragma("unroll") for (int m = 0; m < 4; ++m) _Pragma("unroll") for (int n = 0; n < 2; ++n) _Pragma("unroll") for (int k = 0; k < 2; ++k) \
;         acc[ai][bj][m][n] = __builtin_amdgcn_mfma_f32_16x16x32_bf16(Bt[n][k], At[m][k], acc[ai][bj][m][n], 0, 0, 0); __builtin_amdgcn_s_setprio(0); } while (0)
; #define PG8_WAIT_V(n) asm volatile("s_waitcnt vmcnt(" #n ")" ::: "memory")
; #define PG8_WAIT_L(n) asm volatile("s_waitcnt lgkmcnt(" #n ")" ::: "memory")
; #define PG8_BAR __builtin_amdgcn_s_barrier()
; #define PG8_SCHED __builtin_amdgcn_sched_barrier(0)
; template <class Epi, class Sched, bool ALIGN_EPI = true, bool SP2 = true>
; __device__ __forceinline__ void gemm_phase(LAS unsigned char* lds, const Gemm g, const Sched& S, const Epi& E) {
;     ...
;             const char* a1 = cA + (size_t)(t + 1) * kstep;
;             const char* a2 = last ? nA : cA + (size_t)(t + 2) * kstep; const char* b2 = last ? nB : cB + (size_t)(t + 2) * kstep;
;             const char* a3 = a2 + kstep; const char* b3 = b2 + kstep;
;             if constexpr (SP2) {
;             PG8_LDB(B0, 0, 0); PG8_LDB(B1, 0, 1); PG8_SCHED; PG8_LDA(At, 0, 0); PG8_STAGE(PG8_SA(1, 1), a1 + hstep, voffA);
;             PG8_WAIT_V(8); PG8_WAIT_L(0); PG8_BAR; PG8_MMA(0, 0, At, B0); PG8_MMA(0, 1, At, B1); PG8_BAR; PG8_SCHED;
;             PG8_LDA(At, 0, 1); PG8_STAGE(PG8_SB(0, 0), b2, voffB); PG8_STAGE(PG8_SB(0, 1), b2 + hstep, voffB); PG8_STAGE(PG8_SA(0, 0), a2, voffA);
;             PG8_WAIT_V(8); PG8_WAIT_L(0); PG8_BAR; PG8_MMA(1, 0, At, B0); PG8_MMA(1, 1, At, B1); PG8_BAR; PG8_SCHED;
.Lprio_skip_566:
.LBB0_566:
	s_add_u32 s54, s52, 0x100
	s_addc_u32 s55, s53, 0
	s_add_i32 s46, 0, 0x10000
	s_cmpk_eq_i32 s89, 0x54
	s_cselect_b32 s61, s9, s55
	s_cselect_b32 s60, s8, s54
	v_add_u32_e32 v142, s46, v145
	s_cselect_b32 s25, s31, s3
	s_cselect_b32 s24, s30, s2
	s_add_i32 s47, 0, 0x14000
	ds_read_b128 v[138:141], v142
	ds_read_b128 v[148:151], v142 offset:1024
	ds_read_b128 v[152:155], v142 offset:2048
	ds_read_b128 v[156:159], v142 offset:3072
	v_add_u32_e32 v142, s47, v145
	ds_read_b128 v[170:173], v142
	ds_read_b128 v[174:177], v142 offset:1024
	ds_read_b128 v[178:181], v142 offset:2048
	ds_read_b128 v[182:185], v142 offset:3072
	s_add_i32 m0, s63, 0xc000
	ds_read_b128 v[186:189], v147
	ds_read_b128 v[190:193], v147 offset:1024
	ds_read_b128 v[194:197], v147 offset:2048
	ds_read_b128 v[198:201], v147 offset:3072
	ds_read_b128 v[202:205], v147 offset:4096
	ds_read_b128 v[206:209], v147 offset:5120
	ds_read_b128 v[210:213], v147 offset:6144
	ds_read_b128 v[214:217], v147 offset:7168
	global_load_lds_dwordx4 v134, s[52:53]
	s_add_i32 m0, s63, 0xe000
	s_nop 0
	global_load_lds_dwordx4 v136, s[52:53]
	s_waitcnt vmcnt(8)
	s_waitcnt lgkmcnt(0)
	s_barrier
	v_mfma_f32_16x16x32_bf16 v[124:127], v[138:141], v[186:189], v[124:127]
	v_mfma_f32_16x16x32_bf16 v[120:123], v[152:155], v[186:189], v[120:123]
	v_mfma_f32_16x16x32_bf16 v[108:111], v[138:141], v[194:197], v[108:111]
	v_mfma_f32_16x16x32_bf16 v[104:107], v[152:155], v[194:197], v[104:107]
	v_mfma_f32_16x16x32_bf16 v[92:95], v[138:141], v[202:205], v[92:95]
	v_mfma_f32_16x16x32_bf16 v[88:91], v[152:155], v[202:205], v[88:91]
	v_mfma_f32_16x16x32_bf16 v[76:79], v[138:141], v[210:213], v[76:79]
	v_mfma_f32_16x16x32_bf16 v[72:75], v[152:155], v[210:213], v[72:75]
	v_mfma_f32_16x16x32_bf16 v[124:127], v[148:151], v[190:193], v[124:127]
	v_mfma_f32_16x16x32_bf16 v[120:123], v[156:159], v[190:193], v[120:123]
	v_mfma_f32_16x16x32_bf16 v[108:111], v[148:151], v[198:201], v[108:111]
	v_mfma_f32_16x16x32_bf16 v[104:107], v[156:159], v[198:201], v[104:107]
	v_mfma_f32_16x16x32_bf16 v[92:95], v[148:151], v[206:209], v[92:95]
	v_mfma_f32_16x16x32_bf16 v[88:91], v[156:159], v[206:209], v[88:91]
	v_mfma_f32_16x16x32_bf16 v[76:79], v[148:151], v[214:217], v[76:79]
	v_mfma_f32_16x16x32_bf16 v[72:75], v[156:159], v[214:217], v[72:75]
	v_mfma_f32_16x16x32_bf16 v[116:119], v[170:173], v[186:189], v[116:119]
	v_mfma_f32_16x16x32_bf16 v[112:115], v[178:181], v[186:189], v[112:115]
	v_mfma_f32_16x16x32_bf16 v[100:103], v[170:173], v[194:197], v[100:103]
	v_mfma_f32_16x16x32_bf16 v[96:99], v[178:181], v[194:197], v[96:99]
	v_mfma_f32_16x16x32_bf16 v[84:87], v[170:173], v[202:205], v[84:87]
	v_mfma_f32_16x16x32_bf16 v[80:83], v[178:181], v[202:205], v[80:83]
	v_mfma_f32_16x16x32_bf16 v[68:71], v[170:173], v[210:213], v[68:71]
	v_mfma_f32_16x16x32_bf16 v[64:67], v[178:181], v[210:213], v[64:67]
	v_mfma_f32_16x16x32_bf16 v[116:119], v[174:177], v[190:193], v[116:119]
	v_mfma_f32_16x16x32_bf16 v[112:115], v[182:185], v[190:193], v[112:115]
	v_mfma_f32_16x16x32_bf16 v[100:103], v[174:177], v[198:201], v[100:103]
	v_mfma_f32_16x16x32_bf16 v[96:99], v[182:185], v[198:201], v[96:99]
	v_mfma_f32_16x16x32_bf16 v[84:87], v[174:177], v[206:209], v[84:87]
	v_mfma_f32_16x16x32_bf16 v[80:83], v[182:185], v[206:209], v[80:83]
	v_mfma_f32_16x16x32_bf16 v[68:71], v[174:177], v[214:217], v[68:71]
	v_mfma_f32_16x16x32_bf16 v[64:67], v[182:185], v[214:217], v[64:67]
	s_barrier
	s_add_i32 s46, s46, s62
	s_mov_b32 m0, s46
	ds_read_b128 v[186:189], v147 offset:16384
	ds_read_b128 v[190:193], v147 offset:17408
	ds_read_b128 v[194:197], v147 offset:18432
	ds_read_b128 v[198:201], v147 offset:19456
	ds_read_b128 v[202:205], v147 offset:20480
	ds_read_b128 v[206:209], v147 offset:21504
	ds_read_b128 v[210:213], v147 offset:22528
	ds_read_b128 v[214:217], v147 offset:23552
	global_load_lds_dwordx4 v160, s[24:25]
	s_add_i32 m0, s46, 0x2000
	s_add_u32 s52, s24, 0x160000
	s_addc_u32 s53, s25, 0
	s_add_i32 s46, s47, s62
	global_load_lds_dwordx4 v132, s[24:25]
	s_mov_b32 m0, s46
	s_nop 0
	global_load_lds_dwordx4 v160, s[52:53]
	s_add_i32 m0, s46, 0x2000
	s_nop 0
	global_load_lds_dwordx4 v132, s[52:53]
	s_mov_b32 m0, s63
	s_nop 0
	global_load_lds_dwordx4 v128, s[60:61]
	s_mov_b32 m0, s66
	s_nop 0
	global_load_lds_dwordx4 v130, s[60:61]
	s_waitcnt vmcnt(8)
	s_waitcnt lgkmcnt(0)
	s_barrier
	v_mfma_f32_16x16x32_bf16 v[60:63], v[138:141], v[186:189], v[60:63]
	v_mfma_f32_16x16x32_bf16 v[56:59], v[152:155], v[186:189], v[56:59]
	v_mfma_f32_16x16x32_bf16 v[44:47], v[138:141], v[194:197], v[44:47]
	v_mfma_f32_16x16x32_bf16 v[40:43], v[152:155], v[194:197], v[40:43]
	v_mfma_f32_16x16x32_bf16 v[28:31], v[138:141], v[202:205], v[28:31]
	v_mfma_f32_16x16x32_bf16 v[24:27], v[152:155], v[202:205], v[24:27]
	v_mfma_f32_16x16x32_bf16 v[12:15], v[138:141], v[210:213], v[12:15]
	v_mfma_f32_16x16x32_bf16 v[8:11], v[152:155], v[210:213], v[8:11]
	v_mfma_f32_16x16x32_bf16 v[60:63], v[148:151], v[190:193], v[60:63]
	v_mfma_f32_16x16x32_bf16 v[56:59], v[156:159], v[190:193], v[56:59]
	v_mfma_f32_16x16x32_bf16 v[44:47], v[148:151], v[198:201], v[44:47]
	v_mfma_f32_16x16x32_bf16 v[40:43], v[156:159], v[198:201], v[40:43]
	v_mfma_f32_16x16x32_bf16 v[28:31], v[148:151], v[206:209], v[28:31]
	v_mfma_f32_16x16x32_bf16 v[24:27], v[156:159], v[206:209], v[24:27]
	v_mfma_f32_16x16x32_bf16 v[12:15], v[148:151], v[214:217], v[12:15]
	v_mfma_f32_16x16x32_bf16 v[8:11], v[156:159], v[214:217], v[8:11]
	v_mfma_f32_16x16x32_bf16 v[52:55], v[170:173], v[186:189], v[52:55]
	v_mfma_f32_16x16x32_bf16 v[48:51], v[178:181], v[186:189], v[48:51]
	v_mfma_f32_16x16x32_bf16 v[36:39], v[170:173], v[194:197], v[36:39]
	v_mfma_f32_16x16x32_bf16 v[32:35], v[178:181], v[194:197], v[32:35]
	v_mfma_f32_16x16x32_bf16 v[20:23], v[170:173], v[202:205], v[20:23]
	v_mfma_f32_16x16x32_bf16 v[16:19], v[178:181], v[202:205], v[16:19]
	v_mfma_f32_16x16x32_bf16 v[4:7], v[170:173], v[210:213], v[4:7]
	v_mfma_f32_16x16x32_bf16 v[0:3], v[178:181], v[210:213], v[0:3]
	v_mfma_f32_16x16x32_bf16 v[52:55], v[174:177], v[190:193], v[52:55]
	v_mfma_f32_16x16x32_bf16 v[48:51], v[182:185], v[190:193], v[48:51]
	v_mfma_f32_16x16x32_bf16 v[36:39], v[174:177], v[198:201], v[36:39]
	v_mfma_f32_16x16x32_bf16 v[32:35], v[182:185], v[198:201], v[32:35]
	v_mfma_f32_16x16x32_bf16 v[20:23], v[174:177], v[206:209], v[20:23]
	v_mfma_f32_16x16x32_bf16 v[16:19], v[182:185], v[206:209], v[16:19]
	v_mfma_f32_16x16x32_bf16 v[4:7], v[174:177], v[214:217], v[4:7]
	v_mfma_f32_16x16x32_bf16 v[0:3], v[182:185], v[214:217], v[0:3]
	s_barrier
; #define PG8_STAGE(bufoff, gbase, voff) do { _Pragma("unroll") for (int _i = 0; _i < 2; ++_i) \
;         __builtin_amdgcn_global_load_lds((const unsigned*)((const char*)(gbase) + (voff)[_i]), (LAS unsigned*)(lds + (bufoff) + ldsw + _i * 8192), 16, 0, 0); } while (0)
; #define PG8_LDA(dst, b, h) do { _Pragma("unroll") for (int m = 0; m < 4; ++m) _Pragma("unroll") for (int k = 0; k < 2; ++k) dst[m][k] = *(const LAS bf16x8*)(lds + PG8_SA(b, h) + aoff + m * 2048 + k * 1024); } while (0)
; #define PG8_LDB(dst, b, h) do { _Pragma("unroll") for (int n = 0; n < 2; ++n) _Pragma("unroll") for (int k = 0; k < 2; ++k) dst[n][k] = *(const LAS bf16x8*)(lds + PG8_SB(b, h) + boff + n * 2048 + k * 1024); } while (0)
; #define PG8_MMA(ai, bj, At, Bt) do { __builtin_amdgcn_s_setprio(1); _Pragma("unroll") for (int m = 0; m < 4; ++m) _Pragma("unroll") for (int n = 0; n < 2; ++n) _Pragma("unroll") for (int k = 0; k < 2; ++k) \
;         acc[ai][bj][m][n] = __builtin_amdgcn_mfma_f32_16x16x32_bf16(Bt[n][k], At[m][k], acc[ai][bj][m][n], 0, 0, 0); __builtin_amdgcn_s_setprio(0); } while (0)
; #define PG8_WAIT_V(n) asm volatile("s_waitcnt vmcnt(" #n ")" ::: "memory")
; #define PG8_WAIT_L(n) asm volatile("s_waitcnt lgkmcnt(" #n ")" ::: "memory")
; #define PG8_BAR __builtin_amdgcn_s_barrier()
; #define PG8_SCHED __builtin_amdgcn_sched_barrier(0)
; template <class Epi, class Sched, bool ALIGN_EPI = true, bool SP2 = true>
; __device__ __forceinline__ void gemm_phase(LAS unsigned char* lds, const Gemm g, const Sched& S, const Epi& E) {
;     ...
;             PG8_LDB(B0, 1, 0); PG8_LDB(B1, 1, 1); PG8_SCHED; PG8_LDA(At, 1, 0); PG8_STAGE(PG8_SA(0, 1), a2 + hstep, voffA);
;             PG8_WAIT_V(8); PG8_WAIT_L(0); PG8_BAR; PG8_MMA(0, 0, At, B0); PG8_MMA(0, 1, At, B1); PG8_BAR; PG8_SCHED;
;             PG8_LDA(At, 1, 1); PG8_STAGE(PG8_SB(1, 0), b3, voffB); PG8_STAGE(PG8_SB(1, 1), b3 + hstep, voffB); PG8_STAGE(PG8_SA(1, 0), a3, voffA);
;             PG8_WAIT_V(8); PG8_WAIT_L(0); PG8_BAR; PG8_MMA(1, 0, At, B0); PG8_MMA(1, 1, At, B1); PG8_BAR; PG8_SCHED;
;     ...
;         if constexpr (ALIGN_EPI) { if (wr == 0) PG8_BAR; }
	s_add_i32 s46, 0, 0x18000
	s_add_i32 s47, 0, 0x1c000
	v_add_u32_e32 v156, s46, v145
	v_add_u32_e32 v166, s47, v145
	ds_read_b128 v[138:141], v156
	ds_read_b128 v[148:151], v156 offset:1024
	ds_read_b128 v[152:155], v156 offset:2048
	ds_read_b128 v[156:159], v156 offset:3072
	ds_read_b128 v[170:173], v166
	ds_read_b128 v[174:177], v166 offset:1024
	ds_read_b128 v[178:181], v166 offset:2048
	ds_read_b128 v[182:185], v166 offset:3072
	s_add_u32 s52, s60, 0x160000
	s_addc_u32 s53, s61, 0
	s_mov_b32 m0, s67
	ds_read_b128 v[186:189], v147 offset:32768
	ds_read_b128 v[190:193], v147 offset:33792
	ds_read_b128 v[194:197], v147 offset:34816
	ds_read_b128 v[198:201], v147 offset:35840
	ds_read_b128 v[202:205], v147 offset:36864
	ds_read_b128 v[206:209], v147 offset:37888
	ds_read_b128 v[210:213], v147 offset:38912
	ds_read_b128 v[214:217], v147 offset:39936
	global_load_lds_dwordx4 v128, s[52:53]
	s_mov_b32 m0, s72
	s_nop 0
	global_load_lds_dwordx4 v130, s[52:53]
	s_waitcnt vmcnt(8)
	s_waitcnt lgkmcnt(0)
	s_barrier
	v_mfma_f32_16x16x32_bf16 v[124:127], v[138:141], v[186:189], v[124:127]
	v_mfma_f32_16x16x32_bf16 v[120:123], v[152:155], v[186:189], v[120:123]
	v_mfma_f32_16x16x32_bf16 v[108:111], v[138:141], v[194:197], v[108:111]
	v_mfma_f32_16x16x32_bf16 v[104:107], v[152:155], v[194:197], v[104:107]
	v_mfma_f32_16x16x32_bf16 v[92:95], v[138:141], v[202:205], v[92:95]
	v_mfma_f32_16x16x32_bf16 v[88:91], v[152:155], v[202:205], v[88:91]
	v_mfma_f32_16x16x32_bf16 v[76:79], v[138:141], v[210:213], v[76:79]
	v_mfma_f32_16x16x32_bf16 v[72:75], v[152:155], v[210:213], v[72:75]
	v_mfma_f32_16x16x32_bf16 v[124:127], v[148:151], v[190:193], v[124:127]
	v_mfma_f32_16x16x32_bf16 v[120:123], v[156:159], v[190:193], v[120:123]
	v_mfma_f32_16x16x32_bf16 v[108:111], v[148:151], v[198:201], v[108:111]
	v_mfma_f32_16x16x32_bf16 v[104:107], v[156:159], v[198:201], v[104:107]
	v_mfma_f32_16x16x32_bf16 v[92:95], v[148:151], v[206:209], v[92:95]
	v_mfma_f32_16x16x32_bf16 v[88:91], v[156:159], v[206:209], v[88:91]
	v_mfma_f32_16x16x32_bf16 v[76:79], v[148:151], v[214:217], v[76:79]
	v_mfma_f32_16x16x32_bf16 v[72:75], v[156:159], v[214:217], v[72:75]
	v_mfma_f32_16x16x32_bf16 v[116:119], v[170:173], v[186:189], v[116:119]
	v_mfma_f32_16x16x32_bf16 v[112:115], v[178:181], v[186:189], v[112:115]
	v_mfma_f32_16x16x32_bf16 v[100:103], v[170:173], v[194:197], v[100:103]
	v_mfma_f32_16x16x32_bf16 v[96:99], v[178:181], v[194:197], v[96:99]
	v_mfma_f32_16x16x32_bf16 v[84:87], v[170:173], v[202:205], v[84:87]
	v_mfma_f32_16x16x32_bf16 v[80:83], v[178:181], v[202:205], v[80:83]
	v_mfma_f32_16x16x32_bf16 v[68:71], v[170:173], v[210:213], v[68:71]
	v_mfma_f32_16x16x32_bf16 v[64:67], v[178:181], v[210:213], v[64:67]
	v_mfma_f32_16x16x32_bf16 v[116:119], v[174:177], v[190:193], v[116:119]
	v_mfma_f32_16x16x32_bf16 v[112:115], v[182:185], v[190:193], v[112:115]
	v_mfma_f32_16x16x32_bf16 v[100:103], v[174:177], v[198:201], v[100:103]
	v_mfma_f32_16x16x32_bf16 v[96:99], v[182:185], v[198:201], v[96:99]
	v_mfma_f32_16x16x32_bf16 v[84:87], v[174:177], v[206:209], v[84:87]
	v_mfma_f32_16x16x32_bf16 v[80:83], v[182:185], v[206:209], v[80:83]
	v_mfma_f32_16x16x32_bf16 v[68:71], v[174:177], v[214:217], v[68:71]
	v_mfma_f32_16x16x32_bf16 v[64:67], v[182:185], v[214:217], v[64:67]
	s_barrier
	s_add_i32 s46, s46, s62
	s_mov_b32 m0, s46
	ds_read_b128 v[186:189], v147 offset:49152
	ds_read_b128 v[190:193], v147 offset:50176
	ds_read_b128 v[194:197], v147 offset:51200
	ds_read_b128 v[198:201], v147 offset:52224
	ds_read_b128 v[202:205], v147 offset:53248
	ds_read_b128 v[206:209], v147 offset:54272
	ds_read_b128 v[210:213], v147 offset:55296
	ds_read_b128 v[214:217], v147 offset:56320
	s_add_u32 s98, s24, 0x80
	s_addc_u32 s99, s25, 0
	global_load_lds_dwordx4 v160, s[98:99]
	s_add_i32 m0, s46, 0x2000
	s_add_u32 s24, s24, 0x160080
	s_addc_u32 s25, s25, 0
	s_add_i32 s46, s47, s62
	global_load_lds_dwordx4 v132, s[98:99]
	s_mov_b32 m0, s46
	s_nop 0
	global_load_lds_dwordx4 v160, s[24:25]
	s_add_i32 m0, s46, 0x2000
	s_nop 0
	global_load_lds_dwordx4 v132, s[24:25]
	s_mov_b32 m0, s73
	s_nop 0
	s_add_u32 s98, s52, 0xffea0080
	s_addc_u32 s99, s53, -1
	global_load_lds_dwordx4 v128, s[98:99]
	s_mov_b32 m0, s79
	s_nop 0
	global_load_lds_dwordx4 v130, s[98:99]
	s_waitcnt vmcnt(8)
	s_waitcnt lgkmcnt(0)
	s_barrier
	v_mfma_f32_16x16x32_bf16 v[60:63], v[138:141], v[186:189], v[60:63]
	v_mfma_f32_16x16x32_bf16 v[56:59], v[152:155], v[186:189], v[56:59]
	v_mfma_f32_16x16x32_bf16 v[44:47], v[138:141], v[194:197], v[44:47]
	v_mfma_f32_16x16x32_bf16 v[40:43], v[152:155], v[194:197], v[40:43]
	v_mfma_f32_16x16x32_bf16 v[28:31], v[138:141], v[202:205], v[28:31]
	v_mfma_f32_16x16x32_bf16 v[24:27], v[152:155], v[202:205], v[24:27]
	v_mfma_f32_16x16x32_bf16 v[12:15], v[138:141], v[210:213], v[12:15]
	v_mfma_f32_16x16x32_bf16 v[8:11], v[152:155], v[210:213], v[8:11]
	v_mfma_f32_16x16x32_bf16 v[60:63], v[148:151], v[190:193], v[60:63]
	v_mfma_f32_16x16x32_bf16 v[56:59], v[156:159], v[190:193], v[56:59]
	v_mfma_f32_16x16x32_bf16 v[44:47], v[148:151], v[198:201], v[44:47]
	v_mfma_f32_16x16x32_bf16 v[40:43], v[156:159], v[198:201], v[40:43]
	v_mfma_f32_16x16x32_bf16 v[28:31], v[148:151], v[206:209], v[28:31]
	v_mfma_f32_16x16x32_bf16 v[24:27], v[156:159], v[206:209], v[24:27]
	v_mfma_f32_16x16x32_bf16 v[12:15], v[148:151], v[214:217], v[12:15]
	v_mfma_f32_16x16x32_bf16 v[8:11], v[156:159], v[214:217], v[8:11]
	v_mfma_f32_16x16x32_bf16 v[52:55], v[170:173], v[186:189], v[52:55]
	v_mfma_f32_16x16x32_bf16 v[48:51], v[178:181], v[186:189], v[48:51]
	v_mfma_f32_16x16x32_bf16 v[36:39], v[170:173], v[194:197], v[36:39]
	v_mfma_f32_16x16x32_bf16 v[32:35], v[178:181], v[194:197], v[32:35]
	v_mfma_f32_16x16x32_bf16 v[20:23], v[170:173], v[202:205], v[20:23]
	v_mfma_f32_16x16x32_bf16 v[16:19], v[178:181], v[202:205], v[16:19]
	v_mfma_f32_16x16x32_bf16 v[4:7], v[170:173], v[210:213], v[4:7]
	v_mfma_f32_16x16x32_bf16 v[0:3], v[178:181], v[210:213], v[0:3]
	v_mfma_f32_16x16x32_bf16 v[52:55], v[174:177], v[190:193], v[52:55]
	v_mfma_f32_16x16x32_bf16 v[48:51], v[182:185], v[190:193], v[48:51]
	v_mfma_f32_16x16x32_bf16 v[36:39], v[174:177], v[198:201], v[36:39]
	v_mfma_f32_16x16x32_bf16 v[32:35], v[182:185], v[198:201], v[32:35]
	v_mfma_f32_16x16x32_bf16 v[20:23], v[174:177], v[206:209], v[20:23]
	v_mfma_f32_16x16x32_bf16 v[16:19], v[182:185], v[206:209], v[16:19]
	v_mfma_f32_16x16x32_bf16 v[4:7], v[174:177], v[214:217], v[4:7]
	v_mfma_f32_16x16x32_bf16 v[0:3], v[182:185], v[214:217], v[0:3]
	s_barrier
	s_add_i32 s89, s89, 2
	s_add_u32 s2, s2, 0x100
	s_addc_u32 s3, s3, 0
	s_cmpk_gt_u32 s89, 0x55
	s_mov_b64 s[52:53], s[54:55]
	s_cbranch_scc0 .LBB0_566
	s_setprio 0
	s_and_b64 vcc, exec, s[18:19]
	s_cbranch_vccz .LBB0_569
	s_barrier

; #define PG8_STAGE(bufoff, gbase, voff) do { _Pragma("unroll") for (int _i = 0; _i < 2; ++_i) \
;         __builtin_amdgcn_global_load_lds((const unsigned*)((const char*)(gbase) + (voff)[_i]), (LAS unsigned*)(lds + (bufoff) + ldsw + _i * 8192), 16, 0, 0); } while (0)
; #define PG8_LDA(dst, b, h) do { _Pragma("unroll") for (int m = 0; m < 4; ++m) _Pragma("unroll") for (int k = 0; k < 2; ++k) dst[m][k] = *(const LAS bf16x8*)(lds + PG8_SA(b, h) + aoff + m * 2048 + k * 1024); } while (0)
; #define PG8_LDB(dst, b, h) do { _Pragma("unroll") for (int n = 0; n < 2; ++n) _Pragma("unroll") for (int k = 0; k < 2; ++k) dst[n][k] = *(const LAS bf16x8*)(lds + PG8_SB(b, h) + boff + n * 2048 + k * 1024); } while (0)
; #define PG8_MMA(ai, bj, At, Bt) do { __builtin_amdgcn_s_setprio(1); _Pragma("unroll") for (int m = 0; m < 4; ++m) _Pragma("unroll") for (int n = 0; n < 2; ++n) _Pragma("unroll") for (int k = 0; k < 2; ++k) \
;         acc[ai][bj][m][n] = __builtin_amdgcn_mfma_f32_16x16x32_bf16(Bt[n][k], At[m][k], acc[ai][bj][m][n], 0, 0, 0); __builtin_amdgcn_s_setprio(0); } while (0)
; #define PG8_WAIT_V(n) asm volatile("s_waitcnt vmcnt(" #n ")" ::: "memory")
; #define PG8_WAIT_L(n) asm volatile("s_waitcnt lgkmcnt(" #n ")" ::: "memory")
; #define PG8_BAR __builtin_amdgcn_s_barrier()
; #define PG8_SCHED __builtin_amdgcn_sched_barrier(0)
; template <class Epi, class Sched, bool ALIGN_EPI = true, bool SP2 = true>
; __device__ __forceinline__ void gemm_phase(LAS unsigned char* lds, const Gemm g, const Sched& S, const Epi& E) {
;     ...
;             const char* a1 = cA + (size_t)(t + 1) * kstep;
;             const char* a2 = last ? nA : cA + (size_t)(t + 2) * kstep; const char* b2 = last ? nB : cB + (size_t)(t + 2) * kstep;
;             const char* a3 = a2 + kstep; const char* b3 = b2 + kstep;
;             if constexpr (SP2) {
;             PG8_LDB(B0, 0, 0); PG8_LDB(B1, 0, 1); PG8_SCHED; PG8_LDA(At, 0, 0); PG8_STAGE(PG8_SA(1, 1), a1 + hstep, voffA);
;             PG8_WAIT_V(8); PG8_WAIT_L(0); PG8_BAR; PG8_MMA(0, 0, At, B0); PG8_MMA(0, 1, At, B1); PG8_BAR; PG8_SCHED;
;             PG8_LDA(At, 0, 1); PG8_STAGE(PG8_SB(0, 0), b2, voffB); PG8_STAGE(PG8_SB(0, 1), b2 + hstep, voffB); PG8_STAGE(PG8_SA(0, 0), a2, voffA);
;             PG8_WAIT_V(8); PG8_WAIT_L(0); PG8_BAR; PG8_MMA(1, 0, At, B0); PG8_MMA(1, 1, At, B1); PG8_BAR; PG8_SCHED;
.Lprio_skip_600:
.LBB0_600:
	s_add_u32 s24, s54, 0xfff80080
	s_addc_u32 s25, s55, -1
	s_add_i32 s46, 0, 0x10000
	s_cmp_eq_u32 s83, 28
	s_cselect_b32 s61, s2, s25
	s_cselect_b32 s60, s3, s24
	v_add_u32_e32 v142, s46, v145
	s_cselect_b32 s25, s15, s82
	s_cselect_b32 s24, s17, s79
	s_add_i32 s47, 0, 0x14000
	ds_read_b128 v[138:141], v142
	ds_read_b128 v[148:151], v142 offset:1024
	ds_read_b128 v[152:155], v142 offset:2048
	ds_read_b128 v[156:159], v142 offset:3072
	v_add_u32_e32 v142, s47, v145
	ds_read_b128 v[170:173], v142
	ds_read_b128 v[174:177], v142 offset:1024
	ds_read_b128 v[178:181], v142 offset:2048
	ds_read_b128 v[182:185], v142 offset:3072
	s_add_i32 m0, s43, 0xc000
	ds_read_b128 v[186:189], v147
	ds_read_b128 v[190:193], v147 offset:1024
	ds_read_b128 v[194:197], v147 offset:2048
	ds_read_b128 v[198:201], v147 offset:3072
	ds_read_b128 v[202:205], v147 offset:4096
	ds_read_b128 v[206:209], v147 offset:5120
	ds_read_b128 v[210:213], v147 offset:6144
	ds_read_b128 v[214:217], v147 offset:7168
	global_load_lds_dwordx4 v134, s[54:55]
	s_add_i32 m0, s43, 0xe000
	s_nop 0
	global_load_lds_dwordx4 v136, s[54:55]
	s_waitcnt vmcnt(8)
	s_waitcnt lgkmcnt(0)
	s_barrier
	v_mfma_f32_16x16x32_bf16 v[124:127], v[138:141], v[186:189], v[124:127]
	v_mfma_f32_16x16x32_bf16 v[116:119], v[152:155], v[186:189], v[116:119]
	v_mfma_f32_16x16x32_bf16 v[108:111], v[138:141], v[194:197], v[108:111]
	v_mfma_f32_16x16x32_bf16 v[100:103], v[152:155], v[194:197], v[100:103]
	v_mfma_f32_16x16x32_bf16 v[92:95], v[138:141], v[202:205], v[92:95]
	v_mfma_f32_16x16x32_bf16 v[84:87], v[152:155], v[202:205], v[84:87]
	v_mfma_f32_16x16x32_bf16 v[76:79], v[138:141], v[210:213], v[76:79]
	v_mfma_f32_16x16x32_bf16 v[68:71], v[152:155], v[210:213], v[68:71]
	v_mfma_f32_16x16x32_bf16 v[124:127], v[148:151], v[190:193], v[124:127]
	v_mfma_f32_16x16x32_bf16 v[116:119], v[156:159], v[190:193], v[116:119]
	v_mfma_f32_16x16x32_bf16 v[108:111], v[148:151], v[198:201], v[108:111]
	v_mfma_f32_16x16x32_bf16 v[100:103], v[156:159], v[198:201], v[100:103]
	v_mfma_f32_16x16x32_bf16 v[92:95], v[148:151], v[206:209], v[92:95]
	v_mfma_f32_16x16x32_bf16 v[84:87], v[156:159], v[206:209], v[84:87]
	v_mfma_f32_16x16x32_bf16 v[76:79], v[148:151], v[214:217], v[76:79]
	v_mfma_f32_16x16x32_bf16 v[68:71], v[156:159], v[214:217], v[68:71]
	v_mfma_f32_16x16x32_bf16 v[120:123], v[170:173], v[186:189], v[120:123]
	v_mfma_f32_16x16x32_bf16 v[112:115], v[178:181], v[186:189], v[112:115]
	v_mfma_f32_16x16x32_bf16 v[104:107], v[170:173], v[194:197], v[104:107]
	v_mfma_f32_16x16x32_bf16 v[96:99], v[178:181], v[194:197], v[96:99]
	v_mfma_f32_16x16x32_bf16 v[88:91], v[170:173], v[202:205], v[88:91]
	v_mfma_f32_16x16x32_bf16 v[80:83], v[178:181], v[202:205], v[80:83]
	v_mfma_f32_16x16x32_bf16 v[72:75], v[170:173], v[210:213], v[72:75]
	v_mfma_f32_16x16x32_bf16 v[64:67], v[178:181], v[210:213], v[64:67]
	v_mfma_f32_16x16x32_bf16 v[120:123], v[174:177], v[190:193], v[120:123]
	v_mfma_f32_16x16x32_bf16 v[112:115], v[182:185], v[190:193], v[112:115]
	v_mfma_f32_16x16x32_bf16 v[104:107], v[174:177], v[198:201], v[104:107]
	v_mfma_f32_16x16x32_bf16 v[96:99], v[182:185], v[198:201], v[96:99]
	v_mfma_f32_16x16x32_bf16 v[88:91], v[174:177], v[206:209], v[88:91]
	v_mfma_f32_16x16x32_bf16 v[80:83], v[182:185], v[206:209], v[80:83]
	v_mfma_f32_16x16x32_bf16 v[72:75], v[174:177], v[214:217], v[72:75]
	v_mfma_f32_16x16x32_bf16 v[64:67], v[182:185], v[214:217], v[64:67]
	s_barrier
	s_add_i32 s46, s46, s62
	s_mov_b32 m0, s46
	ds_read_b128 v[186:189], v147 offset:16384
	ds_read_b128 v[190:193], v147 offset:17408
	ds_read_b128 v[194:197], v147 offset:18432
	ds_read_b128 v[198:201], v147 offset:19456
	ds_read_b128 v[202:205], v147 offset:20480
	ds_read_b128 v[206:209], v147 offset:21504
	ds_read_b128 v[210:213], v147 offset:22528
	ds_read_b128 v[214:217], v147 offset:23552
	global_load_lds_dwordx4 v160, s[24:25]
	s_add_i32 m0, s46, 0x2000
	s_add_u32 s88, s24, 0x80000
	s_addc_u32 s89, s25, 0
	s_add_i32 s46, s47, s62
	global_load_lds_dwordx4 v128, s[24:25]
	s_mov_b32 m0, s46
	s_nop 0
	global_load_lds_dwordx4 v160, s[88:89]
	s_add_i32 m0, s46, 0x2000
	s_nop 0
	global_load_lds_dwordx4 v128, s[88:89]
	s_mov_b32 m0, s43
	s_nop 0
	global_load_lds_dwordx4 v132, s[60:61]
	s_mov_b32 m0, s44
	s_nop 0
	global_load_lds_dwordx4 v130, s[60:61]
	s_waitcnt vmcnt(8)
	s_waitcnt lgkmcnt(0)
	s_barrier
	v_mfma_f32_16x16x32_bf16 v[60:63], v[138:141], v[186:189], v[60:63]
	v_mfma_f32_16x16x32_bf16 v[52:55], v[152:155], v[186:189], v[52:55]
	v_mfma_f32_16x16x32_bf16 v[44:47], v[138:141], v[194:197], v[44:47]
	v_mfma_f32_16x16x32_bf16 v[36:39], v[152:155], v[194:197], v[36:39]
	v_mfma_f32_16x16x32_bf16 v[28:31], v[138:141], v[202:205], v[28:31]
	v_mfma_f32_16x16x32_bf16 v[20:23], v[152:155], v[202:205], v[20:23]
	v_mfma_f32_16x16x32_bf16 v[12:15], v[138:141], v[210:213], v[12:15]
	v_mfma_f32_16x16x32_bf16 v[4:7], v[152:155], v[210:213], v[4:7]
	v_mfma_f32_16x16x32_bf16 v[60:63], v[148:151], v[190:193], v[60:63]
	v_mfma_f32_16x16x32_bf16 v[52:55], v[156:159], v[190:193], v[52:55]
	v_mfma_f32_16x16x32_bf16 v[44:47], v[148:151], v[198:201], v[44:47]
	v_mfma_f32_16x16x32_bf16 v[36:39], v[156:159], v[198:201], v[36:39]
	v_mfma_f32_16x16x32_bf16 v[28:31], v[148:151], v[206:209], v[28:31]
	v_mfma_f32_16x16x32_bf16 v[20:23], v[156:159], v[206:209], v[20:23]
	v_mfma_f32_16x16x32_bf16 v[12:15], v[148:151], v[214:217], v[12:15]
	v_mfma_f32_16x16x32_bf16 v[4:7], v[156:159], v[214:217], v[4:7]
	v_mfma_f32_16x16x32_bf16 v[56:59], v[170:173], v[186:189], v[56:59]
	v_mfma_f32_16x16x32_bf16 v[48:51], v[178:181], v[186:189], v[48:51]
	v_mfma_f32_16x16x32_bf16 v[40:43], v[170:173], v[194:197], v[40:43]
	v_mfma_f32_16x16x32_bf16 v[32:35], v[178:181], v[194:197], v[32:35]
	v_mfma_f32_16x16x32_bf16 v[24:27], v[170:173], v[202:205], v[24:27]
	v_mfma_f32_16x16x32_bf16 v[16:19], v[178:181], v[202:205], v[16:19]
	v_mfma_f32_16x16x32_bf16 v[8:11], v[170:173], v[210:213], v[8:11]
	v_mfma_f32_16x16x32_bf16 v[0:3], v[178:181], v[210:213], v[0:3]
	v_mfma_f32_16x16x32_bf16 v[56:59], v[174:177], v[190:193], v[56:59]
	v_mfma_f32_16x16x32_bf16 v[48:51], v[182:185], v[190:193], v[48:51]
	v_mfma_f32_16x16x32_bf16 v[40:43], v[174:177], v[198:201], v[40:43]
	v_mfma_f32_16x16x32_bf16 v[32:35], v[182:185], v[198:201], v[32:35]
	v_mfma_f32_16x16x32_bf16 v[24:27], v[174:177], v[206:209], v[24:27]
	v_mfma_f32_16x16x32_bf16 v[16:19], v[182:185], v[206:209], v[16:19]
	v_mfma_f32_16x16x32_bf16 v[8:11], v[174:177], v[214:217], v[8:11]
	v_mfma_f32_16x16x32_bf16 v[0:3], v[182:185], v[214:217], v[0:3]
	s_barrier
; #define PG8_STAGE(bufoff, gbase, voff) do { _Pragma("unroll") for (int _i = 0; _i < 2; ++_i) \
;         __builtin_amdgcn_global_load_lds((const unsigned*)((const char*)(gbase) + (voff)[_i]), (LAS unsigned*)(lds + (bufoff) + ldsw + _i * 8192), 16, 0, 0); } while (0)
; #define PG8_LDA(dst, b, h) do { _Pragma("unroll") for (int m = 0; m < 4; ++m) _Pragma("unroll") for (int k = 0; k < 2; ++k) dst[m][k] = *(const LAS bf16x8*)(lds + PG8_SA(b, h) + aoff + m * 2048 + k * 1024); } while (0)
; #define PG8_LDB(dst, b, h) do { _Pragma("unroll") for (int n = 0; n < 2; ++n) _Pragma("unroll") for (int k = 0; k < 2; ++k) dst[n][k] = *(const LAS bf16x8*)(lds + PG8_SB(b, h) + boff + n * 2048 + k * 1024); } while (0)
; #define PG8_MMA(ai, bj, At, Bt) do { __builtin_amdgcn_s_setprio(1); _Pragma("unroll") for (int m = 0; m < 4; ++m) _Pragma("unroll") for (int n = 0; n < 2; ++n) _Pragma("unroll") for (int k = 0; k < 2; ++k) \
;         acc[ai][bj][m][n] = __builtin_amdgcn_mfma_f32_16x16x32_bf16(Bt[n][k], At[m][k], acc[ai][bj][m][n], 0, 0, 0); __builtin_amdgcn_s_setprio(0); } while (0)
; #define PG8_WAIT_V(n) asm volatile("s_waitcnt vmcnt(" #n ")" ::: "memory")
; #define PG8_WAIT_L(n) asm volatile("s_waitcnt lgkmcnt(" #n ")" ::: "memory")
; #define PG8_BAR __builtin_amdgcn_s_barrier()
; #define PG8_SCHED __builtin_amdgcn_sched_barrier(0)
; template <class Epi, class Sched, bool ALIGN_EPI = true, bool SP2 = true>
; __device__ __forceinline__ void gemm_phase(LAS unsigned char* lds, const Gemm g, const Sched& S, const Epi& E) {
;     ...
;             PG8_LDB(B0, 1, 0); PG8_LDB(B1, 1, 1); PG8_SCHED; PG8_LDA(At, 1, 0); PG8_STAGE(PG8_SA(0, 1), a2 + hstep, voffA);
;             PG8_WAIT_V(8); PG8_WAIT_L(0); PG8_BAR; PG8_MMA(0, 0, At, B0); PG8_MMA(0, 1, At, B1); PG8_BAR; PG8_SCHED;
;             PG8_LDA(At, 1, 1); PG8_STAGE(PG8_SB(1, 0), b3, voffB); PG8_STAGE(PG8_SB(1, 1), b3 + hstep, voffB); PG8_STAGE(PG8_SA(1, 0), a3, voffA);
;             PG8_WAIT_V(8); PG8_WAIT_L(0); PG8_BAR; PG8_MMA(1, 0, At, B0); PG8_MMA(1, 1, At, B1); PG8_BAR; PG8_SCHED;
;     ...
;         if constexpr (ALIGN_EPI) { if (wr == 0) PG8_BAR; }
	s_add_i32 s46, 0, 0x18000
	s_add_i32 s47, 0, 0x1c000
	v_add_u32_e32 v156, s46, v145
	v_add_u32_e32 v166, s47, v145
	ds_read_b128 v[138:141], v156
	ds_read_b128 v[148:151], v156 offset:1024
	ds_read_b128 v[152:155], v156 offset:2048
	ds_read_b128 v[156:159], v156 offset:3072
	ds_read_b128 v[170:173], v166
	ds_read_b128 v[174:177], v166 offset:1024
	ds_read_b128 v[178:181], v166 offset:2048
	ds_read_b128 v[182:185], v166 offset:3072
	s_add_u32 s60, s60, 0x80000
	s_addc_u32 s61, s61, 0
	s_mov_b32 m0, s45
	ds_read_b128 v[186:189], v147 offset:32768
	ds_read_b128 v[190:193], v147 offset:33792
	ds_read_b128 v[194:197], v147 offset:34816
	ds_read_b128 v[198:201], v147 offset:35840
	ds_read_b128 v[202:205], v147 offset:36864
	ds_read_b128 v[206:209], v147 offset:37888
	ds_read_b128 v[210:213], v147 offset:38912
	ds_read_b128 v[214:217], v147 offset:39936
	global_load_lds_dwordx4 v132, s[60:61]
	s_mov_b32 m0, s53
	s_nop 0
	global_load_lds_dwordx4 v130, s[60:61]
	s_waitcnt vmcnt(8)
	s_waitcnt lgkmcnt(0)
	s_barrier
	v_mfma_f32_16x16x32_bf16 v[124:127], v[138:141], v[186:189], v[124:127]
	v_mfma_f32_16x16x32_bf16 v[116:119], v[152:155], v[186:189], v[116:119]
	v_mfma_f32_16x16x32_bf16 v[108:111], v[138:141], v[194:197], v[108:111]
	v_mfma_f32_16x16x32_bf16 v[100:103], v[152:155], v[194:197], v[100:103]
	v_mfma_f32_16x16x32_bf16 v[92:95], v[138:141], v[202:205], v[92:95]
	v_mfma_f32_16x16x32_bf16 v[84:87], v[152:155], v[202:205], v[84:87]
	v_mfma_f32_16x16x32_bf16 v[76:79], v[138:141], v[210:213], v[76:79]
	v_mfma_f32_16x16x32_bf16 v[68:71], v[152:155], v[210:213], v[68:71]
	v_mfma_f32_16x16x32_bf16 v[124:127], v[148:151], v[190:193], v[124:127]
	v_mfma_f32_16x16x32_bf16 v[116:119], v[156:159], v[190:193], v[116:119]
	v_mfma_f32_16x16x32_bf16 v[108:111], v[148:151], v[198:201], v[108:111]
	v_mfma_f32_16x16x32_bf16 v[100:103], v[156:159], v[198:201], v[100:103]
	v_mfma_f32_16x16x32_bf16 v[92:95], v[148:151], v[206:209], v[92:95]
	v_mfma_f32_16x16x32_bf16 v[84:87], v[156:159], v[206:209], v[84:87]
	v_mfma_f32_16x16x32_bf16 v[76:79], v[148:151], v[214:217], v[76:79]
	v_mfma_f32_16x16x32_bf16 v[68:71], v[156:159], v[214:217], v[68:71]
	v_mfma_f32_16x16x32_bf16 v[120:123], v[170:173], v[186:189], v[120:123]
	v_mfma_f32_16x16x32_bf16 v[112:115], v[178:181], v[186:189], v[112:115]
	v_mfma_f32_16x16x32_bf16 v[104:107], v[170:173], v[194:197], v[104:107]
	v_mfma_f32_16x16x32_bf16 v[96:99], v[178:181], v[194:197], v[96:99]
	v_mfma_f32_16x16x32_bf16 v[88:91], v[170:173], v[202:205], v[88:91]
	v_mfma_f32_16x16x32_bf16 v[80:83], v[178:181], v[202:205], v[80:83]
	v_mfma_f32_16x16x32_bf16 v[72:75], v[170:173], v[210:213], v[72:75]
	v_mfma_f32_16x16x32_bf16 v[64:67], v[178:181], v[210:213], v[64:67]
	v_mfma_f32_16x16x32_bf16 v[120:123], v[174:177], v[190:193], v[120:123]
	v_mfma_f32_16x16x32_bf16 v[112:115], v[182:185], v[190:193], v[112:115]
	v_mfma_f32_16x16x32_bf16 v[104:107], v[174:177], v[198:201], v[104:107]
	v_mfma_f32_16x16x32_bf16 v[96:99], v[182:185], v[198:201], v[96:99]
	v_mfma_f32_16x16x32_bf16 v[88:91], v[174:177], v[206:209], v[88:91]
	v_mfma_f32_16x16x32_bf16 v[80:83], v[182:185], v[206:209], v[80:83]
	v_mfma_f32_16x16x32_bf16 v[72:75], v[174:177], v[214:217], v[72:75]
	v_mfma_f32_16x16x32_bf16 v[64:67], v[182:185], v[214:217], v[64:67]
	s_barrier
	s_add_i32 s46, s46, s62
	s_mov_b32 m0, s46
	ds_read_b128 v[186:189], v147 offset:49152
	ds_read_b128 v[190:193], v147 offset:50176
	ds_read_b128 v[194:197], v147 offset:51200
	ds_read_b128 v[198:201], v147 offset:52224
	ds_read_b128 v[202:205], v147 offset:53248
	ds_read_b128 v[206:209], v147 offset:54272
	ds_read_b128 v[210:213], v147 offset:55296
	ds_read_b128 v[214:217], v147 offset:56320
	s_add_u32 s98, s24, 0x80
	s_addc_u32 s99, s25, 0
	global_load_lds_dwordx4 v160, s[98:99]
	s_add_i32 m0, s46, 0x2000
	s_add_u32 s24, s24, 0x80080
	s_addc_u32 s25, s25, 0
	s_add_i32 s46, s47, s62
	global_load_lds_dwordx4 v128, s[98:99]
	s_mov_b32 m0, s46
	s_nop 0
	global_load_lds_dwordx4 v160, s[24:25]
	s_add_i32 m0, s46, 0x2000
	s_nop 0
	global_load_lds_dwordx4 v128, s[24:25]
	s_mov_b32 m0, s63
	s_nop 0
	s_add_u32 s98, s60, 0xfff80080
	s_addc_u32 s99, s61, -1
	global_load_lds_dwordx4 v132, s[98:99]
	s_mov_b32 m0, s66
	s_nop 0
	global_load_lds_dwordx4 v130, s[98:99]
	s_waitcnt vmcnt(8)
	s_waitcnt lgkmcnt(0)
	s_barrier
	v_mfma_f32_16x16x32_bf16 v[60:63], v[138:141], v[186:189], v[60:63]
	v_mfma_f32_16x16x32_bf16 v[52:55], v[152:155], v[186:189], v[52:55]
	v_mfma_f32_16x16x32_bf16 v[44:47], v[138:141], v[194:197], v[44:47]
	v_mfma_f32_16x16x32_bf16 v[36:39], v[152:155], v[194:197], v[36:39]
	v_mfma_f32_16x16x32_bf16 v[28:31], v[138:141], v[202:205], v[28:31]
	v_mfma_f32_16x16x32_bf16 v[20:23], v[152:155], v[202:205], v[20:23]
	v_mfma_f32_16x16x32_bf16 v[12:15], v[138:141], v[210:213], v[12:15]
	v_mfma_f32_16x16x32_bf16 v[4:7], v[152:155], v[210:213], v[4:7]
	v_mfma_f32_16x16x32_bf16 v[60:63], v[148:151], v[190:193], v[60:63]
	v_mfma_f32_16x16x32_bf16 v[52:55], v[156:159], v[190:193], v[52:55]
	v_mfma_f32_16x16x32_bf16 v[44:47], v[148:151], v[198:201], v[44:47]
	v_mfma_f32_16x16x32_bf16 v[36:39], v[156:159], v[198:201], v[36:39]
	v_mfma_f32_16x16x32_bf16 v[28:31], v[148:151], v[206:209], v[28:31]
	v_mfma_f32_16x16x32_bf16 v[20:23], v[156:159], v[206:209], v[20:23]
	v_mfma_f32_16x16x32_bf16 v[12:15], v[148:151], v[214:217], v[12:15]
	v_mfma_f32_16x16x32_bf16 v[4:7], v[156:159], v[214:217], v[4:7]
	v_mfma_f32_16x16x32_bf16 v[56:59], v[170:173], v[186:189], v[56:59]
	v_mfma_f32_16x16x32_bf16 v[48:51], v[178:181], v[186:189], v[48:51]
	v_mfma_f32_16x16x32_bf16 v[40:43], v[170:173], v[194:197], v[40:43]
	v_mfma_f32_16x16x32_bf16 v[32:35], v[178:181], v[194:197], v[32:35]
	v_mfma_f32_16x16x32_bf16 v[24:27], v[170:173], v[202:205], v[24:27]
	v_mfma_f32_16x16x32_bf16 v[16:19], v[178:181], v[202:205], v[16:19]
	v_mfma_f32_16x16x32_bf16 v[8:11], v[170:173], v[210:213], v[8:11]
	v_mfma_f32_16x16x32_bf16 v[0:3], v[178:181], v[210:213], v[0:3]
	v_mfma_f32_16x16x32_bf16 v[56:59], v[174:177], v[190:193], v[56:59]
	v_mfma_f32_16x16x32_bf16 v[48:51], v[182:185], v[190:193], v[48:51]
	v_mfma_f32_16x16x32_bf16 v[40:43], v[174:177], v[198:201], v[40:43]
	v_mfma_f32_16x16x32_bf16 v[32:35], v[182:185], v[198:201], v[32:35]
	v_mfma_f32_16x16x32_bf16 v[24:27], v[174:177], v[206:209], v[24:27]
	v_mfma_f32_16x16x32_bf16 v[16:19], v[182:185], v[206:209], v[16:19]
	v_mfma_f32_16x16x32_bf16 v[8:11], v[174:177], v[214:217], v[8:11]
	v_mfma_f32_16x16x32_bf16 v[0:3], v[182:185], v[214:217], v[0:3]
	s_barrier
	s_add_i32 s83, s83, 2
	s_add_u32 s54, s54, 0x100
	s_addc_u32 s55, s55, 0
	s_add_u32 s79, s79, 0x100
	s_addc_u32 s82, s82, 0
	s_cmp_gt_u32 s83, 29
	s_cbranch_scc0 .LBB0_600
	s_setprio 0
	s_and_b64 vcc, exec, s[10:11]
	s_cbranch_vccz .LBB0_603
	s_barrier
